# tail converter stores write-through (sc1) so the grid barrier's L2 write-back no longer has their dirty lines
# baseline (speedup 1.0000x reference)
; #define LAS __attribute__((address_space(3)))
; __device__ __forceinline__ void tr_load(const float* W, int N, int item, int lane, float (&wv)[32]) {
;     const int nblk = N / 32, kb = item / nblk, nb = item % nblk, k0 = 64 * kb, n0 = 32 * nb;
; #pragma unroll
;     for (int i = 0; i < 32; ++i) { const int kk = 2 * i + (lane >> 5); wv[i] = __builtin_nontemporal_load(W + (size_t)(k0 + kk) * N + n0 + (lane & 31)); }
; }
; template <int MAP, bool HASG, bool PERMW>
; __device__ __forceinline__ void tr_store(int K, int N, bf16_t* WT, LAS float* scr, int item, int lane, const float* gk) {
;     const int nblk = N / 32, kb = item / nblk, nb = item % nblk, k0 = 64 * kb, n0 = 32 * nb;
;     asm volatile("s_waitcnt lgkmcnt(0)" ::: "memory");
;     const int c = lane & 7;
;     f32x4 g0 = {1.f, 1.f, 1.f, 1.f}, g1 = {1.f, 1.f, 1.f, 1.f};
;     if (HASG) { g0 = *(const f32x4*)(gk + k0 + 8 * c); g1 = *(const f32x4*)(gk + k0 + 8 * c + 4); }
; #pragma unroll
;     for (int j = 0; j < 4; ++j) { const int n = (lane >> 3) + 8 * j; const LAS float* s = scr + (8 * c) * 33 + n;
;         u32x4 o; o.x = pk2(s[0 * 33] * g0[0], s[1 * 33] * g0[1]); o.y = pk2(s[2 * 33] * g0[2], s[3 * 33] * g0[3]); o.z = pk2(s[4 * 33] * g1[0], s[5 * 33] * g1[1]); o.w = pk2(s[6 * 33] * g1[2], s[7 * 33] * g1[3]);
;         const int wr_ = rowmap<MAP>(n0 + n), slot_ = PERMW ? ((wr_ & ~31) + invperm32(wr_ & 31)) : wr_;
;         *(u32x4*)((char*)WT + tiled_off(slot_, k0 + 8 * c, K / 64)) = o; }
;     asm volatile("s_waitcnt lgkmcnt(0)" ::: "memory");
; }
; template <int MAP, bool HASG = false, bool PERMW = false>
; __device__ __forceinline__ void transpose_mat(const float* W, int K, int N, bf16_t* WT, LAS float* scr, int gw, int ngw, int lane, const float* gk = nullptr) {
;     ...
;     for (;;) {
;         __builtin_amdgcn_sched_barrier(0);
; #pragma unroll
;         for (int i = 0; i < 32; ++i) { const int kk = 2 * i + (lane >> 5); scr[kk * 33 + (lane & 31)] = wv[i]; }
;         __builtin_amdgcn_sched_barrier(0);
;         const int nx = it + ngw;
;         if (nx < nitems) tr_load(W, N, nx, lane, wv);
;         __builtin_amdgcn_sched_barrier(0);
;         tr_store<MAP, HASG, PERMW>(K, N, WT, scr, it, lane, gk);
;         if (nx >= nitems) break;
;         it = nx;
;     }
.Ltc1a_loop:
	s_add_u32 s9, s9, s19
	s_cmpk_ge_u32 s9, 0x1600
	s_cbranch_scc1 .Ltc1a_lastA
	s_lshr_b32 s11, s9, 6
	s_and_b32 s12, s9, 63
	s_lshl_b32 s13, s11, 19
	s_lshl_b32 s14, s12, 7
	s_add_u32 s13, s13, s14
	s_add_u32 s14, s4, s13
	s_addc_u32 s15, s5, 0
	global_load_dword v88, v3, s[14:15] nt
	s_add_u32 s14, s14, 0x4000
	s_addc_u32 s15, s15, 0
	global_load_dword v89, v3, s[14:15] nt
	s_add_u32 s14, s14, 0x4000
	s_addc_u32 s15, s15, 0
	global_load_dword v90, v3, s[14:15] nt
	s_add_u32 s14, s14, 0x4000
	s_addc_u32 s15, s15, 0
	global_load_dword v91, v3, s[14:15] nt
	s_add_u32 s14, s14, 0x4000
	s_addc_u32 s15, s15, 0
	global_load_dword v92, v3, s[14:15] nt
	s_add_u32 s14, s14, 0x4000
	s_addc_u32 s15, s15, 0
	global_load_dword v93, v3, s[14:15] nt
	s_add_u32 s14, s14, 0x4000
	s_addc_u32 s15, s15, 0
	global_load_dword v94, v3, s[14:15] nt
	s_add_u32 s14, s14, 0x4000
	s_addc_u32 s15, s15, 0
	global_load_dword v95, v3, s[14:15] nt
	s_add_u32 s14, s14, 0x4000
	s_addc_u32 s15, s15, 0
	global_load_dword v96, v3, s[14:15] nt
	s_add_u32 s14, s14, 0x4000
	s_addc_u32 s15, s15, 0
	global_load_dword v97, v3, s[14:15] nt
	s_add_u32 s14, s14, 0x4000
	s_addc_u32 s15, s15, 0
	global_load_dword v98, v3, s[14:15] nt
	s_add_u32 s14, s14, 0x4000
	s_addc_u32 s15, s15, 0
	global_load_dword v99, v3, s[14:15] nt
	s_add_u32 s14, s14, 0x4000
	s_addc_u32 s15, s15, 0
	global_load_dword v100, v3, s[14:15] nt
	s_add_u32 s14, s14, 0x4000
	s_addc_u32 s15, s15, 0
	global_load_dword v101, v3, s[14:15] nt
	s_add_u32 s14, s14, 0x4000
	s_addc_u32 s15, s15, 0
	global_load_dword v102, v3, s[14:15] nt
	s_add_u32 s14, s14, 0x4000
	s_addc_u32 s15, s15, 0
	global_load_dword v103, v3, s[14:15] nt
	s_add_u32 s14, s14, 0x4000
	s_addc_u32 s15, s15, 0
	global_load_dword v104, v3, s[14:15] nt
	s_add_u32 s14, s14, 0x4000
	s_addc_u32 s15, s15, 0
	global_load_dword v105, v3, s[14:15] nt
	s_add_u32 s14, s14, 0x4000
	s_addc_u32 s15, s15, 0
	global_load_dword v106, v3, s[14:15] nt
	s_add_u32 s14, s14, 0x4000
	s_addc_u32 s15, s15, 0
	global_load_dword v107, v3, s[14:15] nt
	s_add_u32 s14, s14, 0x4000
	s_addc_u32 s15, s15, 0
	global_load_dword v108, v3, s[14:15] nt
	s_add_u32 s14, s14, 0x4000
	s_addc_u32 s15, s15, 0
	global_load_dword v109, v3, s[14:15] nt
	s_add_u32 s14, s14, 0x4000
	s_addc_u32 s15, s15, 0
	global_load_dword v110, v3, s[14:15] nt
	s_add_u32 s14, s14, 0x4000
	s_addc_u32 s15, s15, 0
	global_load_dword v111, v3, s[14:15] nt
	s_add_u32 s14, s14, 0x4000
	s_addc_u32 s15, s15, 0
	global_load_dword v112, v3, s[14:15] nt
	s_add_u32 s14, s14, 0x4000
	s_addc_u32 s15, s15, 0
	global_load_dword v113, v3, s[14:15] nt
	s_add_u32 s14, s14, 0x4000
	s_addc_u32 s15, s15, 0
	global_load_dword v114, v3, s[14:15] nt
	s_add_u32 s14, s14, 0x4000
	s_addc_u32 s15, s15, 0
	global_load_dword v115, v3, s[14:15] nt
	s_add_u32 s14, s14, 0x4000
	s_addc_u32 s15, s15, 0
	global_load_dword v116, v3, s[14:15] nt
	s_add_u32 s14, s14, 0x4000
	s_addc_u32 s15, s15, 0
	global_load_dword v117, v3, s[14:15] nt
	s_add_u32 s14, s14, 0x4000
	s_addc_u32 s15, s15, 0
	global_load_dword v118, v3, s[14:15] nt
	s_add_u32 s14, s14, 0x4000
	s_addc_u32 s15, s15, 0
	global_load_dword v119, v3, s[14:15] nt
	s_lshr_b32 s24, s12, 2
	s_mul_i32 s24, s24, 0x58
	s_add_u32 s24, s24, s11
	s_lshl_b32 s24, s24, 14
	s_and_b32 s25, s12, 3
	s_lshl_b32 s25, s25, 12
	s_add_u32 s24, s24, s25
	s_add_u32 s24, s6, s24
	s_addc_u32 s25, s7, 0
	s_waitcnt vmcnt(32)
	ds_write_b32 v4, v16
	ds_write_b32 v4, v17 offset:264
	ds_write_b32 v4, v18 offset:528
	ds_write_b32 v4, v19 offset:792
	ds_write_b32 v4, v20 offset:1056
	ds_write_b32 v4, v21 offset:1320
	ds_write_b32 v4, v22 offset:1584
	ds_write_b32 v4, v23 offset:1848
	ds_write_b32 v4, v24 offset:2112
	ds_write_b32 v4, v25 offset:2376
	ds_write_b32 v4, v26 offset:2640
	ds_write_b32 v4, v27 offset:2904
	ds_write_b32 v4, v28 offset:3168
	ds_write_b32 v4, v29 offset:3432
	ds_write_b32 v4, v30 offset:3696
	ds_write_b32 v4, v31 offset:3960
	ds_write_b32 v4, v32 offset:4224
	ds_write_b32 v4, v33 offset:4488
	ds_write_b32 v4, v34 offset:4752
	ds_write_b32 v4, v35 offset:5016
	ds_write_b32 v4, v36 offset:5280
	ds_write_b32 v4, v37 offset:5544
	ds_write_b32 v4, v38 offset:5808
	ds_write_b32 v4, v39 offset:6072
	ds_write_b32 v4, v40 offset:6336
	ds_write_b32 v4, v41 offset:6600
	ds_write_b32 v4, v42 offset:6864
	ds_write_b32 v4, v43 offset:7128
	ds_write_b32 v4, v44 offset:7392
	ds_write_b32 v4, v45 offset:7656
	ds_write_b32 v4, v46 offset:7920
	ds_write_b32 v4, v47 offset:8184
	s_waitcnt lgkmcnt(0)
	ds_read_b32 v48, v7
	ds_read_b32 v49, v7 offset:132
	ds_read_b32 v50, v7 offset:264
	ds_read_b32 v51, v7 offset:396
	ds_read_b32 v52, v7 offset:528
	ds_read_b32 v53, v7 offset:660
	ds_read_b32 v54, v7 offset:792
	ds_read_b32 v55, v7 offset:924
	ds_read_b32 v56, v7 offset:32
	ds_read_b32 v57, v7 offset:164
	ds_read_b32 v58, v7 offset:296
	ds_read_b32 v59, v7 offset:428
	ds_read_b32 v60, v7 offset:560
	ds_read_b32 v61, v7 offset:692
	ds_read_b32 v62, v7 offset:824
	ds_read_b32 v63, v7 offset:956
	ds_read_b32 v64, v7 offset:64
	ds_read_b32 v65, v7 offset:196
	ds_read_b32 v66, v7 offset:328
	ds_read_b32 v67, v7 offset:460
	ds_read_b32 v68, v7 offset:592
	ds_read_b32 v69, v7 offset:724
	ds_read_b32 v70, v7 offset:856
	ds_read_b32 v71, v7 offset:988
	ds_read_b32 v72, v7 offset:96
	ds_read_b32 v73, v7 offset:228
	ds_read_b32 v74, v7 offset:360
	ds_read_b32 v75, v7 offset:492
	ds_read_b32 v76, v7 offset:624
	ds_read_b32 v77, v7 offset:756
	ds_read_b32 v78, v7 offset:888
	ds_read_b32 v79, v7 offset:1020
	s_waitcnt lgkmcnt(0)
	v_cvt_pk_bf16_f32 v48, v48, v49
	v_cvt_pk_bf16_f32 v49, v50, v51
	v_cvt_pk_bf16_f32 v50, v52, v53
	v_cvt_pk_bf16_f32 v51, v54, v55
	global_store_dwordx4 v8, v[48:51], s[16:17] sc1
	v_cvt_pk_bf16_f32 v56, v56, v57
	v_cvt_pk_bf16_f32 v57, v58, v59
	v_cvt_pk_bf16_f32 v58, v60, v61
	v_cvt_pk_bf16_f32 v59, v62, v63
	global_store_dwordx4 v9, v[56:59], s[16:17] sc1
	v_cvt_pk_bf16_f32 v64, v64, v65
	v_cvt_pk_bf16_f32 v65, v66, v67
	v_cvt_pk_bf16_f32 v66, v68, v69
	v_cvt_pk_bf16_f32 v67, v70, v71
	global_store_dwordx4 v8, v[64:67], s[16:17] offset:2048 sc1
	v_cvt_pk_bf16_f32 v72, v72, v73
	v_cvt_pk_bf16_f32 v73, v74, v75
	v_cvt_pk_bf16_f32 v74, v76, v77
	v_cvt_pk_bf16_f32 v75, v78, v79
	global_store_dwordx4 v9, v[72:75], s[16:17] offset:2048 sc1
	s_add_u32 s9, s9, s19
	s_cmpk_ge_u32 s9, 0x1600
	s_cbranch_scc1 .Ltc1a_lastB
; #define LAS __attribute__((address_space(3)))
; __device__ __forceinline__ void tr_load(const float* W, int N, int item, int lane, float (&wv)[32]) {
;     const int nblk = N / 32, kb = item / nblk, nb = item % nblk, k0 = 64 * kb, n0 = 32 * nb;
; #pragma unroll
;     for (int i = 0; i < 32; ++i) { const int kk = 2 * i + (lane >> 5); wv[i] = __builtin_nontemporal_load(W + (size_t)(k0 + kk) * N + n0 + (lane & 31)); }
; }
; template <int MAP, bool HASG, bool PERMW>
; __device__ __forceinline__ void tr_store(int K, int N, bf16_t* WT, LAS float* scr, int item, int lane, const float* gk) {
;     const int nblk = N / 32, kb = item / nblk, nb = item % nblk, k0 = 64 * kb, n0 = 32 * nb;
;     asm volatile("s_waitcnt lgkmcnt(0)" ::: "memory");
;     const int c = lane & 7;
;     f32x4 g0 = {1.f, 1.f, 1.f, 1.f}, g1 = {1.f, 1.f, 1.f, 1.f};
;     if (HASG) { g0 = *(const f32x4*)(gk + k0 + 8 * c); g1 = *(const f32x4*)(gk + k0 + 8 * c + 4); }
; #pragma unroll
;     for (int j = 0; j < 4; ++j) { const int n = (lane >> 3) + 8 * j; const LAS float* s = scr + (8 * c) * 33 + n;
;         u32x4 o; o.x = pk2(s[0 * 33] * g0[0], s[1 * 33] * g0[1]); o.y = pk2(s[2 * 33] * g0[2], s[3 * 33] * g0[3]); o.z = pk2(s[4 * 33] * g1[0], s[5 * 33] * g1[1]); o.w = pk2(s[6 * 33] * g1[2], s[7 * 33] * g1[3]);
;         const int wr_ = rowmap<MAP>(n0 + n), slot_ = PERMW ? ((wr_ & ~31) + invperm32(wr_ & 31)) : wr_;
;         *(u32x4*)((char*)WT + tiled_off(slot_, k0 + 8 * c, K / 64)) = o; }
;     asm volatile("s_waitcnt lgkmcnt(0)" ::: "memory");
; }
; template <int MAP, bool HASG = false, bool PERMW = false>
; __device__ __forceinline__ void transpose_mat(const float* W, int K, int N, bf16_t* WT, LAS float* scr, int gw, int ngw, int lane, const float* gk = nullptr) {
;     ...
;     for (;;) {
;         __builtin_amdgcn_sched_barrier(0);
; #pragma unroll
;         for (int i = 0; i < 32; ++i) { const int kk = 2 * i + (lane >> 5); scr[kk * 33 + (lane & 31)] = wv[i]; }
;         __builtin_amdgcn_sched_barrier(0);
;         const int nx = it + ngw;
;         if (nx < nitems) tr_load(W, N, nx, lane, wv);
;         __builtin_amdgcn_sched_barrier(0);
;         tr_store<MAP, HASG, PERMW>(K, N, WT, scr, it, lane, gk);
;         if (nx >= nitems) break;
;         it = nx;
;     }
	s_lshr_b32 s11, s9, 6
	s_and_b32 s12, s9, 63
	s_lshl_b32 s13, s11, 19
	s_lshl_b32 s14, s12, 7
	s_add_u32 s13, s13, s14
	s_add_u32 s14, s4, s13
	s_addc_u32 s15, s5, 0
	global_load_dword v16, v3, s[14:15] nt
	s_add_u32 s14, s14, 0x4000
	s_addc_u32 s15, s15, 0
	global_load_dword v17, v3, s[14:15] nt
	s_add_u32 s14, s14, 0x4000
	s_addc_u32 s15, s15, 0
	global_load_dword v18, v3, s[14:15] nt
	s_add_u32 s14, s14, 0x4000
	s_addc_u32 s15, s15, 0
	global_load_dword v19, v3, s[14:15] nt
	s_add_u32 s14, s14, 0x4000
	s_addc_u32 s15, s15, 0
	global_load_dword v20, v3, s[14:15] nt
	s_add_u32 s14, s14, 0x4000
	s_addc_u32 s15, s15, 0
	global_load_dword v21, v3, s[14:15] nt
	s_add_u32 s14, s14, 0x4000
	s_addc_u32 s15, s15, 0
	global_load_dword v22, v3, s[14:15] nt
	s_add_u32 s14, s14, 0x4000
	s_addc_u32 s15, s15, 0
	global_load_dword v23, v3, s[14:15] nt
	s_add_u32 s14, s14, 0x4000
	s_addc_u32 s15, s15, 0
	global_load_dword v24, v3, s[14:15] nt
	s_add_u32 s14, s14, 0x4000
	s_addc_u32 s15, s15, 0
	global_load_dword v25, v3, s[14:15] nt
	s_add_u32 s14, s14, 0x4000
	s_addc_u32 s15, s15, 0
	global_load_dword v26, v3, s[14:15] nt
	s_add_u32 s14, s14, 0x4000
	s_addc_u32 s15, s15, 0
	global_load_dword v27, v3, s[14:15] nt
	s_add_u32 s14, s14, 0x4000
	s_addc_u32 s15, s15, 0
	global_load_dword v28, v3, s[14:15] nt
	s_add_u32 s14, s14, 0x4000
	s_addc_u32 s15, s15, 0
	global_load_dword v29, v3, s[14:15] nt
	s_add_u32 s14, s14, 0x4000
	s_addc_u32 s15, s15, 0
	global_load_dword v30, v3, s[14:15] nt
	s_add_u32 s14, s14, 0x4000
	s_addc_u32 s15, s15, 0
	global_load_dword v31, v3, s[14:15] nt
	s_add_u32 s14, s14, 0x4000
	s_addc_u32 s15, s15, 0
	global_load_dword v32, v3, s[14:15] nt
	s_add_u32 s14, s14, 0x4000
	s_addc_u32 s15, s15, 0
	global_load_dword v33, v3, s[14:15] nt
	s_add_u32 s14, s14, 0x4000
	s_addc_u32 s15, s15, 0
	global_load_dword v34, v3, s[14:15] nt
	s_add_u32 s14, s14, 0x4000
	s_addc_u32 s15, s15, 0
	global_load_dword v35, v3, s[14:15] nt
	s_add_u32 s14, s14, 0x4000
	s_addc_u32 s15, s15, 0
	global_load_dword v36, v3, s[14:15] nt
	s_add_u32 s14, s14, 0x4000
	s_addc_u32 s15, s15, 0
	global_load_dword v37, v3, s[14:15] nt
	s_add_u32 s14, s14, 0x4000
	s_addc_u32 s15, s15, 0
	global_load_dword v38, v3, s[14:15] nt
	s_add_u32 s14, s14, 0x4000
	s_addc_u32 s15, s15, 0
	global_load_dword v39, v3, s[14:15] nt
	s_add_u32 s14, s14, 0x4000
	s_addc_u32 s15, s15, 0
	global_load_dword v40, v3, s[14:15] nt
	s_add_u32 s14, s14, 0x4000
	s_addc_u32 s15, s15, 0
	global_load_dword v41, v3, s[14:15] nt
	s_add_u32 s14, s14, 0x4000
	s_addc_u32 s15, s15, 0
	global_load_dword v42, v3, s[14:15] nt
	s_add_u32 s14, s14, 0x4000
	s_addc_u32 s15, s15, 0
	global_load_dword v43, v3, s[14:15] nt
	s_add_u32 s14, s14, 0x4000
	s_addc_u32 s15, s15, 0
	global_load_dword v44, v3, s[14:15] nt
	s_add_u32 s14, s14, 0x4000
	s_addc_u32 s15, s15, 0
	global_load_dword v45, v3, s[14:15] nt
	s_add_u32 s14, s14, 0x4000
	s_addc_u32 s15, s15, 0
	global_load_dword v46, v3, s[14:15] nt
	s_add_u32 s14, s14, 0x4000
	s_addc_u32 s15, s15, 0
	global_load_dword v47, v3, s[14:15] nt
	s_lshr_b32 s16, s12, 2
	s_mul_i32 s16, s16, 0x58
	s_add_u32 s16, s16, s11
	s_lshl_b32 s16, s16, 14
	s_and_b32 s17, s12, 3
	s_lshl_b32 s17, s17, 12
	s_add_u32 s16, s16, s17
	s_add_u32 s16, s6, s16
	s_addc_u32 s17, s7, 0
	s_waitcnt vmcnt(32)
	ds_write_b32 v4, v88
	ds_write_b32 v4, v89 offset:264
	ds_write_b32 v4, v90 offset:528
	ds_write_b32 v4, v91 offset:792
	ds_write_b32 v4, v92 offset:1056
	ds_write_b32 v4, v93 offset:1320
	ds_write_b32 v4, v94 offset:1584
	ds_write_b32 v4, v95 offset:1848
	ds_write_b32 v4, v96 offset:2112
	ds_write_b32 v4, v97 offset:2376
	ds_write_b32 v4, v98 offset:2640
	ds_write_b32 v4, v99 offset:2904
	ds_write_b32 v4, v100 offset:3168
	ds_write_b32 v4, v101 offset:3432
	ds_write_b32 v4, v102 offset:3696
	ds_write_b32 v4, v103 offset:3960
	ds_write_b32 v4, v104 offset:4224
	ds_write_b32 v4, v105 offset:4488
	ds_write_b32 v4, v106 offset:4752
	ds_write_b32 v4, v107 offset:5016
	ds_write_b32 v4, v108 offset:5280
	ds_write_b32 v4, v109 offset:5544
	ds_write_b32 v4, v110 offset:5808
	ds_write_b32 v4, v111 offset:6072
	ds_write_b32 v4, v112 offset:6336
	ds_write_b32 v4, v113 offset:6600
	ds_write_b32 v4, v114 offset:6864
	ds_write_b32 v4, v115 offset:7128
	ds_write_b32 v4, v116 offset:7392
	ds_write_b32 v4, v117 offset:7656
	ds_write_b32 v4, v118 offset:7920
	ds_write_b32 v4, v119 offset:8184
	s_waitcnt lgkmcnt(0)
	ds_read_b32 v48, v7
	ds_read_b32 v49, v7 offset:132
	ds_read_b32 v50, v7 offset:264
	ds_read_b32 v51, v7 offset:396
	ds_read_b32 v52, v7 offset:528
	ds_read_b32 v53, v7 offset:660
	ds_read_b32 v54, v7 offset:792
	ds_read_b32 v55, v7 offset:924
	ds_read_b32 v56, v7 offset:32
	ds_read_b32 v57, v7 offset:164
	ds_read_b32 v58, v7 offset:296
	ds_read_b32 v59, v7 offset:428
	ds_read_b32 v60, v7 offset:560
	ds_read_b32 v61, v7 offset:692
	ds_read_b32 v62, v7 offset:824
	ds_read_b32 v63, v7 offset:956
	ds_read_b32 v64, v7 offset:64
	ds_read_b32 v65, v7 offset:196
	ds_read_b32 v66, v7 offset:328
	ds_read_b32 v67, v7 offset:460
	ds_read_b32 v68, v7 offset:592
	ds_read_b32 v69, v7 offset:724
	ds_read_b32 v70, v7 offset:856
	ds_read_b32 v71, v7 offset:988
	ds_read_b32 v72, v7 offset:96
	ds_read_b32 v73, v7 offset:228
	ds_read_b32 v74, v7 offset:360
	ds_read_b32 v75, v7 offset:492
	ds_read_b32 v76, v7 offset:624
	ds_read_b32 v77, v7 offset:756
	ds_read_b32 v78, v7 offset:888
	ds_read_b32 v79, v7 offset:1020
	s_waitcnt lgkmcnt(0)
	v_cvt_pk_bf16_f32 v48, v48, v49
	v_cvt_pk_bf16_f32 v49, v50, v51
	v_cvt_pk_bf16_f32 v50, v52, v53
	v_cvt_pk_bf16_f32 v51, v54, v55
	global_store_dwordx4 v8, v[48:51], s[24:25] sc1
	v_cvt_pk_bf16_f32 v56, v56, v57
	v_cvt_pk_bf16_f32 v57, v58, v59
	v_cvt_pk_bf16_f32 v58, v60, v61
	v_cvt_pk_bf16_f32 v59, v62, v63
	global_store_dwordx4 v9, v[56:59], s[24:25] sc1
	v_cvt_pk_bf16_f32 v64, v64, v65
	v_cvt_pk_bf16_f32 v65, v66, v67
	v_cvt_pk_bf16_f32 v66, v68, v69
	v_cvt_pk_bf16_f32 v67, v70, v71
	global_store_dwordx4 v8, v[64:67], s[24:25] offset:2048 sc1
	v_cvt_pk_bf16_f32 v72, v72, v73
	v_cvt_pk_bf16_f32 v73, v74, v75
	v_cvt_pk_bf16_f32 v74, v76, v77
	v_cvt_pk_bf16_f32 v75, v78, v79
	global_store_dwordx4 v9, v[72:75], s[24:25] offset:2048 sc1
	s_branch .Ltc1a_loop
; #define LAS __attribute__((address_space(3)))
; __device__ __forceinline__ unsigned pk2(float lo, float hi) { f32x2 f = {lo, hi}; bf16x2_t b = __builtin_convertvector(f, bf16x2_t); return __builtin_bit_cast(unsigned, b); }
; template <int MAP, bool HASG, bool PERMW>
; __device__ __forceinline__ void tr_store(int K, int N, bf16_t* WT, LAS float* scr, int item, int lane, const float* gk) {
;     ...
;     asm volatile("s_waitcnt lgkmcnt(0)" ::: "memory");
;     const int c = lane & 7;
;     f32x4 g0 = {1.f, 1.f, 1.f, 1.f}, g1 = {1.f, 1.f, 1.f, 1.f};
;     if (HASG) { g0 = *(const f32x4*)(gk + k0 + 8 * c); g1 = *(const f32x4*)(gk + k0 + 8 * c + 4); }
; #pragma unroll
;     for (int j = 0; j < 4; ++j) { const int n = (lane >> 3) + 8 * j; const LAS float* s = scr + (8 * c) * 33 + n;
;         u32x4 o; o.x = pk2(s[0 * 33] * g0[0], s[1 * 33] * g0[1]); o.y = pk2(s[2 * 33] * g0[2], s[3 * 33] * g0[3]); o.z = pk2(s[4 * 33] * g1[0], s[5 * 33] * g1[1]); o.w = pk2(s[6 * 33] * g1[2], s[7 * 33] * g1[3]);
;         const int wr_ = rowmap<MAP>(n0 + n), slot_ = PERMW ? ((wr_ & ~31) + invperm32(wr_ & 31)) : wr_;
;         *(u32x4*)((char*)WT + tiled_off(slot_, k0 + 8 * c, K / 64)) = o; }
;     asm volatile("s_waitcnt lgkmcnt(0)" ::: "memory");
; template <int MAP, bool HASG = false, bool PERMW = false>
; __device__ __forceinline__ void transpose_mat(const float* W, int K, int N, bf16_t* WT, LAS float* scr, int gw, int ngw, int lane, const float* gk = nullptr) {
;     ...
;         for (int i = 0; i < 32; ++i) { const int kk = 2 * i + (lane >> 5); scr[kk * 33 + (lane & 31)] = wv[i]; }
.Ltc1a_lastA:
	s_waitcnt vmcnt(0)
	ds_write_b32 v4, v16
	ds_write_b32 v4, v17 offset:264
	ds_write_b32 v4, v18 offset:528
	ds_write_b32 v4, v19 offset:792
	ds_write_b32 v4, v20 offset:1056
	ds_write_b32 v4, v21 offset:1320
	ds_write_b32 v4, v22 offset:1584
	ds_write_b32 v4, v23 offset:1848
	ds_write_b32 v4, v24 offset:2112
	ds_write_b32 v4, v25 offset:2376
	ds_write_b32 v4, v26 offset:2640
	ds_write_b32 v4, v27 offset:2904
	ds_write_b32 v4, v28 offset:3168
	ds_write_b32 v4, v29 offset:3432
	ds_write_b32 v4, v30 offset:3696
	ds_write_b32 v4, v31 offset:3960
	ds_write_b32 v4, v32 offset:4224
	ds_write_b32 v4, v33 offset:4488
	ds_write_b32 v4, v34 offset:4752
	ds_write_b32 v4, v35 offset:5016
	ds_write_b32 v4, v36 offset:5280
	ds_write_b32 v4, v37 offset:5544
	ds_write_b32 v4, v38 offset:5808
	ds_write_b32 v4, v39 offset:6072
	ds_write_b32 v4, v40 offset:6336
	ds_write_b32 v4, v41 offset:6600
	ds_write_b32 v4, v42 offset:6864
	ds_write_b32 v4, v43 offset:7128
	ds_write_b32 v4, v44 offset:7392
	ds_write_b32 v4, v45 offset:7656
	ds_write_b32 v4, v46 offset:7920
	ds_write_b32 v4, v47 offset:8184
	s_waitcnt lgkmcnt(0)
	ds_read_b32 v48, v7
	ds_read_b32 v49, v7 offset:132
	ds_read_b32 v50, v7 offset:264
	ds_read_b32 v51, v7 offset:396
	ds_read_b32 v52, v7 offset:528
	ds_read_b32 v53, v7 offset:660
	ds_read_b32 v54, v7 offset:792
	ds_read_b32 v55, v7 offset:924
	ds_read_b32 v56, v7 offset:32
	ds_read_b32 v57, v7 offset:164
	ds_read_b32 v58, v7 offset:296
	ds_read_b32 v59, v7 offset:428
	ds_read_b32 v60, v7 offset:560
	ds_read_b32 v61, v7 offset:692
	ds_read_b32 v62, v7 offset:824
	ds_read_b32 v63, v7 offset:956
	ds_read_b32 v64, v7 offset:64
	ds_read_b32 v65, v7 offset:196
	ds_read_b32 v66, v7 offset:328
	ds_read_b32 v67, v7 offset:460
	ds_read_b32 v68, v7 offset:592
	ds_read_b32 v69, v7 offset:724
	ds_read_b32 v70, v7 offset:856
	ds_read_b32 v71, v7 offset:988
	ds_read_b32 v72, v7 offset:96
	ds_read_b32 v73, v7 offset:228
	ds_read_b32 v74, v7 offset:360
	ds_read_b32 v75, v7 offset:492
	ds_read_b32 v76, v7 offset:624
	ds_read_b32 v77, v7 offset:756
	ds_read_b32 v78, v7 offset:888
	ds_read_b32 v79, v7 offset:1020
	s_waitcnt lgkmcnt(0)
	v_cvt_pk_bf16_f32 v48, v48, v49
	v_cvt_pk_bf16_f32 v49, v50, v51
	v_cvt_pk_bf16_f32 v50, v52, v53
	v_cvt_pk_bf16_f32 v51, v54, v55
	global_store_dwordx4 v8, v[48:51], s[16:17] sc1
	v_cvt_pk_bf16_f32 v56, v56, v57
	v_cvt_pk_bf16_f32 v57, v58, v59
	v_cvt_pk_bf16_f32 v58, v60, v61
	v_cvt_pk_bf16_f32 v59, v62, v63
	global_store_dwordx4 v9, v[56:59], s[16:17] sc1
	v_cvt_pk_bf16_f32 v64, v64, v65
	v_cvt_pk_bf16_f32 v65, v66, v67
	v_cvt_pk_bf16_f32 v66, v68, v69
	v_cvt_pk_bf16_f32 v67, v70, v71
	global_store_dwordx4 v8, v[64:67], s[16:17] offset:2048 sc1
	v_cvt_pk_bf16_f32 v72, v72, v73
	v_cvt_pk_bf16_f32 v73, v74, v75
	v_cvt_pk_bf16_f32 v74, v76, v77
	v_cvt_pk_bf16_f32 v75, v78, v79
	global_store_dwordx4 v9, v[72:75], s[16:17] offset:2048 sc1
	s_branch .Ltc1a_exit
.Ltc1a_lastB:
	s_waitcnt vmcnt(0)
	ds_write_b32 v4, v88
	ds_write_b32 v4, v89 offset:264
	ds_write_b32 v4, v90 offset:528
	ds_write_b32 v4, v91 offset:792
	ds_write_b32 v4, v92 offset:1056
	ds_write_b32 v4, v93 offset:1320
	ds_write_b32 v4, v94 offset:1584
	ds_write_b32 v4, v95 offset:1848
	ds_write_b32 v4, v96 offset:2112
	ds_write_b32 v4, v97 offset:2376
	ds_write_b32 v4, v98 offset:2640
	ds_write_b32 v4, v99 offset:2904
	ds_write_b32 v4, v100 offset:3168
	ds_write_b32 v4, v101 offset:3432
	ds_write_b32 v4, v102 offset:3696
	ds_write_b32 v4, v103 offset:3960
	ds_write_b32 v4, v104 offset:4224
	ds_write_b32 v4, v105 offset:4488
	ds_write_b32 v4, v106 offset:4752
	ds_write_b32 v4, v107 offset:5016
	ds_write_b32 v4, v108 offset:5280
	ds_write_b32 v4, v109 offset:5544
	ds_write_b32 v4, v110 offset:5808
	ds_write_b32 v4, v111 offset:6072
	ds_write_b32 v4, v112 offset:6336
	ds_write_b32 v4, v113 offset:6600
	ds_write_b32 v4, v114 offset:6864
	ds_write_b32 v4, v115 offset:7128
	ds_write_b32 v4, v116 offset:7392
	ds_write_b32 v4, v117 offset:7656
	ds_write_b32 v4, v118 offset:7920
	ds_write_b32 v4, v119 offset:8184
	s_waitcnt lgkmcnt(0)
	ds_read_b32 v48, v7
	ds_read_b32 v49, v7 offset:132
	ds_read_b32 v50, v7 offset:264
	ds_read_b32 v51, v7 offset:396
	ds_read_b32 v52, v7 offset:528
	ds_read_b32 v53, v7 offset:660
	ds_read_b32 v54, v7 offset:792
	ds_read_b32 v55, v7 offset:924
	ds_read_b32 v56, v7 offset:32
	ds_read_b32 v57, v7 offset:164
	ds_read_b32 v58, v7 offset:296
	ds_read_b32 v59, v7 offset:428
	ds_read_b32 v60, v7 offset:560
	ds_read_b32 v61, v7 offset:692
	ds_read_b32 v62, v7 offset:824
	ds_read_b32 v63, v7 offset:956
	ds_read_b32 v64, v7 offset:64
	ds_read_b32 v65, v7 offset:196
	ds_read_b32 v66, v7 offset:328
	ds_read_b32 v67, v7 offset:460
	ds_read_b32 v68, v7 offset:592
	ds_read_b32 v69, v7 offset:724
	ds_read_b32 v70, v7 offset:856
	ds_read_b32 v71, v7 offset:988
	ds_read_b32 v72, v7 offset:96
	ds_read_b32 v73, v7 offset:228
	ds_read_b32 v74, v7 offset:360
	ds_read_b32 v75, v7 offset:492
	ds_read_b32 v76, v7 offset:624
	ds_read_b32 v77, v7 offset:756
	ds_read_b32 v78, v7 offset:888
	ds_read_b32 v79, v7 offset:1020
	s_waitcnt lgkmcnt(0)
	v_cvt_pk_bf16_f32 v48, v48, v49
	v_cvt_pk_bf16_f32 v49, v50, v51
	v_cvt_pk_bf16_f32 v50, v52, v53
	v_cvt_pk_bf16_f32 v51, v54, v55
	global_store_dwordx4 v8, v[48:51], s[24:25] sc1
	v_cvt_pk_bf16_f32 v56, v56, v57
	v_cvt_pk_bf16_f32 v57, v58, v59
	v_cvt_pk_bf16_f32 v58, v60, v61
	v_cvt_pk_bf16_f32 v59, v62, v63
	global_store_dwordx4 v9, v[56:59], s[24:25] sc1
	v_cvt_pk_bf16_f32 v64, v64, v65
	v_cvt_pk_bf16_f32 v65, v66, v67
	v_cvt_pk_bf16_f32 v66, v68, v69
	v_cvt_pk_bf16_f32 v67, v70, v71
	global_store_dwordx4 v8, v[64:67], s[24:25] offset:2048 sc1
	v_cvt_pk_bf16_f32 v72, v72, v73
	v_cvt_pk_bf16_f32 v73, v74, v75
	v_cvt_pk_bf16_f32 v74, v76, v77
	v_cvt_pk_bf16_f32 v75, v78, v79
	global_store_dwordx4 v9, v[72:75], s[24:25] offset:2048 sc1

; #define LAS __attribute__((address_space(3)))
; __device__ __forceinline__ void tr_load(const float* W, int N, int item, int lane, float (&wv)[32]) {
;     const int nblk = N / 32, kb = item / nblk, nb = item % nblk, k0 = 64 * kb, n0 = 32 * nb;
; #pragma unroll
;     for (int i = 0; i < 32; ++i) { const int kk = 2 * i + (lane >> 5); wv[i] = __builtin_nontemporal_load(W + (size_t)(k0 + kk) * N + n0 + (lane & 31)); }
; }
; template <int MAP, bool HASG, bool PERMW>
; __device__ __forceinline__ void tr_store(int K, int N, bf16_t* WT, LAS float* scr, int item, int lane, const float* gk) {
;     const int nblk = N / 32, kb = item / nblk, nb = item % nblk, k0 = 64 * kb, n0 = 32 * nb;
;     asm volatile("s_waitcnt lgkmcnt(0)" ::: "memory");
;     const int c = lane & 7;
;     f32x4 g0 = {1.f, 1.f, 1.f, 1.f}, g1 = {1.f, 1.f, 1.f, 1.f};
;     if (HASG) { g0 = *(const f32x4*)(gk + k0 + 8 * c); g1 = *(const f32x4*)(gk + k0 + 8 * c + 4); }
; template <int MAP, bool HASG = false, bool PERMW = false>
; __device__ __forceinline__ void transpose_mat(const float* W, int K, int N, bf16_t* WT, LAS float* scr, int gw, int ngw, int lane, const float* gk = nullptr) {
;     ...
;     for (;;) {
;         __builtin_amdgcn_sched_barrier(0);
; #pragma unroll
;         for (int i = 0; i < 32; ++i) { const int kk = 2 * i + (lane >> 5); scr[kk * 33 + (lane & 31)] = wv[i]; }
;         __builtin_amdgcn_sched_barrier(0);
;         const int nx = it + ngw;
;         if (nx < nitems) tr_load(W, N, nx, lane, wv);
.Ltc1c_loop:
	s_add_u32 s9, s9, s19
	s_cmpk_ge_u32 s9, 0x3400
	s_cbranch_scc1 .Ltc1c_lastA
	s_mul_hi_u32 s11, s9, 0x4ec4ec4f
	s_lshr_b32 s11, s11, 7
	s_mul_i32 s12, s11, 0x1a0
	s_sub_u32 s12, s9, s12
	s_mul_i32 s13, s11, 0x340000
	s_lshl_b32 s14, s12, 7
	s_add_u32 s13, s13, s14
	s_add_u32 s14, s4, s13
	s_addc_u32 s15, s5, 0
	global_load_dword v88, v12, s[14:15] nt
	s_add_u32 s14, s14, 0x1a000
	s_addc_u32 s15, s15, 0
	global_load_dword v89, v12, s[14:15] nt
	s_add_u32 s14, s14, 0x1a000
	s_addc_u32 s15, s15, 0
	global_load_dword v90, v12, s[14:15] nt
	s_add_u32 s14, s14, 0x1a000
	s_addc_u32 s15, s15, 0
	global_load_dword v91, v12, s[14:15] nt
	s_add_u32 s14, s14, 0x1a000
	s_addc_u32 s15, s15, 0
	global_load_dword v92, v12, s[14:15] nt
	s_add_u32 s14, s14, 0x1a000
	s_addc_u32 s15, s15, 0
	global_load_dword v93, v12, s[14:15] nt
	s_add_u32 s14, s14, 0x1a000
	s_addc_u32 s15, s15, 0
	global_load_dword v94, v12, s[14:15] nt
	s_add_u32 s14, s14, 0x1a000
	s_addc_u32 s15, s15, 0
	global_load_dword v95, v12, s[14:15] nt
	s_add_u32 s14, s14, 0x1a000
	s_addc_u32 s15, s15, 0
	global_load_dword v96, v12, s[14:15] nt
	s_add_u32 s14, s14, 0x1a000
	s_addc_u32 s15, s15, 0
	global_load_dword v97, v12, s[14:15] nt
	s_add_u32 s14, s14, 0x1a000
	s_addc_u32 s15, s15, 0
	global_load_dword v98, v12, s[14:15] nt
	s_add_u32 s14, s14, 0x1a000
	s_addc_u32 s15, s15, 0
	global_load_dword v99, v12, s[14:15] nt
	s_add_u32 s14, s14, 0x1a000
	s_addc_u32 s15, s15, 0
	global_load_dword v100, v12, s[14:15] nt
	s_add_u32 s14, s14, 0x1a000
	s_addc_u32 s15, s15, 0
	global_load_dword v101, v12, s[14:15] nt
	s_add_u32 s14, s14, 0x1a000
	s_addc_u32 s15, s15, 0
	global_load_dword v102, v12, s[14:15] nt
	s_add_u32 s14, s14, 0x1a000
	s_addc_u32 s15, s15, 0
	global_load_dword v103, v12, s[14:15] nt
	s_add_u32 s14, s14, 0x1a000
	s_addc_u32 s15, s15, 0
	global_load_dword v104, v12, s[14:15] nt
	s_add_u32 s14, s14, 0x1a000
	s_addc_u32 s15, s15, 0
	global_load_dword v105, v12, s[14:15] nt
	s_add_u32 s14, s14, 0x1a000
	s_addc_u32 s15, s15, 0
	global_load_dword v106, v12, s[14:15] nt
	s_add_u32 s14, s14, 0x1a000
	s_addc_u32 s15, s15, 0
	global_load_dword v107, v12, s[14:15] nt
	s_add_u32 s14, s14, 0x1a000
	s_addc_u32 s15, s15, 0
	global_load_dword v108, v12, s[14:15] nt
	s_add_u32 s14, s14, 0x1a000
	s_addc_u32 s15, s15, 0
	global_load_dword v109, v12, s[14:15] nt
	s_add_u32 s14, s14, 0x1a000
	s_addc_u32 s15, s15, 0
	global_load_dword v110, v12, s[14:15] nt
	s_add_u32 s14, s14, 0x1a000
	s_addc_u32 s15, s15, 0
	global_load_dword v111, v12, s[14:15] nt
	s_add_u32 s14, s14, 0x1a000
	s_addc_u32 s15, s15, 0
	global_load_dword v112, v12, s[14:15] nt
	s_add_u32 s14, s14, 0x1a000
	s_addc_u32 s15, s15, 0
	global_load_dword v113, v12, s[14:15] nt
	s_add_u32 s14, s14, 0x1a000
	s_addc_u32 s15, s15, 0
	global_load_dword v114, v12, s[14:15] nt
	s_add_u32 s14, s14, 0x1a000
	s_addc_u32 s15, s15, 0
	global_load_dword v115, v12, s[14:15] nt
	s_add_u32 s14, s14, 0x1a000
	s_addc_u32 s15, s15, 0
	global_load_dword v116, v12, s[14:15] nt
	s_add_u32 s14, s14, 0x1a000
	s_addc_u32 s15, s15, 0
	global_load_dword v117, v12, s[14:15] nt
	s_add_u32 s14, s14, 0x1a000
	s_addc_u32 s15, s15, 0
	global_load_dword v118, v12, s[14:15] nt
	s_add_u32 s14, s14, 0x1a000
	s_addc_u32 s15, s15, 0
	global_load_dword v119, v12, s[14:15] nt
	s_lshl_b32 s14, s11, 8
	s_add_u32 s14, s20, s14
	s_addc_u32 s15, s21, 0
	global_load_dwordx4 v[120:123], v14, s[14:15]
	global_load_dwordx4 v[124:127], v14, s[14:15] offset:16
	s_sub_u32 s13, s12, 0x60
	s_cmp_lt_u32 s13, 0x40
	s_cselect_b32 s29, 1, 0
	s_cmp_lt_u32 s12, 0x40
	s_cselect_b32 s13, 1, 0
	s_or_b32 s29, s29, s13
	s_lshr_b32 s24, s12, 2
	s_lshl_b32 s24, s24, 5
	s_add_u32 s24, s24, s11
	s_lshl_b32 s24, s24, 14
	s_and_b32 s13, s12, 1
	s_lshl_b32 s13, s13, 13
	s_bfe_u32 s14, s12, 0x10001
	s_lshl_b32 s14, s14, 11
	s_add_u32 s13, s13, s14
	s_and_b32 s14, s12, 3
	s_lshl_b32 s14, s14, 12
	s_cmp_lg_u32 s29, 0
	s_cselect_b32 s13, s13, s14
	s_add_u32 s24, s24, s13
	s_add_u32 s24, s6, s24
	s_addc_u32 s25, s7, 0
	s_add_u32 s26, s24, 0x1000
	s_addc_u32 s27, s25, 0
	s_waitcnt vmcnt(34)
	ds_write_b32 v4, v16
	ds_write_b32 v4, v17 offset:264
	ds_write_b32 v4, v18 offset:528
	ds_write_b32 v4, v19 offset:792
	ds_write_b32 v4, v20 offset:1056
	ds_write_b32 v4, v21 offset:1320
	ds_write_b32 v4, v22 offset:1584
	ds_write_b32 v4, v23 offset:1848
	ds_write_b32 v4, v24 offset:2112
	ds_write_b32 v4, v25 offset:2376
	ds_write_b32 v4, v26 offset:2640
	ds_write_b32 v4, v27 offset:2904
	ds_write_b32 v4, v28 offset:3168
	ds_write_b32 v4, v29 offset:3432
	ds_write_b32 v4, v30 offset:3696
	ds_write_b32 v4, v31 offset:3960
	ds_write_b32 v4, v32 offset:4224
	ds_write_b32 v4, v33 offset:4488
	ds_write_b32 v4, v34 offset:4752
	ds_write_b32 v4, v35 offset:5016
	ds_write_b32 v4, v36 offset:5280
	ds_write_b32 v4, v37 offset:5544
	ds_write_b32 v4, v38 offset:5808
	ds_write_b32 v4, v39 offset:6072
	ds_write_b32 v4, v40 offset:6336
	ds_write_b32 v4, v41 offset:6600
	ds_write_b32 v4, v42 offset:6864
	ds_write_b32 v4, v43 offset:7128
	ds_write_b32 v4, v44 offset:7392
	ds_write_b32 v4, v45 offset:7656
	ds_write_b32 v4, v46 offset:7920
	ds_write_b32 v4, v47 offset:8184
	s_waitcnt lgkmcnt(0)
; #define LAS __attribute__((address_space(3)))
; __device__ __forceinline__ unsigned pk2(float lo, float hi) { f32x2 f = {lo, hi}; bf16x2_t b = __builtin_convertvector(f, bf16x2_t); return __builtin_bit_cast(unsigned, b); }
; template <int MAP> __device__ __forceinline__ int rowmap(int n) {
;     ...
;         const bool rot = (n < 2048) || (n >= 3072 && n < 5120);
;         if (!rot) return n;
;         const int c = n & 127, i = c & 63, half = c >> 6;
;         return (n & ~127) + 32 * (i >> 4) + 8 * ((i >> 2) & 3) + 4 * half + (i & 3);
; template <int MAP, bool HASG, bool PERMW>
; __device__ __forceinline__ void tr_store(int K, int N, bf16_t* WT, LAS float* scr, int item, int lane, const float* gk) {
;     ...
;     for (int j = 0; j < 4; ++j) { const int n = (lane >> 3) + 8 * j; const LAS float* s = scr + (8 * c) * 33 + n;
;         u32x4 o; o.x = pk2(s[0 * 33] * g0[0], s[1 * 33] * g0[1]); o.y = pk2(s[2 * 33] * g0[2], s[3 * 33] * g0[3]); o.z = pk2(s[4 * 33] * g1[0], s[5 * 33] * g1[1]); o.w = pk2(s[6 * 33] * g1[2], s[7 * 33] * g1[3]);
;         const int wr_ = rowmap<MAP>(n0 + n), slot_ = PERMW ? ((wr_ & ~31) + invperm32(wr_ & 31)) : wr_;
;         *(u32x4*)((char*)WT + tiled_off(slot_, k0 + 8 * c, K / 64)) = o; }
	ds_read_b32 v48, v7
	ds_read_b32 v49, v7 offset:132
	ds_read_b32 v50, v7 offset:264
	ds_read_b32 v51, v7 offset:396
	ds_read_b32 v52, v7 offset:528
	ds_read_b32 v53, v7 offset:660
	ds_read_b32 v54, v7 offset:792
	ds_read_b32 v55, v7 offset:924
	ds_read_b32 v56, v7 offset:32
	ds_read_b32 v57, v7 offset:164
	ds_read_b32 v58, v7 offset:296
	ds_read_b32 v59, v7 offset:428
	ds_read_b32 v60, v7 offset:560
	ds_read_b32 v61, v7 offset:692
	ds_read_b32 v62, v7 offset:824
	ds_read_b32 v63, v7 offset:956
	ds_read_b32 v64, v7 offset:64
	ds_read_b32 v65, v7 offset:196
	ds_read_b32 v66, v7 offset:328
	ds_read_b32 v67, v7 offset:460
	ds_read_b32 v68, v7 offset:592
	ds_read_b32 v69, v7 offset:724
	ds_read_b32 v70, v7 offset:856
	ds_read_b32 v71, v7 offset:988
	ds_read_b32 v72, v7 offset:96
	ds_read_b32 v73, v7 offset:228
	ds_read_b32 v74, v7 offset:360
	ds_read_b32 v75, v7 offset:492
	ds_read_b32 v76, v7 offset:624
	ds_read_b32 v77, v7 offset:756
	ds_read_b32 v78, v7 offset:888
	ds_read_b32 v79, v7 offset:1020
	s_waitcnt lgkmcnt(0)
	v_mul_f32_e32 v48, v48, v80
	v_mul_f32_e32 v49, v49, v81
	v_mul_f32_e32 v50, v50, v82
	v_mul_f32_e32 v51, v51, v83
	v_mul_f32_e32 v52, v52, v84
	v_mul_f32_e32 v53, v53, v85
	v_mul_f32_e32 v54, v54, v86
	v_mul_f32_e32 v55, v55, v87
	v_cvt_pk_bf16_f32 v48, v48, v49
	v_cvt_pk_bf16_f32 v49, v50, v51
	v_cvt_pk_bf16_f32 v50, v52, v53
	v_cvt_pk_bf16_f32 v51, v54, v55
	v_mul_f32_e32 v56, v56, v80
	v_mul_f32_e32 v57, v57, v81
	v_mul_f32_e32 v58, v58, v82
	v_mul_f32_e32 v59, v59, v83
	v_mul_f32_e32 v60, v60, v84
	v_mul_f32_e32 v61, v61, v85
	v_mul_f32_e32 v62, v62, v86
	v_mul_f32_e32 v63, v63, v87
	v_cvt_pk_bf16_f32 v56, v56, v57
	v_cvt_pk_bf16_f32 v57, v58, v59
	v_cvt_pk_bf16_f32 v58, v60, v61
	v_cvt_pk_bf16_f32 v59, v62, v63
	v_mul_f32_e32 v64, v64, v80
	v_mul_f32_e32 v65, v65, v81
	v_mul_f32_e32 v66, v66, v82
	v_mul_f32_e32 v67, v67, v83
	v_mul_f32_e32 v68, v68, v84
	v_mul_f32_e32 v69, v69, v85
	v_mul_f32_e32 v70, v70, v86
	v_mul_f32_e32 v71, v71, v87
	v_cvt_pk_bf16_f32 v64, v64, v65
	v_cvt_pk_bf16_f32 v65, v66, v67
	v_cvt_pk_bf16_f32 v66, v68, v69
	v_cvt_pk_bf16_f32 v67, v70, v71
	v_mul_f32_e32 v72, v72, v80
	v_mul_f32_e32 v73, v73, v81
	v_mul_f32_e32 v74, v74, v82
	v_mul_f32_e32 v75, v75, v83
	v_mul_f32_e32 v76, v76, v84
	v_mul_f32_e32 v77, v77, v85
	v_mul_f32_e32 v78, v78, v86
	v_mul_f32_e32 v79, v79, v87
	v_cvt_pk_bf16_f32 v72, v72, v73
	v_cvt_pk_bf16_f32 v73, v74, v75
	v_cvt_pk_bf16_f32 v74, v76, v77
	v_cvt_pk_bf16_f32 v75, v78, v79
	s_cmp_lg_u32 s28, 0
	s_cbranch_scc1 .Ltcw1_rot
	global_store_dwordx4 v10, v[48:51], s[16:17] sc1
	global_store_dwordx4 v10, v[56:59], s[16:17] offset:256 sc1
	global_store_dwordx4 v11, v[64:67], s[16:17] offset:512 sc1
	global_store_dwordx4 v11, v[72:75], s[16:17] offset:768 sc1
	s_branch .Ltcw1_done
.Ltcw1_rot:
	global_store_dwordx4 v8, v[48:51], s[16:17] sc1
	global_store_dwordx4 v9, v[56:59], s[16:17] sc1
	global_store_dwordx4 v8, v[64:67], s[22:23] sc1
	global_store_dwordx4 v9, v[72:75], s[22:23] sc1
.Ltcw1_done:
	s_add_u32 s9, s9, s19
	s_cmpk_ge_u32 s9, 0x3400
	s_cbranch_scc1 .Ltc1c_lastB
	s_mul_hi_u32 s11, s9, 0x4ec4ec4f
	s_lshr_b32 s11, s11, 7
	s_mul_i32 s12, s11, 0x1a0
	s_sub_u32 s12, s9, s12
	s_mul_i32 s13, s11, 0x340000
	s_lshl_b32 s14, s12, 7
	s_add_u32 s13, s13, s14
	s_add_u32 s14, s4, s13
	s_addc_u32 s15, s5, 0
	global_load_dword v16, v12, s[14:15] nt
	s_add_u32 s14, s14, 0x1a000
	s_addc_u32 s15, s15, 0
	global_load_dword v17, v12, s[14:15] nt
	s_add_u32 s14, s14, 0x1a000
	s_addc_u32 s15, s15, 0
	global_load_dword v18, v12, s[14:15] nt
	s_add_u32 s14, s14, 0x1a000
	s_addc_u32 s15, s15, 0
	global_load_dword v19, v12, s[14:15] nt
	s_add_u32 s14, s14, 0x1a000
	s_addc_u32 s15, s15, 0
	global_load_dword v20, v12, s[14:15] nt
	s_add_u32 s14, s14, 0x1a000
	s_addc_u32 s15, s15, 0
	global_load_dword v21, v12, s[14:15] nt
	s_add_u32 s14, s14, 0x1a000
	s_addc_u32 s15, s15, 0
	global_load_dword v22, v12, s[14:15] nt
	s_add_u32 s14, s14, 0x1a000
	s_addc_u32 s15, s15, 0
	global_load_dword v23, v12, s[14:15] nt
	s_add_u32 s14, s14, 0x1a000
	s_addc_u32 s15, s15, 0
	global_load_dword v24, v12, s[14:15] nt
	s_add_u32 s14, s14, 0x1a000
	s_addc_u32 s15, s15, 0
	global_load_dword v25, v12, s[14:15] nt
	s_add_u32 s14, s14, 0x1a000
	s_addc_u32 s15, s15, 0
	global_load_dword v26, v12, s[14:15] nt
	s_add_u32 s14, s14, 0x1a000
	s_addc_u32 s15, s15, 0
	global_load_dword v27, v12, s[14:15] nt
	s_add_u32 s14, s14, 0x1a000
	s_addc_u32 s15, s15, 0
	global_load_dword v28, v12, s[14:15] nt
	s_add_u32 s14, s14, 0x1a000
	s_addc_u32 s15, s15, 0
	global_load_dword v29, v12, s[14:15] nt
	s_add_u32 s14, s14, 0x1a000
	s_addc_u32 s15, s15, 0
	global_load_dword v30, v12, s[14:15] nt
	s_add_u32 s14, s14, 0x1a000
	s_addc_u32 s15, s15, 0
	global_load_dword v31, v12, s[14:15] nt
	s_add_u32 s14, s14, 0x1a000
	s_addc_u32 s15, s15, 0
	global_load_dword v32, v12, s[14:15] nt
	s_add_u32 s14, s14, 0x1a000
	s_addc_u32 s15, s15, 0
	global_load_dword v33, v12, s[14:15] nt
	s_add_u32 s14, s14, 0x1a000
	s_addc_u32 s15, s15, 0
	global_load_dword v34, v12, s[14:15] nt
	s_add_u32 s14, s14, 0x1a000
	s_addc_u32 s15, s15, 0
	global_load_dword v35, v12, s[14:15] nt
	s_add_u32 s14, s14, 0x1a000
	s_addc_u32 s15, s15, 0
	global_load_dword v36, v12, s[14:15] nt
	s_add_u32 s14, s14, 0x1a000
	s_addc_u32 s15, s15, 0
	global_load_dword v37, v12, s[14:15] nt
	s_add_u32 s14, s14, 0x1a000
	s_addc_u32 s15, s15, 0
	global_load_dword v38, v12, s[14:15] nt
	s_add_u32 s14, s14, 0x1a000
	s_addc_u32 s15, s15, 0
	global_load_dword v39, v12, s[14:15] nt
	s_add_u32 s14, s14, 0x1a000
	s_addc_u32 s15, s15, 0
	global_load_dword v40, v12, s[14:15] nt
; #define LAS __attribute__((address_space(3)))
; __device__ __forceinline__ unsigned pk2(float lo, float hi) { f32x2 f = {lo, hi}; bf16x2_t b = __builtin_convertvector(f, bf16x2_t); return __builtin_bit_cast(unsigned, b); }
; template <int MAP> __device__ __forceinline__ int rowmap(int n) {
;     ...
;         const bool rot = (n < 2048) || (n >= 3072 && n < 5120);
;         if (!rot) return n;
;         const int c = n & 127, i = c & 63, half = c >> 6;
;         return (n & ~127) + 32 * (i >> 4) + 8 * ((i >> 2) & 3) + 4 * half + (i & 3);
; template <int MAP, bool HASG, bool PERMW>
; __device__ __forceinline__ void tr_store(int K, int N, bf16_t* WT, LAS float* scr, int item, int lane, const float* gk) {
;     ...
;     for (int j = 0; j < 4; ++j) { const int n = (lane >> 3) + 8 * j; const LAS float* s = scr + (8 * c) * 33 + n;
;         u32x4 o; o.x = pk2(s[0 * 33] * g0[0], s[1 * 33] * g0[1]); o.y = pk2(s[2 * 33] * g0[2], s[3 * 33] * g0[3]); o.z = pk2(s[4 * 33] * g1[0], s[5 * 33] * g1[1]); o.w = pk2(s[6 * 33] * g1[2], s[7 * 33] * g1[3]);
;         const int wr_ = rowmap<MAP>(n0 + n), slot_ = PERMW ? ((wr_ & ~31) + invperm32(wr_ & 31)) : wr_;
;         *(u32x4*)((char*)WT + tiled_off(slot_, k0 + 8 * c, K / 64)) = o; }
	s_add_u32 s14, s14, 0x1a000
	s_addc_u32 s15, s15, 0
	global_load_dword v41, v12, s[14:15] nt
	s_add_u32 s14, s14, 0x1a000
	s_addc_u32 s15, s15, 0
	global_load_dword v42, v12, s[14:15] nt
	s_add_u32 s14, s14, 0x1a000
	s_addc_u32 s15, s15, 0
	global_load_dword v43, v12, s[14:15] nt
	s_add_u32 s14, s14, 0x1a000
	s_addc_u32 s15, s15, 0
	global_load_dword v44, v12, s[14:15] nt
	s_add_u32 s14, s14, 0x1a000
	s_addc_u32 s15, s15, 0
	global_load_dword v45, v12, s[14:15] nt
	s_add_u32 s14, s14, 0x1a000
	s_addc_u32 s15, s15, 0
	global_load_dword v46, v12, s[14:15] nt
	s_add_u32 s14, s14, 0x1a000
	s_addc_u32 s15, s15, 0
	global_load_dword v47, v12, s[14:15] nt
	s_lshl_b32 s14, s11, 8
	s_add_u32 s14, s20, s14
	s_addc_u32 s15, s21, 0
	global_load_dwordx4 v[80:83], v14, s[14:15]
	global_load_dwordx4 v[84:87], v14, s[14:15] offset:16
	s_sub_u32 s13, s12, 0x60
	s_cmp_lt_u32 s13, 0x40
	s_cselect_b32 s28, 1, 0
	s_cmp_lt_u32 s12, 0x40
	s_cselect_b32 s13, 1, 0
	s_or_b32 s28, s28, s13
	s_lshr_b32 s16, s12, 2
	s_lshl_b32 s16, s16, 5
	s_add_u32 s16, s16, s11
	s_lshl_b32 s16, s16, 14
	s_and_b32 s13, s12, 1
	s_lshl_b32 s13, s13, 13
	s_bfe_u32 s14, s12, 0x10001
	s_lshl_b32 s14, s14, 11
	s_add_u32 s13, s13, s14
	s_and_b32 s14, s12, 3
	s_lshl_b32 s14, s14, 12
	s_cmp_lg_u32 s28, 0
	s_cselect_b32 s13, s13, s14
	s_add_u32 s16, s16, s13
	s_add_u32 s16, s6, s16
	s_addc_u32 s17, s7, 0
	s_add_u32 s22, s16, 0x1000
	s_addc_u32 s23, s17, 0
	s_waitcnt vmcnt(34)
	ds_write_b32 v4, v88
	ds_write_b32 v4, v89 offset:264
	ds_write_b32 v4, v90 offset:528
	ds_write_b32 v4, v91 offset:792
	ds_write_b32 v4, v92 offset:1056
	ds_write_b32 v4, v93 offset:1320
	ds_write_b32 v4, v94 offset:1584
	ds_write_b32 v4, v95 offset:1848
	ds_write_b32 v4, v96 offset:2112
	ds_write_b32 v4, v97 offset:2376
	ds_write_b32 v4, v98 offset:2640
	ds_write_b32 v4, v99 offset:2904
	ds_write_b32 v4, v100 offset:3168
	ds_write_b32 v4, v101 offset:3432
	ds_write_b32 v4, v102 offset:3696
	ds_write_b32 v4, v103 offset:3960
	ds_write_b32 v4, v104 offset:4224
	ds_write_b32 v4, v105 offset:4488
	ds_write_b32 v4, v106 offset:4752
	ds_write_b32 v4, v107 offset:5016
	ds_write_b32 v4, v108 offset:5280
	ds_write_b32 v4, v109 offset:5544
	ds_write_b32 v4, v110 offset:5808
	ds_write_b32 v4, v111 offset:6072
	ds_write_b32 v4, v112 offset:6336
	ds_write_b32 v4, v113 offset:6600
	ds_write_b32 v4, v114 offset:6864
	ds_write_b32 v4, v115 offset:7128
	ds_write_b32 v4, v116 offset:7392
	ds_write_b32 v4, v117 offset:7656
	ds_write_b32 v4, v118 offset:7920
	ds_write_b32 v4, v119 offset:8184
	s_waitcnt lgkmcnt(0)
	ds_read_b32 v48, v7
	ds_read_b32 v49, v7 offset:132
	ds_read_b32 v50, v7 offset:264
	ds_read_b32 v51, v7 offset:396
	ds_read_b32 v52, v7 offset:528
	ds_read_b32 v53, v7 offset:660
	ds_read_b32 v54, v7 offset:792
	ds_read_b32 v55, v7 offset:924
	ds_read_b32 v56, v7 offset:32
	ds_read_b32 v57, v7 offset:164
	ds_read_b32 v58, v7 offset:296
	ds_read_b32 v59, v7 offset:428
	ds_read_b32 v60, v7 offset:560
	ds_read_b32 v61, v7 offset:692
	ds_read_b32 v62, v7 offset:824
	ds_read_b32 v63, v7 offset:956
	ds_read_b32 v64, v7 offset:64
	ds_read_b32 v65, v7 offset:196
	ds_read_b32 v66, v7 offset:328
	ds_read_b32 v67, v7 offset:460
	ds_read_b32 v68, v7 offset:592
	ds_read_b32 v69, v7 offset:724
	ds_read_b32 v70, v7 offset:856
	ds_read_b32 v71, v7 offset:988
	ds_read_b32 v72, v7 offset:96
	ds_read_b32 v73, v7 offset:228
	ds_read_b32 v74, v7 offset:360
	ds_read_b32 v75, v7 offset:492
	ds_read_b32 v76, v7 offset:624
	ds_read_b32 v77, v7 offset:756
	ds_read_b32 v78, v7 offset:888
	ds_read_b32 v79, v7 offset:1020
	s_waitcnt lgkmcnt(0)
	v_mul_f32_e32 v48, v48, v120
	v_mul_f32_e32 v49, v49, v121
	v_mul_f32_e32 v50, v50, v122
	v_mul_f32_e32 v51, v51, v123
	v_mul_f32_e32 v52, v52, v124
	v_mul_f32_e32 v53, v53, v125
	v_mul_f32_e32 v54, v54, v126
	v_mul_f32_e32 v55, v55, v127
	v_cvt_pk_bf16_f32 v48, v48, v49
	v_cvt_pk_bf16_f32 v49, v50, v51
	v_cvt_pk_bf16_f32 v50, v52, v53
	v_cvt_pk_bf16_f32 v51, v54, v55
	v_mul_f32_e32 v56, v56, v120
	v_mul_f32_e32 v57, v57, v121
	v_mul_f32_e32 v58, v58, v122
	v_mul_f32_e32 v59, v59, v123
	v_mul_f32_e32 v60, v60, v124
	v_mul_f32_e32 v61, v61, v125
	v_mul_f32_e32 v62, v62, v126
	v_mul_f32_e32 v63, v63, v127
	v_cvt_pk_bf16_f32 v56, v56, v57
	v_cvt_pk_bf16_f32 v57, v58, v59
	v_cvt_pk_bf16_f32 v58, v60, v61
	v_cvt_pk_bf16_f32 v59, v62, v63
	v_mul_f32_e32 v64, v64, v120
	v_mul_f32_e32 v65, v65, v121
	v_mul_f32_e32 v66, v66, v122
	v_mul_f32_e32 v67, v67, v123
	v_mul_f32_e32 v68, v68, v124
	v_mul_f32_e32 v69, v69, v125
	v_mul_f32_e32 v70, v70, v126
	v_mul_f32_e32 v71, v71, v127
	v_cvt_pk_bf16_f32 v64, v64, v65
	v_cvt_pk_bf16_f32 v65, v66, v67
	v_cvt_pk_bf16_f32 v66, v68, v69
	v_cvt_pk_bf16_f32 v67, v70, v71
	v_mul_f32_e32 v72, v72, v120
	v_mul_f32_e32 v73, v73, v121
	v_mul_f32_e32 v74, v74, v122
	v_mul_f32_e32 v75, v75, v123
	v_mul_f32_e32 v76, v76, v124
	v_mul_f32_e32 v77, v77, v125
	v_mul_f32_e32 v78, v78, v126
	v_mul_f32_e32 v79, v79, v127
	v_cvt_pk_bf16_f32 v72, v72, v73
	v_cvt_pk_bf16_f32 v73, v74, v75
	v_cvt_pk_bf16_f32 v74, v76, v77
	v_cvt_pk_bf16_f32 v75, v78, v79
	s_cmp_lg_u32 s29, 0
	s_cbranch_scc1 .Ltcw2_rot
	global_store_dwordx4 v10, v[48:51], s[24:25] sc1
	global_store_dwordx4 v10, v[56:59], s[24:25] offset:256 sc1
	global_store_dwordx4 v11, v[64:67], s[24:25] offset:512 sc1
	global_store_dwordx4 v11, v[72:75], s[24:25] offset:768 sc1
	s_branch .Ltcw2_done
.Ltcw2_rot:
	global_store_dwordx4 v8, v[48:51], s[24:25] sc1
	global_store_dwordx4 v9, v[56:59], s[24:25] sc1
	global_store_dwordx4 v8, v[64:67], s[26:27] sc1
	global_store_dwordx4 v9, v[72:75], s[26:27] sc1

; #define LAS __attribute__((address_space(3)))
; __device__ __forceinline__ unsigned pk2(float lo, float hi) { f32x2 f = {lo, hi}; bf16x2_t b = __builtin_convertvector(f, bf16x2_t); return __builtin_bit_cast(unsigned, b); }
; template <int MAP, bool HASG, bool PERMW>
; __device__ __forceinline__ void tr_store(int K, int N, bf16_t* WT, LAS float* scr, int item, int lane, const float* gk) {
;     const int nblk = N / 32, kb = item / nblk, nb = item % nblk, k0 = 64 * kb, n0 = 32 * nb;
;     asm volatile("s_waitcnt lgkmcnt(0)" ::: "memory");
;     const int c = lane & 7;
;     f32x4 g0 = {1.f, 1.f, 1.f, 1.f}, g1 = {1.f, 1.f, 1.f, 1.f};
;     if (HASG) { g0 = *(const f32x4*)(gk + k0 + 8 * c); g1 = *(const f32x4*)(gk + k0 + 8 * c + 4); }
; #pragma unroll
;     for (int j = 0; j < 4; ++j) { const int n = (lane >> 3) + 8 * j; const LAS float* s = scr + (8 * c) * 33 + n;
;         u32x4 o; o.x = pk2(s[0 * 33] * g0[0], s[1 * 33] * g0[1]); o.y = pk2(s[2 * 33] * g0[2], s[3 * 33] * g0[3]); o.z = pk2(s[4 * 33] * g1[0], s[5 * 33] * g1[1]); o.w = pk2(s[6 * 33] * g1[2], s[7 * 33] * g1[3]);
;         const int wr_ = rowmap<MAP>(n0 + n), slot_ = PERMW ? ((wr_ & ~31) + invperm32(wr_ & 31)) : wr_;
;         *(u32x4*)((char*)WT + tiled_off(slot_, k0 + 8 * c, K / 64)) = o; }
;     asm volatile("s_waitcnt lgkmcnt(0)" ::: "memory");
; }
.Ltc1c_lastA:
	s_waitcnt vmcnt(0)
	ds_write_b32 v4, v16
	ds_write_b32 v4, v17 offset:264
	ds_write_b32 v4, v18 offset:528
	ds_write_b32 v4, v19 offset:792
	ds_write_b32 v4, v20 offset:1056
	ds_write_b32 v4, v21 offset:1320
	ds_write_b32 v4, v22 offset:1584
	ds_write_b32 v4, v23 offset:1848
	ds_write_b32 v4, v24 offset:2112
	ds_write_b32 v4, v25 offset:2376
	ds_write_b32 v4, v26 offset:2640
	ds_write_b32 v4, v27 offset:2904
	ds_write_b32 v4, v28 offset:3168
	ds_write_b32 v4, v29 offset:3432
	ds_write_b32 v4, v30 offset:3696
	ds_write_b32 v4, v31 offset:3960
	ds_write_b32 v4, v32 offset:4224
	ds_write_b32 v4, v33 offset:4488
	ds_write_b32 v4, v34 offset:4752
	ds_write_b32 v4, v35 offset:5016
	ds_write_b32 v4, v36 offset:5280
	ds_write_b32 v4, v37 offset:5544
	ds_write_b32 v4, v38 offset:5808
	ds_write_b32 v4, v39 offset:6072
	ds_write_b32 v4, v40 offset:6336
	ds_write_b32 v4, v41 offset:6600
	ds_write_b32 v4, v42 offset:6864
	ds_write_b32 v4, v43 offset:7128
	ds_write_b32 v4, v44 offset:7392
	ds_write_b32 v4, v45 offset:7656
	ds_write_b32 v4, v46 offset:7920
	ds_write_b32 v4, v47 offset:8184
	s_waitcnt lgkmcnt(0)
	ds_read_b32 v48, v7
	ds_read_b32 v49, v7 offset:132
	ds_read_b32 v50, v7 offset:264
	ds_read_b32 v51, v7 offset:396
	ds_read_b32 v52, v7 offset:528
	ds_read_b32 v53, v7 offset:660
	ds_read_b32 v54, v7 offset:792
	ds_read_b32 v55, v7 offset:924
	ds_read_b32 v56, v7 offset:32
	ds_read_b32 v57, v7 offset:164
	ds_read_b32 v58, v7 offset:296
	ds_read_b32 v59, v7 offset:428
	ds_read_b32 v60, v7 offset:560
	ds_read_b32 v61, v7 offset:692
	ds_read_b32 v62, v7 offset:824
	ds_read_b32 v63, v7 offset:956
	ds_read_b32 v64, v7 offset:64
	ds_read_b32 v65, v7 offset:196
	ds_read_b32 v66, v7 offset:328
	ds_read_b32 v67, v7 offset:460
	ds_read_b32 v68, v7 offset:592
	ds_read_b32 v69, v7 offset:724
	ds_read_b32 v70, v7 offset:856
	ds_read_b32 v71, v7 offset:988
	ds_read_b32 v72, v7 offset:96
	ds_read_b32 v73, v7 offset:228
	ds_read_b32 v74, v7 offset:360
	ds_read_b32 v75, v7 offset:492
	ds_read_b32 v76, v7 offset:624
	ds_read_b32 v77, v7 offset:756
	ds_read_b32 v78, v7 offset:888
	ds_read_b32 v79, v7 offset:1020
	s_waitcnt lgkmcnt(0)
	v_mul_f32_e32 v48, v48, v80
	v_mul_f32_e32 v49, v49, v81
	v_mul_f32_e32 v50, v50, v82
	v_mul_f32_e32 v51, v51, v83
	v_mul_f32_e32 v52, v52, v84
	v_mul_f32_e32 v53, v53, v85
	v_mul_f32_e32 v54, v54, v86
	v_mul_f32_e32 v55, v55, v87
	v_cvt_pk_bf16_f32 v48, v48, v49
	v_cvt_pk_bf16_f32 v49, v50, v51
	v_cvt_pk_bf16_f32 v50, v52, v53
	v_cvt_pk_bf16_f32 v51, v54, v55
	v_mul_f32_e32 v56, v56, v80
	v_mul_f32_e32 v57, v57, v81
	v_mul_f32_e32 v58, v58, v82
	v_mul_f32_e32 v59, v59, v83
	v_mul_f32_e32 v60, v60, v84
	v_mul_f32_e32 v61, v61, v85
	v_mul_f32_e32 v62, v62, v86
	v_mul_f32_e32 v63, v63, v87
	v_cvt_pk_bf16_f32 v56, v56, v57
	v_cvt_pk_bf16_f32 v57, v58, v59
	v_cvt_pk_bf16_f32 v58, v60, v61
	v_cvt_pk_bf16_f32 v59, v62, v63
	v_mul_f32_e32 v64, v64, v80
	v_mul_f32_e32 v65, v65, v81
	v_mul_f32_e32 v66, v66, v82
	v_mul_f32_e32 v67, v67, v83
	v_mul_f32_e32 v68, v68, v84
	v_mul_f32_e32 v69, v69, v85
	v_mul_f32_e32 v70, v70, v86
	v_mul_f32_e32 v71, v71, v87
	v_cvt_pk_bf16_f32 v64, v64, v65
	v_cvt_pk_bf16_f32 v65, v66, v67
	v_cvt_pk_bf16_f32 v66, v68, v69
	v_cvt_pk_bf16_f32 v67, v70, v71
	v_mul_f32_e32 v72, v72, v80
	v_mul_f32_e32 v73, v73, v81
	v_mul_f32_e32 v74, v74, v82
	v_mul_f32_e32 v75, v75, v83
	v_mul_f32_e32 v76, v76, v84
	v_mul_f32_e32 v77, v77, v85
	v_mul_f32_e32 v78, v78, v86
	v_mul_f32_e32 v79, v79, v87
	v_cvt_pk_bf16_f32 v72, v72, v73
	v_cvt_pk_bf16_f32 v73, v74, v75
	v_cvt_pk_bf16_f32 v74, v76, v77
	v_cvt_pk_bf16_f32 v75, v78, v79
	s_cmp_lg_u32 s28, 0
	s_cbranch_scc1 .Ltcw3_rot
	global_store_dwordx4 v10, v[48:51], s[16:17] sc1
	global_store_dwordx4 v10, v[56:59], s[16:17] offset:256 sc1
	global_store_dwordx4 v11, v[64:67], s[16:17] offset:512 sc1
	global_store_dwordx4 v11, v[72:75], s[16:17] offset:768 sc1
	s_branch .Ltcw3_done

; #define LAS __attribute__((address_space(3)))
; __device__ __forceinline__ unsigned pk2(float lo, float hi) { f32x2 f = {lo, hi}; bf16x2_t b = __builtin_convertvector(f, bf16x2_t); return __builtin_bit_cast(unsigned, b); }
; template <int MAP, bool HASG, bool PERMW>
; __device__ __forceinline__ void tr_store(int K, int N, bf16_t* WT, LAS float* scr, int item, int lane, const float* gk) {
;     const int nblk = N / 32, kb = item / nblk, nb = item % nblk, k0 = 64 * kb, n0 = 32 * nb;
;     asm volatile("s_waitcnt lgkmcnt(0)" ::: "memory");
;     const int c = lane & 7;
;     f32x4 g0 = {1.f, 1.f, 1.f, 1.f}, g1 = {1.f, 1.f, 1.f, 1.f};
;     if (HASG) { g0 = *(const f32x4*)(gk + k0 + 8 * c); g1 = *(const f32x4*)(gk + k0 + 8 * c + 4); }
; #pragma unroll
;     for (int j = 0; j < 4; ++j) { const int n = (lane >> 3) + 8 * j; const LAS float* s = scr + (8 * c) * 33 + n;
;         u32x4 o; o.x = pk2(s[0 * 33] * g0[0], s[1 * 33] * g0[1]); o.y = pk2(s[2 * 33] * g0[2], s[3 * 33] * g0[3]); o.z = pk2(s[4 * 33] * g1[0], s[5 * 33] * g1[1]); o.w = pk2(s[6 * 33] * g1[2], s[7 * 33] * g1[3]);
;         const int wr_ = rowmap<MAP>(n0 + n), slot_ = PERMW ? ((wr_ & ~31) + invperm32(wr_ & 31)) : wr_;
;         *(u32x4*)((char*)WT + tiled_off(slot_, k0 + 8 * c, K / 64)) = o; }
;     asm volatile("s_waitcnt lgkmcnt(0)" ::: "memory");
; }
.Ltc1c_lastB:
	s_waitcnt vmcnt(0)
	ds_write_b32 v4, v88
	ds_write_b32 v4, v89 offset:264
	ds_write_b32 v4, v90 offset:528
	ds_write_b32 v4, v91 offset:792
	ds_write_b32 v4, v92 offset:1056
	ds_write_b32 v4, v93 offset:1320
	ds_write_b32 v4, v94 offset:1584
	ds_write_b32 v4, v95 offset:1848
	ds_write_b32 v4, v96 offset:2112
	ds_write_b32 v4, v97 offset:2376
	ds_write_b32 v4, v98 offset:2640
	ds_write_b32 v4, v99 offset:2904
	ds_write_b32 v4, v100 offset:3168
	ds_write_b32 v4, v101 offset:3432
	ds_write_b32 v4, v102 offset:3696
	ds_write_b32 v4, v103 offset:3960
	ds_write_b32 v4, v104 offset:4224
	ds_write_b32 v4, v105 offset:4488
	ds_write_b32 v4, v106 offset:4752
	ds_write_b32 v4, v107 offset:5016
	ds_write_b32 v4, v108 offset:5280
	ds_write_b32 v4, v109 offset:5544
	ds_write_b32 v4, v110 offset:5808
	ds_write_b32 v4, v111 offset:6072
	ds_write_b32 v4, v112 offset:6336
	ds_write_b32 v4, v113 offset:6600
	ds_write_b32 v4, v114 offset:6864
	ds_write_b32 v4, v115 offset:7128
	ds_write_b32 v4, v116 offset:7392
	ds_write_b32 v4, v117 offset:7656
	ds_write_b32 v4, v118 offset:7920
	ds_write_b32 v4, v119 offset:8184
	s_waitcnt lgkmcnt(0)
	ds_read_b32 v48, v7
	ds_read_b32 v49, v7 offset:132
	ds_read_b32 v50, v7 offset:264
	ds_read_b32 v51, v7 offset:396
	ds_read_b32 v52, v7 offset:528
	ds_read_b32 v53, v7 offset:660
	ds_read_b32 v54, v7 offset:792
	ds_read_b32 v55, v7 offset:924
	ds_read_b32 v56, v7 offset:32
	ds_read_b32 v57, v7 offset:164
	ds_read_b32 v58, v7 offset:296
	ds_read_b32 v59, v7 offset:428
	ds_read_b32 v60, v7 offset:560
	ds_read_b32 v61, v7 offset:692
	ds_read_b32 v62, v7 offset:824
	ds_read_b32 v63, v7 offset:956
	ds_read_b32 v64, v7 offset:64
	ds_read_b32 v65, v7 offset:196
	ds_read_b32 v66, v7 offset:328
	ds_read_b32 v67, v7 offset:460
	ds_read_b32 v68, v7 offset:592
	ds_read_b32 v69, v7 offset:724
	ds_read_b32 v70, v7 offset:856
	ds_read_b32 v71, v7 offset:988
	ds_read_b32 v72, v7 offset:96
	ds_read_b32 v73, v7 offset:228
	ds_read_b32 v74, v7 offset:360
	ds_read_b32 v75, v7 offset:492
	ds_read_b32 v76, v7 offset:624
	ds_read_b32 v77, v7 offset:756
	ds_read_b32 v78, v7 offset:888
	ds_read_b32 v79, v7 offset:1020
	s_waitcnt lgkmcnt(0)
	v_mul_f32_e32 v48, v48, v120
	v_mul_f32_e32 v49, v49, v121
	v_mul_f32_e32 v50, v50, v122
	v_mul_f32_e32 v51, v51, v123
	v_mul_f32_e32 v52, v52, v124
	v_mul_f32_e32 v53, v53, v125
	v_mul_f32_e32 v54, v54, v126
	v_mul_f32_e32 v55, v55, v127
	v_cvt_pk_bf16_f32 v48, v48, v49
	v_cvt_pk_bf16_f32 v49, v50, v51
	v_cvt_pk_bf16_f32 v50, v52, v53
	v_cvt_pk_bf16_f32 v51, v54, v55
	v_mul_f32_e32 v56, v56, v120
	v_mul_f32_e32 v57, v57, v121
	v_mul_f32_e32 v58, v58, v122
	v_mul_f32_e32 v59, v59, v123
	v_mul_f32_e32 v60, v60, v124
	v_mul_f32_e32 v61, v61, v125
	v_mul_f32_e32 v62, v62, v126
	v_mul_f32_e32 v63, v63, v127
	v_cvt_pk_bf16_f32 v56, v56, v57
	v_cvt_pk_bf16_f32 v57, v58, v59
	v_cvt_pk_bf16_f32 v58, v60, v61
	v_cvt_pk_bf16_f32 v59, v62, v63
	v_mul_f32_e32 v64, v64, v120
	v_mul_f32_e32 v65, v65, v121
	v_mul_f32_e32 v66, v66, v122
	v_mul_f32_e32 v67, v67, v123
	v_mul_f32_e32 v68, v68, v124
	v_mul_f32_e32 v69, v69, v125
	v_mul_f32_e32 v70, v70, v126
	v_mul_f32_e32 v71, v71, v127
	v_cvt_pk_bf16_f32 v64, v64, v65
	v_cvt_pk_bf16_f32 v65, v66, v67
	v_cvt_pk_bf16_f32 v66, v68, v69
	v_cvt_pk_bf16_f32 v67, v70, v71
	v_mul_f32_e32 v72, v72, v120
	v_mul_f32_e32 v73, v73, v121
	v_mul_f32_e32 v74, v74, v122
	v_mul_f32_e32 v75, v75, v123
	v_mul_f32_e32 v76, v76, v124
	v_mul_f32_e32 v77, v77, v125
	v_mul_f32_e32 v78, v78, v126
	v_mul_f32_e32 v79, v79, v127
	v_cvt_pk_bf16_f32 v72, v72, v73
	v_cvt_pk_bf16_f32 v73, v74, v75
	v_cvt_pk_bf16_f32 v74, v76, v77
	v_cvt_pk_bf16_f32 v75, v78, v79
	s_cmp_lg_u32 s29, 0
	s_cbranch_scc1 .Ltcw4_rot
	global_store_dwordx4 v10, v[48:51], s[24:25] sc1
	global_store_dwordx4 v10, v[56:59], s[24:25] offset:256 sc1
	global_store_dwordx4 v11, v[64:67], s[24:25] offset:512 sc1
	global_store_dwordx4 v11, v[72:75], s[24:25] offset:768 sc1
	s_branch .Ltcw4_done

; __device__ __forceinline__ void tr_load(const float* W, int N, int item, int lane, float (&wv)[32]) {
;     const int nblk = N / 32, kb = item / nblk, nb = item % nblk, k0 = 64 * kb, n0 = 32 * nb;
; #pragma unroll
;     for (int i = 0; i < 32; ++i) { const int kk = 2 * i + (lane >> 5); wv[i] = __builtin_nontemporal_load(W + (size_t)(k0 + kk) * N + n0 + (lane & 31)); }
; }
; template <int MAP, bool HASG, bool PERMW>
; __device__ __forceinline__ void tr_store(int K, int N, bf16_t* WT, LAS float* scr, int item, int lane, const float* gk) {
;     const int nblk = N / 32, kb = item / nblk, nb = item % nblk, k0 = 64 * kb, n0 = 32 * nb;
;     asm volatile("s_waitcnt lgkmcnt(0)" ::: "memory");
;     const int c = lane & 7;
;     f32x4 g0 = {1.f, 1.f, 1.f, 1.f}, g1 = {1.f, 1.f, 1.f, 1.f};
;     if (HASG) { g0 = *(const f32x4*)(gk + k0 + 8 * c); g1 = *(const f32x4*)(gk + k0 + 8 * c + 4); }
; #pragma unroll
;     for (int j = 0; j < 4; ++j) { const int n = (lane >> 3) + 8 * j; const LAS float* s = scr + (8 * c) * 33 + n;
;         u32x4 o; o.x = pk2(s[0 * 33] * g0[0], s[1 * 33] * g0[1]); o.y = pk2(s[2 * 33] * g0[2], s[3 * 33] * g0[3]); o.z = pk2(s[4 * 33] * g1[0], s[5 * 33] * g1[1]); o.w = pk2(s[6 * 33] * g1[2], s[7 * 33] * g1[3]);
;         const int wr_ = rowmap<MAP>(n0 + n), slot_ = PERMW ? ((wr_ & ~31) + invperm32(wr_ & 31)) : wr_;
;         *(u32x4*)((char*)WT + tiled_off(slot_, k0 + 8 * c, K / 64)) = o; }
;     asm volatile("s_waitcnt lgkmcnt(0)" ::: "memory");
; }
; template <int MAP, bool HASG = false, bool PERMW = false>
; __device__ __forceinline__ void transpose_mat(const float* W, int K, int N, bf16_t* WT, LAS float* scr, int gw, int ngw, int lane, const float* gk = nullptr) {
;     const int nitems = (K / 64) * (N / 32);
;     int it = gw;
;     if (it >= nitems) return;
;     float wv[32];
;     tr_load(W, N, it, lane, wv);
;     for (;;) {
;         __builtin_amdgcn_sched_barrier(0);
; #pragma unroll
;         for (int i = 0; i < 32; ++i) { const int kk = 2 * i + (lane >> 5); scr[kk * 33 + (lane & 31)] = wv[i]; }
;         __builtin_amdgcn_sched_barrier(0);
;         const int nx = it + ngw;
;         if (nx < nitems) tr_load(W, N, nx, lane, wv);
;         __builtin_amdgcn_sched_barrier(0);
;         tr_store<MAP, HASG, PERMW>(K, N, WT, scr, it, lane, gk);
;         if (nx >= nitems) break;
;         it = nx;
;     }
; }
.Ltc3a_loop:
	s_add_u32 s9, s9, s19
	s_cmpk_ge_u32 s9, 0x400
	s_cbranch_scc1 .Ltc3a_lastA
	s_lshr_b32 s11, s9, 6
	s_and_b32 s12, s9, 63
	s_lshl_b32 s13, s11, 19
	s_lshl_b32 s14, s12, 7
	s_add_u32 s13, s13, s14
	s_add_u32 s14, s4, s13
	s_addc_u32 s15, s5, 0
	global_load_dword v88, v3, s[14:15] nt
	s_add_u32 s14, s14, 0x4000
	s_addc_u32 s15, s15, 0
	global_load_dword v89, v3, s[14:15] nt
	s_add_u32 s14, s14, 0x4000
	s_addc_u32 s15, s15, 0
	global_load_dword v90, v3, s[14:15] nt
	s_add_u32 s14, s14, 0x4000
	s_addc_u32 s15, s15, 0
	global_load_dword v91, v3, s[14:15] nt
	s_add_u32 s14, s14, 0x4000
	s_addc_u32 s15, s15, 0
	global_load_dword v92, v3, s[14:15] nt
	s_add_u32 s14, s14, 0x4000
	s_addc_u32 s15, s15, 0
	global_load_dword v93, v3, s[14:15] nt
	s_add_u32 s14, s14, 0x4000
	s_addc_u32 s15, s15, 0
	global_load_dword v94, v3, s[14:15] nt
	s_add_u32 s14, s14, 0x4000
	s_addc_u32 s15, s15, 0
	global_load_dword v95, v3, s[14:15] nt
	s_add_u32 s14, s14, 0x4000
	s_addc_u32 s15, s15, 0
	global_load_dword v96, v3, s[14:15] nt
	s_add_u32 s14, s14, 0x4000
	s_addc_u32 s15, s15, 0
	global_load_dword v97, v3, s[14:15] nt
	s_add_u32 s14, s14, 0x4000
	s_addc_u32 s15, s15, 0
	global_load_dword v98, v3, s[14:15] nt
	s_add_u32 s14, s14, 0x4000
	s_addc_u32 s15, s15, 0
	global_load_dword v99, v3, s[14:15] nt
	s_add_u32 s14, s14, 0x4000
	s_addc_u32 s15, s15, 0
	global_load_dword v100, v3, s[14:15] nt
	s_add_u32 s14, s14, 0x4000
	s_addc_u32 s15, s15, 0
	global_load_dword v101, v3, s[14:15] nt
	s_add_u32 s14, s14, 0x4000
	s_addc_u32 s15, s15, 0
	global_load_dword v102, v3, s[14:15] nt
	s_add_u32 s14, s14, 0x4000
	s_addc_u32 s15, s15, 0
	global_load_dword v103, v3, s[14:15] nt
	s_add_u32 s14, s14, 0x4000
	s_addc_u32 s15, s15, 0
	global_load_dword v104, v3, s[14:15] nt
	s_add_u32 s14, s14, 0x4000
	s_addc_u32 s15, s15, 0
	global_load_dword v105, v3, s[14:15] nt
	s_add_u32 s14, s14, 0x4000
	s_addc_u32 s15, s15, 0
	global_load_dword v106, v3, s[14:15] nt
	s_add_u32 s14, s14, 0x4000
	s_addc_u32 s15, s15, 0
	global_load_dword v107, v3, s[14:15] nt
	s_add_u32 s14, s14, 0x4000
	s_addc_u32 s15, s15, 0
	global_load_dword v108, v3, s[14:15] nt
	s_add_u32 s14, s14, 0x4000
	s_addc_u32 s15, s15, 0
	global_load_dword v109, v3, s[14:15] nt
	s_add_u32 s14, s14, 0x4000
	s_addc_u32 s15, s15, 0
	global_load_dword v110, v3, s[14:15] nt
	s_add_u32 s14, s14, 0x4000
	s_addc_u32 s15, s15, 0
	global_load_dword v111, v3, s[14:15] nt
	s_add_u32 s14, s14, 0x4000
	s_addc_u32 s15, s15, 0
	global_load_dword v112, v3, s[14:15] nt
	s_add_u32 s14, s14, 0x4000
	s_addc_u32 s15, s15, 0
	global_load_dword v113, v3, s[14:15] nt
	s_add_u32 s14, s14, 0x4000
	s_addc_u32 s15, s15, 0
	global_load_dword v114, v3, s[14:15] nt
	s_add_u32 s14, s14, 0x4000
	s_addc_u32 s15, s15, 0
	global_load_dword v115, v3, s[14:15] nt
	s_add_u32 s14, s14, 0x4000
	s_addc_u32 s15, s15, 0
	global_load_dword v116, v3, s[14:15] nt
	s_add_u32 s14, s14, 0x4000
	s_addc_u32 s15, s15, 0
	global_load_dword v117, v3, s[14:15] nt
	s_add_u32 s14, s14, 0x4000
	s_addc_u32 s15, s15, 0
	global_load_dword v118, v3, s[14:15] nt
	s_add_u32 s14, s14, 0x4000
	s_addc_u32 s15, s15, 0
	global_load_dword v119, v3, s[14:15] nt
	s_lshr_b32 s24, s12, 2
	s_mul_i32 s24, s24, 0x10
	s_add_u32 s24, s24, s11
	s_lshl_b32 s24, s24, 14
	s_and_b32 s25, s12, 3
	s_lshl_b32 s25, s25, 12
	s_add_u32 s24, s24, s25
	s_add_u32 s24, s6, s24
	s_addc_u32 s25, s7, 0
	s_waitcnt vmcnt(32)
	ds_write_b32 v4, v16
	ds_write_b32 v4, v17 offset:264
	ds_write_b32 v4, v18 offset:528
	ds_write_b32 v4, v19 offset:792
	ds_write_b32 v4, v20 offset:1056
	ds_write_b32 v4, v21 offset:1320
	ds_write_b32 v4, v22 offset:1584
	ds_write_b32 v4, v23 offset:1848
	ds_write_b32 v4, v24 offset:2112
	ds_write_b32 v4, v25 offset:2376
	ds_write_b32 v4, v26 offset:2640
	ds_write_b32 v4, v27 offset:2904
	ds_write_b32 v4, v28 offset:3168
	ds_write_b32 v4, v29 offset:3432
	ds_write_b32 v4, v30 offset:3696
	ds_write_b32 v4, v31 offset:3960
	ds_write_b32 v4, v32 offset:4224
	ds_write_b32 v4, v33 offset:4488
	ds_write_b32 v4, v34 offset:4752
	ds_write_b32 v4, v35 offset:5016
	ds_write_b32 v4, v36 offset:5280
	ds_write_b32 v4, v37 offset:5544
	ds_write_b32 v4, v38 offset:5808
	ds_write_b32 v4, v39 offset:6072
	ds_write_b32 v4, v40 offset:6336
	ds_write_b32 v4, v41 offset:6600
	ds_write_b32 v4, v42 offset:6864
	ds_write_b32 v4, v43 offset:7128
	ds_write_b32 v4, v44 offset:7392
	ds_write_b32 v4, v45 offset:7656
	ds_write_b32 v4, v46 offset:7920
	ds_write_b32 v4, v47 offset:8184
	s_waitcnt lgkmcnt(0)
	ds_read_b32 v48, v7
	ds_read_b32 v49, v7 offset:132
	ds_read_b32 v50, v7 offset:264
	ds_read_b32 v51, v7 offset:396
	ds_read_b32 v52, v7 offset:528
	ds_read_b32 v53, v7 offset:660
	ds_read_b32 v54, v7 offset:792
	ds_read_b32 v55, v7 offset:924
	ds_read_b32 v56, v7 offset:32
	ds_read_b32 v57, v7 offset:164
	ds_read_b32 v58, v7 offset:296
	ds_read_b32 v59, v7 offset:428
	ds_read_b32 v60, v7 offset:560
	ds_read_b32 v61, v7 offset:692
	ds_read_b32 v62, v7 offset:824
	ds_read_b32 v63, v7 offset:956
	ds_read_b32 v64, v7 offset:64
	ds_read_b32 v65, v7 offset:196
	ds_read_b32 v66, v7 offset:328
	ds_read_b32 v67, v7 offset:460
	ds_read_b32 v68, v7 offset:592
	ds_read_b32 v69, v7 offset:724
	ds_read_b32 v70, v7 offset:856
	ds_read_b32 v71, v7 offset:988
	ds_read_b32 v72, v7 offset:96
	ds_read_b32 v73, v7 offset:228
	ds_read_b32 v74, v7 offset:360
	ds_read_b32 v75, v7 offset:492
	ds_read_b32 v76, v7 offset:624
	ds_read_b32 v77, v7 offset:756
	ds_read_b32 v78, v7 offset:888
	ds_read_b32 v79, v7 offset:1020
	s_waitcnt lgkmcnt(0)
	v_cvt_pk_bf16_f32 v48, v48, v49
	v_cvt_pk_bf16_f32 v49, v50, v51
	v_cvt_pk_bf16_f32 v50, v52, v53
	v_cvt_pk_bf16_f32 v51, v54, v55
	global_store_dwordx4 v10, v[48:51], s[16:17] sc1
	v_cvt_pk_bf16_f32 v56, v56, v57
	v_cvt_pk_bf16_f32 v57, v58, v59
	v_cvt_pk_bf16_f32 v58, v60, v61
	v_cvt_pk_bf16_f32 v59, v62, v63
	global_store_dwordx4 v10, v[56:59], s[16:17] offset:256 sc1
	v_cvt_pk_bf16_f32 v64, v64, v65
	v_cvt_pk_bf16_f32 v65, v66, v67
	v_cvt_pk_bf16_f32 v66, v68, v69
	v_cvt_pk_bf16_f32 v67, v70, v71
	global_store_dwordx4 v11, v[64:67], s[16:17] offset:512 sc1
	v_cvt_pk_bf16_f32 v72, v72, v73
	v_cvt_pk_bf16_f32 v73, v74, v75
	v_cvt_pk_bf16_f32 v74, v76, v77
	v_cvt_pk_bf16_f32 v75, v78, v79
	global_store_dwordx4 v11, v[72:75], s[16:17] offset:768 sc1
	s_add_u32 s9, s9, s19
	s_cmpk_ge_u32 s9, 0x400
	s_cbranch_scc1 .Ltc3a_lastB
; __device__ __forceinline__ void tr_load(const float* W, int N, int item, int lane, float (&wv)[32]) {
;     const int nblk = N / 32, kb = item / nblk, nb = item % nblk, k0 = 64 * kb, n0 = 32 * nb;
; #pragma unroll
;     for (int i = 0; i < 32; ++i) { const int kk = 2 * i + (lane >> 5); wv[i] = __builtin_nontemporal_load(W + (size_t)(k0 + kk) * N + n0 + (lane & 31)); }
; }
; template <int MAP, bool HASG, bool PERMW>
; __device__ __forceinline__ void tr_store(int K, int N, bf16_t* WT, LAS float* scr, int item, int lane, const float* gk) {
;     const int nblk = N / 32, kb = item / nblk, nb = item % nblk, k0 = 64 * kb, n0 = 32 * nb;
;     asm volatile("s_waitcnt lgkmcnt(0)" ::: "memory");
;     const int c = lane & 7;
;     f32x4 g0 = {1.f, 1.f, 1.f, 1.f}, g1 = {1.f, 1.f, 1.f, 1.f};
;     if (HASG) { g0 = *(const f32x4*)(gk + k0 + 8 * c); g1 = *(const f32x4*)(gk + k0 + 8 * c + 4); }
; #pragma unroll
;     for (int j = 0; j < 4; ++j) { const int n = (lane >> 3) + 8 * j; const LAS float* s = scr + (8 * c) * 33 + n;
;         u32x4 o; o.x = pk2(s[0 * 33] * g0[0], s[1 * 33] * g0[1]); o.y = pk2(s[2 * 33] * g0[2], s[3 * 33] * g0[3]); o.z = pk2(s[4 * 33] * g1[0], s[5 * 33] * g1[1]); o.w = pk2(s[6 * 33] * g1[2], s[7 * 33] * g1[3]);
;         const int wr_ = rowmap<MAP>(n0 + n), slot_ = PERMW ? ((wr_ & ~31) + invperm32(wr_ & 31)) : wr_;
;         *(u32x4*)((char*)WT + tiled_off(slot_, k0 + 8 * c, K / 64)) = o; }
;     asm volatile("s_waitcnt lgkmcnt(0)" ::: "memory");
; }
; template <int MAP, bool HASG = false, bool PERMW = false>
; __device__ __forceinline__ void transpose_mat(const float* W, int K, int N, bf16_t* WT, LAS float* scr, int gw, int ngw, int lane, const float* gk = nullptr) {
;     const int nitems = (K / 64) * (N / 32);
;     int it = gw;
;     if (it >= nitems) return;
;     float wv[32];
;     tr_load(W, N, it, lane, wv);
;     for (;;) {
;         __builtin_amdgcn_sched_barrier(0);
; #pragma unroll
;         for (int i = 0; i < 32; ++i) { const int kk = 2 * i + (lane >> 5); scr[kk * 33 + (lane & 31)] = wv[i]; }
;         __builtin_amdgcn_sched_barrier(0);
;         const int nx = it + ngw;
;         if (nx < nitems) tr_load(W, N, nx, lane, wv);
;         __builtin_amdgcn_sched_barrier(0);
;         tr_store<MAP, HASG, PERMW>(K, N, WT, scr, it, lane, gk);
;         if (nx >= nitems) break;
;         it = nx;
;     }
; }
	s_lshr_b32 s11, s9, 6
	s_and_b32 s12, s9, 63
	s_lshl_b32 s13, s11, 19
	s_lshl_b32 s14, s12, 7
	s_add_u32 s13, s13, s14
	s_add_u32 s14, s4, s13
	s_addc_u32 s15, s5, 0
	global_load_dword v16, v3, s[14:15] nt
	s_add_u32 s14, s14, 0x4000
	s_addc_u32 s15, s15, 0
	global_load_dword v17, v3, s[14:15] nt
	s_add_u32 s14, s14, 0x4000
	s_addc_u32 s15, s15, 0
	global_load_dword v18, v3, s[14:15] nt
	s_add_u32 s14, s14, 0x4000
	s_addc_u32 s15, s15, 0
	global_load_dword v19, v3, s[14:15] nt
	s_add_u32 s14, s14, 0x4000
	s_addc_u32 s15, s15, 0
	global_load_dword v20, v3, s[14:15] nt
	s_add_u32 s14, s14, 0x4000
	s_addc_u32 s15, s15, 0
	global_load_dword v21, v3, s[14:15] nt
	s_add_u32 s14, s14, 0x4000
	s_addc_u32 s15, s15, 0
	global_load_dword v22, v3, s[14:15] nt
	s_add_u32 s14, s14, 0x4000
	s_addc_u32 s15, s15, 0
	global_load_dword v23, v3, s[14:15] nt
	s_add_u32 s14, s14, 0x4000
	s_addc_u32 s15, s15, 0
	global_load_dword v24, v3, s[14:15] nt
	s_add_u32 s14, s14, 0x4000
	s_addc_u32 s15, s15, 0
	global_load_dword v25, v3, s[14:15] nt
	s_add_u32 s14, s14, 0x4000
	s_addc_u32 s15, s15, 0
	global_load_dword v26, v3, s[14:15] nt
	s_add_u32 s14, s14, 0x4000
	s_addc_u32 s15, s15, 0
	global_load_dword v27, v3, s[14:15] nt
	s_add_u32 s14, s14, 0x4000
	s_addc_u32 s15, s15, 0
	global_load_dword v28, v3, s[14:15] nt
	s_add_u32 s14, s14, 0x4000
	s_addc_u32 s15, s15, 0
	global_load_dword v29, v3, s[14:15] nt
	s_add_u32 s14, s14, 0x4000
	s_addc_u32 s15, s15, 0
	global_load_dword v30, v3, s[14:15] nt
	s_add_u32 s14, s14, 0x4000
	s_addc_u32 s15, s15, 0
	global_load_dword v31, v3, s[14:15] nt
	s_add_u32 s14, s14, 0x4000
	s_addc_u32 s15, s15, 0
	global_load_dword v32, v3, s[14:15] nt
	s_add_u32 s14, s14, 0x4000
	s_addc_u32 s15, s15, 0
	global_load_dword v33, v3, s[14:15] nt
	s_add_u32 s14, s14, 0x4000
	s_addc_u32 s15, s15, 0
	global_load_dword v34, v3, s[14:15] nt
	s_add_u32 s14, s14, 0x4000
	s_addc_u32 s15, s15, 0
	global_load_dword v35, v3, s[14:15] nt
	s_add_u32 s14, s14, 0x4000
	s_addc_u32 s15, s15, 0
	global_load_dword v36, v3, s[14:15] nt
	s_add_u32 s14, s14, 0x4000
	s_addc_u32 s15, s15, 0
	global_load_dword v37, v3, s[14:15] nt
	s_add_u32 s14, s14, 0x4000
	s_addc_u32 s15, s15, 0
	global_load_dword v38, v3, s[14:15] nt
	s_add_u32 s14, s14, 0x4000
	s_addc_u32 s15, s15, 0
	global_load_dword v39, v3, s[14:15] nt
	s_add_u32 s14, s14, 0x4000
	s_addc_u32 s15, s15, 0
	global_load_dword v40, v3, s[14:15] nt
	s_add_u32 s14, s14, 0x4000
	s_addc_u32 s15, s15, 0
	global_load_dword v41, v3, s[14:15] nt
	s_add_u32 s14, s14, 0x4000
	s_addc_u32 s15, s15, 0
	global_load_dword v42, v3, s[14:15] nt
	s_add_u32 s14, s14, 0x4000
	s_addc_u32 s15, s15, 0
	global_load_dword v43, v3, s[14:15] nt
	s_add_u32 s14, s14, 0x4000
	s_addc_u32 s15, s15, 0
	global_load_dword v44, v3, s[14:15] nt
	s_add_u32 s14, s14, 0x4000
	s_addc_u32 s15, s15, 0
	global_load_dword v45, v3, s[14:15] nt
	s_add_u32 s14, s14, 0x4000
	s_addc_u32 s15, s15, 0
	global_load_dword v46, v3, s[14:15] nt
	s_add_u32 s14, s14, 0x4000
	s_addc_u32 s15, s15, 0
	global_load_dword v47, v3, s[14:15] nt
	s_lshr_b32 s16, s12, 2
	s_mul_i32 s16, s16, 0x10
	s_add_u32 s16, s16, s11
	s_lshl_b32 s16, s16, 14
	s_and_b32 s17, s12, 3
	s_lshl_b32 s17, s17, 12
	s_add_u32 s16, s16, s17
	s_add_u32 s16, s6, s16
	s_addc_u32 s17, s7, 0
	s_waitcnt vmcnt(32)
	ds_write_b32 v4, v88
	ds_write_b32 v4, v89 offset:264
	ds_write_b32 v4, v90 offset:528
	ds_write_b32 v4, v91 offset:792
	ds_write_b32 v4, v92 offset:1056
	ds_write_b32 v4, v93 offset:1320
	ds_write_b32 v4, v94 offset:1584
	ds_write_b32 v4, v95 offset:1848
	ds_write_b32 v4, v96 offset:2112
	ds_write_b32 v4, v97 offset:2376
	ds_write_b32 v4, v98 offset:2640
	ds_write_b32 v4, v99 offset:2904
	ds_write_b32 v4, v100 offset:3168
	ds_write_b32 v4, v101 offset:3432
	ds_write_b32 v4, v102 offset:3696
	ds_write_b32 v4, v103 offset:3960
	ds_write_b32 v4, v104 offset:4224
	ds_write_b32 v4, v105 offset:4488
	ds_write_b32 v4, v106 offset:4752
	ds_write_b32 v4, v107 offset:5016
	ds_write_b32 v4, v108 offset:5280
	ds_write_b32 v4, v109 offset:5544
	ds_write_b32 v4, v110 offset:5808
	ds_write_b32 v4, v111 offset:6072
	ds_write_b32 v4, v112 offset:6336
	ds_write_b32 v4, v113 offset:6600
	ds_write_b32 v4, v114 offset:6864
	ds_write_b32 v4, v115 offset:7128
	ds_write_b32 v4, v116 offset:7392
	ds_write_b32 v4, v117 offset:7656
	ds_write_b32 v4, v118 offset:7920
	ds_write_b32 v4, v119 offset:8184
	s_waitcnt lgkmcnt(0)
	ds_read_b32 v48, v7
	ds_read_b32 v49, v7 offset:132
	ds_read_b32 v50, v7 offset:264
	ds_read_b32 v51, v7 offset:396
	ds_read_b32 v52, v7 offset:528
	ds_read_b32 v53, v7 offset:660
	ds_read_b32 v54, v7 offset:792
	ds_read_b32 v55, v7 offset:924
	ds_read_b32 v56, v7 offset:32
	ds_read_b32 v57, v7 offset:164
	ds_read_b32 v58, v7 offset:296
	ds_read_b32 v59, v7 offset:428
	ds_read_b32 v60, v7 offset:560
	ds_read_b32 v61, v7 offset:692
	ds_read_b32 v62, v7 offset:824
	ds_read_b32 v63, v7 offset:956
	ds_read_b32 v64, v7 offset:64
	ds_read_b32 v65, v7 offset:196
	ds_read_b32 v66, v7 offset:328
	ds_read_b32 v67, v7 offset:460
	ds_read_b32 v68, v7 offset:592
	ds_read_b32 v69, v7 offset:724
	ds_read_b32 v70, v7 offset:856
	ds_read_b32 v71, v7 offset:988
	ds_read_b32 v72, v7 offset:96
	ds_read_b32 v73, v7 offset:228
	ds_read_b32 v74, v7 offset:360
	ds_read_b32 v75, v7 offset:492
	ds_read_b32 v76, v7 offset:624
	ds_read_b32 v77, v7 offset:756
	ds_read_b32 v78, v7 offset:888
	ds_read_b32 v79, v7 offset:1020
	s_waitcnt lgkmcnt(0)
	v_cvt_pk_bf16_f32 v48, v48, v49
	v_cvt_pk_bf16_f32 v49, v50, v51
	v_cvt_pk_bf16_f32 v50, v52, v53
	v_cvt_pk_bf16_f32 v51, v54, v55
	global_store_dwordx4 v10, v[48:51], s[24:25] sc1
	v_cvt_pk_bf16_f32 v56, v56, v57
	v_cvt_pk_bf16_f32 v57, v58, v59
	v_cvt_pk_bf16_f32 v58, v60, v61
	v_cvt_pk_bf16_f32 v59, v62, v63
	global_store_dwordx4 v10, v[56:59], s[24:25] offset:256 sc1
	v_cvt_pk_bf16_f32 v64, v64, v65
	v_cvt_pk_bf16_f32 v65, v66, v67
	v_cvt_pk_bf16_f32 v66, v68, v69
	v_cvt_pk_bf16_f32 v67, v70, v71
	global_store_dwordx4 v11, v[64:67], s[24:25] offset:512 sc1
	v_cvt_pk_bf16_f32 v72, v72, v73
	v_cvt_pk_bf16_f32 v73, v74, v75
	v_cvt_pk_bf16_f32 v74, v76, v77
	v_cvt_pk_bf16_f32 v75, v78, v79
	global_store_dwordx4 v11, v[72:75], s[24:25] offset:768 sc1
	s_branch .Ltc3a_loop
; #define LAS __attribute__((address_space(3)))
; __device__ __forceinline__ unsigned pk2(float lo, float hi) { f32x2 f = {lo, hi}; bf16x2_t b = __builtin_convertvector(f, bf16x2_t); return __builtin_bit_cast(unsigned, b); }
; template <int MAP, bool HASG, bool PERMW>
; __device__ __forceinline__ void tr_store(int K, int N, bf16_t* WT, LAS float* scr, int item, int lane, const float* gk) {
;     const int nblk = N / 32, kb = item / nblk, nb = item % nblk, k0 = 64 * kb, n0 = 32 * nb;
;     asm volatile("s_waitcnt lgkmcnt(0)" ::: "memory");
;     const int c = lane & 7;
;     f32x4 g0 = {1.f, 1.f, 1.f, 1.f}, g1 = {1.f, 1.f, 1.f, 1.f};
;     if (HASG) { g0 = *(const f32x4*)(gk + k0 + 8 * c); g1 = *(const f32x4*)(gk + k0 + 8 * c + 4); }
; #pragma unroll
;     for (int j = 0; j < 4; ++j) { const int n = (lane >> 3) + 8 * j; const LAS float* s = scr + (8 * c) * 33 + n;
;         u32x4 o; o.x = pk2(s[0 * 33] * g0[0], s[1 * 33] * g0[1]); o.y = pk2(s[2 * 33] * g0[2], s[3 * 33] * g0[3]); o.z = pk2(s[4 * 33] * g1[0], s[5 * 33] * g1[1]); o.w = pk2(s[6 * 33] * g1[2], s[7 * 33] * g1[3]);
;         const int wr_ = rowmap<MAP>(n0 + n), slot_ = PERMW ? ((wr_ & ~31) + invperm32(wr_ & 31)) : wr_;
;         *(u32x4*)((char*)WT + tiled_off(slot_, k0 + 8 * c, K / 64)) = o; }
;     asm volatile("s_waitcnt lgkmcnt(0)" ::: "memory");
; }
; template <int MAP, bool HASG = false, bool PERMW = false>
; __device__ __forceinline__ void transpose_mat(const float* W, int K, int N, bf16_t* WT, LAS float* scr, int gw, int ngw, int lane, const float* gk = nullptr) {
;     const int nitems = (K / 64) * (N / 32);
;     int it = gw;
;     if (it >= nitems) return;
;     float wv[32];
;     tr_load(W, N, it, lane, wv);
;     for (;;) {
;         __builtin_amdgcn_sched_barrier(0);
; #pragma unroll
;         for (int i = 0; i < 32; ++i) { const int kk = 2 * i + (lane >> 5); scr[kk * 33 + (lane & 31)] = wv[i]; }
.Ltc3a_lastA:
	s_waitcnt vmcnt(0)
	ds_write_b32 v4, v16
	ds_write_b32 v4, v17 offset:264
	ds_write_b32 v4, v18 offset:528
	ds_write_b32 v4, v19 offset:792
	ds_write_b32 v4, v20 offset:1056
	ds_write_b32 v4, v21 offset:1320
	ds_write_b32 v4, v22 offset:1584
	ds_write_b32 v4, v23 offset:1848
	ds_write_b32 v4, v24 offset:2112
	ds_write_b32 v4, v25 offset:2376
	ds_write_b32 v4, v26 offset:2640
	ds_write_b32 v4, v27 offset:2904
	ds_write_b32 v4, v28 offset:3168
	ds_write_b32 v4, v29 offset:3432
	ds_write_b32 v4, v30 offset:3696
	ds_write_b32 v4, v31 offset:3960
	ds_write_b32 v4, v32 offset:4224
	ds_write_b32 v4, v33 offset:4488
	ds_write_b32 v4, v34 offset:4752
	ds_write_b32 v4, v35 offset:5016
	ds_write_b32 v4, v36 offset:5280
	ds_write_b32 v4, v37 offset:5544
	ds_write_b32 v4, v38 offset:5808
	ds_write_b32 v4, v39 offset:6072
	ds_write_b32 v4, v40 offset:6336
	ds_write_b32 v4, v41 offset:6600
	ds_write_b32 v4, v42 offset:6864
	ds_write_b32 v4, v43 offset:7128
	ds_write_b32 v4, v44 offset:7392
	ds_write_b32 v4, v45 offset:7656
	ds_write_b32 v4, v46 offset:7920
	ds_write_b32 v4, v47 offset:8184
	s_waitcnt lgkmcnt(0)
	ds_read_b32 v48, v7
	ds_read_b32 v49, v7 offset:132
	ds_read_b32 v50, v7 offset:264
	ds_read_b32 v51, v7 offset:396
	ds_read_b32 v52, v7 offset:528
	ds_read_b32 v53, v7 offset:660
	ds_read_b32 v54, v7 offset:792
	ds_read_b32 v55, v7 offset:924
	ds_read_b32 v56, v7 offset:32
	ds_read_b32 v57, v7 offset:164
	ds_read_b32 v58, v7 offset:296
	ds_read_b32 v59, v7 offset:428
	ds_read_b32 v60, v7 offset:560
	ds_read_b32 v61, v7 offset:692
	ds_read_b32 v62, v7 offset:824
	ds_read_b32 v63, v7 offset:956
	ds_read_b32 v64, v7 offset:64
	ds_read_b32 v65, v7 offset:196
	ds_read_b32 v66, v7 offset:328
	ds_read_b32 v67, v7 offset:460
	ds_read_b32 v68, v7 offset:592
	ds_read_b32 v69, v7 offset:724
	ds_read_b32 v70, v7 offset:856
	ds_read_b32 v71, v7 offset:988
	ds_read_b32 v72, v7 offset:96
	ds_read_b32 v73, v7 offset:228
	ds_read_b32 v74, v7 offset:360
	ds_read_b32 v75, v7 offset:492
	ds_read_b32 v76, v7 offset:624
	ds_read_b32 v77, v7 offset:756
	ds_read_b32 v78, v7 offset:888
	ds_read_b32 v79, v7 offset:1020
	s_waitcnt lgkmcnt(0)
	v_cvt_pk_bf16_f32 v48, v48, v49
	v_cvt_pk_bf16_f32 v49, v50, v51
	v_cvt_pk_bf16_f32 v50, v52, v53
	v_cvt_pk_bf16_f32 v51, v54, v55
	global_store_dwordx4 v10, v[48:51], s[16:17] sc1
	v_cvt_pk_bf16_f32 v56, v56, v57
	v_cvt_pk_bf16_f32 v57, v58, v59
	v_cvt_pk_bf16_f32 v58, v60, v61
	v_cvt_pk_bf16_f32 v59, v62, v63
	global_store_dwordx4 v10, v[56:59], s[16:17] offset:256 sc1
	v_cvt_pk_bf16_f32 v64, v64, v65
	v_cvt_pk_bf16_f32 v65, v66, v67
	v_cvt_pk_bf16_f32 v66, v68, v69
	v_cvt_pk_bf16_f32 v67, v70, v71
	global_store_dwordx4 v11, v[64:67], s[16:17] offset:512 sc1
	v_cvt_pk_bf16_f32 v72, v72, v73
	v_cvt_pk_bf16_f32 v73, v74, v75
	v_cvt_pk_bf16_f32 v74, v76, v77
	v_cvt_pk_bf16_f32 v75, v78, v79
	global_store_dwordx4 v11, v[72:75], s[16:17] offset:768 sc1
	s_branch .Ltc3a_exit
.Ltc3a_lastB:
	s_waitcnt vmcnt(0)
	ds_write_b32 v4, v88
	ds_write_b32 v4, v89 offset:264
	ds_write_b32 v4, v90 offset:528
	ds_write_b32 v4, v91 offset:792
	ds_write_b32 v4, v92 offset:1056
	ds_write_b32 v4, v93 offset:1320
	ds_write_b32 v4, v94 offset:1584
	ds_write_b32 v4, v95 offset:1848
	ds_write_b32 v4, v96 offset:2112
	ds_write_b32 v4, v97 offset:2376
	ds_write_b32 v4, v98 offset:2640
	ds_write_b32 v4, v99 offset:2904
	ds_write_b32 v4, v100 offset:3168
	ds_write_b32 v4, v101 offset:3432
	ds_write_b32 v4, v102 offset:3696
	ds_write_b32 v4, v103 offset:3960
	ds_write_b32 v4, v104 offset:4224
	ds_write_b32 v4, v105 offset:4488
	ds_write_b32 v4, v106 offset:4752
	ds_write_b32 v4, v107 offset:5016
	ds_write_b32 v4, v108 offset:5280
	ds_write_b32 v4, v109 offset:5544
	ds_write_b32 v4, v110 offset:5808
	ds_write_b32 v4, v111 offset:6072
	ds_write_b32 v4, v112 offset:6336
	ds_write_b32 v4, v113 offset:6600
	ds_write_b32 v4, v114 offset:6864
	ds_write_b32 v4, v115 offset:7128
	ds_write_b32 v4, v116 offset:7392
	ds_write_b32 v4, v117 offset:7656
	ds_write_b32 v4, v118 offset:7920
	ds_write_b32 v4, v119 offset:8184
	s_waitcnt lgkmcnt(0)
	ds_read_b32 v48, v7
	ds_read_b32 v49, v7 offset:132
	ds_read_b32 v50, v7 offset:264
	ds_read_b32 v51, v7 offset:396
	ds_read_b32 v52, v7 offset:528
	ds_read_b32 v53, v7 offset:660
	ds_read_b32 v54, v7 offset:792
	ds_read_b32 v55, v7 offset:924
	ds_read_b32 v56, v7 offset:32
	ds_read_b32 v57, v7 offset:164
	ds_read_b32 v58, v7 offset:296
	ds_read_b32 v59, v7 offset:428
	ds_read_b32 v60, v7 offset:560
	ds_read_b32 v61, v7 offset:692
	ds_read_b32 v62, v7 offset:824
	ds_read_b32 v63, v7 offset:956
	ds_read_b32 v64, v7 offset:64
	ds_read_b32 v65, v7 offset:196
	ds_read_b32 v66, v7 offset:328
	ds_read_b32 v67, v7 offset:460
	ds_read_b32 v68, v7 offset:592
	ds_read_b32 v69, v7 offset:724
	ds_read_b32 v70, v7 offset:856
	ds_read_b32 v71, v7 offset:988
	ds_read_b32 v72, v7 offset:96
	ds_read_b32 v73, v7 offset:228
	ds_read_b32 v74, v7 offset:360
	ds_read_b32 v75, v7 offset:492
	ds_read_b32 v76, v7 offset:624
	ds_read_b32 v77, v7 offset:756
	ds_read_b32 v78, v7 offset:888
	ds_read_b32 v79, v7 offset:1020
	s_waitcnt lgkmcnt(0)
	v_cvt_pk_bf16_f32 v48, v48, v49
	v_cvt_pk_bf16_f32 v49, v50, v51
	v_cvt_pk_bf16_f32 v50, v52, v53
	v_cvt_pk_bf16_f32 v51, v54, v55
	global_store_dwordx4 v10, v[48:51], s[24:25] sc1
	v_cvt_pk_bf16_f32 v56, v56, v57
	v_cvt_pk_bf16_f32 v57, v58, v59
	v_cvt_pk_bf16_f32 v58, v60, v61
	v_cvt_pk_bf16_f32 v59, v62, v63
	global_store_dwordx4 v10, v[56:59], s[24:25] offset:256 sc1
	v_cvt_pk_bf16_f32 v64, v64, v65
	v_cvt_pk_bf16_f32 v65, v66, v67
	v_cvt_pk_bf16_f32 v66, v68, v69
	v_cvt_pk_bf16_f32 v67, v70, v71
	global_store_dwordx4 v11, v[64:67], s[24:25] offset:512 sc1
	v_cvt_pk_bf16_f32 v72, v72, v73
	v_cvt_pk_bf16_f32 v73, v74, v75
	v_cvt_pk_bf16_f32 v74, v76, v77
	v_cvt_pk_bf16_f32 v75, v78, v79
	global_store_dwordx4 v11, v[72:75], s[24:25] offset:768 sc1

; __device__ __forceinline__ void tr_load(const float* W, int N, int item, int lane, float (&wv)[32]) {
;     const int nblk = N / 32, kb = item / nblk, nb = item % nblk, k0 = 64 * kb, n0 = 32 * nb;
; #pragma unroll
;     for (int i = 0; i < 32; ++i) { const int kk = 2 * i + (lane >> 5); wv[i] = __builtin_nontemporal_load(W + (size_t)(k0 + kk) * N + n0 + (lane & 31)); }
; }
; template <int MAP, bool HASG, bool PERMW>
; __device__ __forceinline__ void tr_store(int K, int N, bf16_t* WT, LAS float* scr, int item, int lane, const float* gk) {
;     const int nblk = N / 32, kb = item / nblk, nb = item % nblk, k0 = 64 * kb, n0 = 32 * nb;
;     asm volatile("s_waitcnt lgkmcnt(0)" ::: "memory");
;     const int c = lane & 7;
;     f32x4 g0 = {1.f, 1.f, 1.f, 1.f}, g1 = {1.f, 1.f, 1.f, 1.f};
;     if (HASG) { g0 = *(const f32x4*)(gk + k0 + 8 * c); g1 = *(const f32x4*)(gk + k0 + 8 * c + 4); }
; #pragma unroll
;     for (int j = 0; j < 4; ++j) { const int n = (lane >> 3) + 8 * j; const LAS float* s = scr + (8 * c) * 33 + n;
;         u32x4 o; o.x = pk2(s[0 * 33] * g0[0], s[1 * 33] * g0[1]); o.y = pk2(s[2 * 33] * g0[2], s[3 * 33] * g0[3]); o.z = pk2(s[4 * 33] * g1[0], s[5 * 33] * g1[1]); o.w = pk2(s[6 * 33] * g1[2], s[7 * 33] * g1[3]);
;         const int wr_ = rowmap<MAP>(n0 + n), slot_ = PERMW ? ((wr_ & ~31) + invperm32(wr_ & 31)) : wr_;
;         *(u32x4*)((char*)WT + tiled_off(slot_, k0 + 8 * c, K / 64)) = o; }
;     asm volatile("s_waitcnt lgkmcnt(0)" ::: "memory");
; }
; template <int MAP, bool HASG = false, bool PERMW = false>
; __device__ __forceinline__ void transpose_mat(const float* W, int K, int N, bf16_t* WT, LAS float* scr, int gw, int ngw, int lane, const float* gk = nullptr) {
;     const int nitems = (K / 64) * (N / 32);
;     int it = gw;
;     if (it >= nitems) return;
;     float wv[32];
;     tr_load(W, N, it, lane, wv);
;     for (;;) {
;         __builtin_amdgcn_sched_barrier(0);
; #pragma unroll
;         for (int i = 0; i < 32; ++i) { const int kk = 2 * i + (lane >> 5); scr[kk * 33 + (lane & 31)] = wv[i]; }
;         __builtin_amdgcn_sched_barrier(0);
;         const int nx = it + ngw;
;         if (nx < nitems) tr_load(W, N, nx, lane, wv);
;         __builtin_amdgcn_sched_barrier(0);
;         tr_store<MAP, HASG, PERMW>(K, N, WT, scr, it, lane, gk);
;         if (nx >= nitems) break;
;         it = nx;
;     }
; }
.Ltc3b_loop:
	s_add_u32 s9, s9, s19
	s_cmpk_ge_u32 s9, 0x800
	s_cbranch_scc1 .Ltc3b_lastA
	s_lshr_b32 s11, s9, 6
	s_and_b32 s12, s9, 63
	s_lshl_b32 s13, s11, 19
	s_lshl_b32 s14, s12, 7
	s_add_u32 s13, s13, s14
	s_add_u32 s14, s4, s13
	s_addc_u32 s15, s5, 0
	global_load_dword v88, v3, s[14:15] nt
	s_add_u32 s14, s14, 0x4000
	s_addc_u32 s15, s15, 0
	global_load_dword v89, v3, s[14:15] nt
	s_add_u32 s14, s14, 0x4000
	s_addc_u32 s15, s15, 0
	global_load_dword v90, v3, s[14:15] nt
	s_add_u32 s14, s14, 0x4000
	s_addc_u32 s15, s15, 0
	global_load_dword v91, v3, s[14:15] nt
	s_add_u32 s14, s14, 0x4000
	s_addc_u32 s15, s15, 0
	global_load_dword v92, v3, s[14:15] nt
	s_add_u32 s14, s14, 0x4000
	s_addc_u32 s15, s15, 0
	global_load_dword v93, v3, s[14:15] nt
	s_add_u32 s14, s14, 0x4000
	s_addc_u32 s15, s15, 0
	global_load_dword v94, v3, s[14:15] nt
	s_add_u32 s14, s14, 0x4000
	s_addc_u32 s15, s15, 0
	global_load_dword v95, v3, s[14:15] nt
	s_add_u32 s14, s14, 0x4000
	s_addc_u32 s15, s15, 0
	global_load_dword v96, v3, s[14:15] nt
	s_add_u32 s14, s14, 0x4000
	s_addc_u32 s15, s15, 0
	global_load_dword v97, v3, s[14:15] nt
	s_add_u32 s14, s14, 0x4000
	s_addc_u32 s15, s15, 0
	global_load_dword v98, v3, s[14:15] nt
	s_add_u32 s14, s14, 0x4000
	s_addc_u32 s15, s15, 0
	global_load_dword v99, v3, s[14:15] nt
	s_add_u32 s14, s14, 0x4000
	s_addc_u32 s15, s15, 0
	global_load_dword v100, v3, s[14:15] nt
	s_add_u32 s14, s14, 0x4000
	s_addc_u32 s15, s15, 0
	global_load_dword v101, v3, s[14:15] nt
	s_add_u32 s14, s14, 0x4000
	s_addc_u32 s15, s15, 0
	global_load_dword v102, v3, s[14:15] nt
	s_add_u32 s14, s14, 0x4000
	s_addc_u32 s15, s15, 0
	global_load_dword v103, v3, s[14:15] nt
	s_add_u32 s14, s14, 0x4000
	s_addc_u32 s15, s15, 0
	global_load_dword v104, v3, s[14:15] nt
	s_add_u32 s14, s14, 0x4000
	s_addc_u32 s15, s15, 0
	global_load_dword v105, v3, s[14:15] nt
	s_add_u32 s14, s14, 0x4000
	s_addc_u32 s15, s15, 0
	global_load_dword v106, v3, s[14:15] nt
	s_add_u32 s14, s14, 0x4000
	s_addc_u32 s15, s15, 0
	global_load_dword v107, v3, s[14:15] nt
	s_add_u32 s14, s14, 0x4000
	s_addc_u32 s15, s15, 0
	global_load_dword v108, v3, s[14:15] nt
	s_add_u32 s14, s14, 0x4000
	s_addc_u32 s15, s15, 0
	global_load_dword v109, v3, s[14:15] nt
	s_add_u32 s14, s14, 0x4000
	s_addc_u32 s15, s15, 0
	global_load_dword v110, v3, s[14:15] nt
	s_add_u32 s14, s14, 0x4000
	s_addc_u32 s15, s15, 0
	global_load_dword v111, v3, s[14:15] nt
	s_add_u32 s14, s14, 0x4000
	s_addc_u32 s15, s15, 0
	global_load_dword v112, v3, s[14:15] nt
	s_add_u32 s14, s14, 0x4000
	s_addc_u32 s15, s15, 0
	global_load_dword v113, v3, s[14:15] nt
	s_add_u32 s14, s14, 0x4000
	s_addc_u32 s15, s15, 0
	global_load_dword v114, v3, s[14:15] nt
	s_add_u32 s14, s14, 0x4000
	s_addc_u32 s15, s15, 0
	global_load_dword v115, v3, s[14:15] nt
	s_add_u32 s14, s14, 0x4000
	s_addc_u32 s15, s15, 0
	global_load_dword v116, v3, s[14:15] nt
	s_add_u32 s14, s14, 0x4000
	s_addc_u32 s15, s15, 0
	global_load_dword v117, v3, s[14:15] nt
	s_add_u32 s14, s14, 0x4000
	s_addc_u32 s15, s15, 0
	global_load_dword v118, v3, s[14:15] nt
	s_add_u32 s14, s14, 0x4000
	s_addc_u32 s15, s15, 0
	global_load_dword v119, v3, s[14:15] nt
	s_lshr_b32 s24, s12, 2
	s_mul_i32 s24, s24, 0x20
	s_add_u32 s24, s24, s11
	s_lshl_b32 s24, s24, 14
	s_and_b32 s25, s12, 3
	s_lshl_b32 s25, s25, 12
	s_add_u32 s24, s24, s25
	s_add_u32 s24, s6, s24
	s_addc_u32 s25, s7, 0
	s_waitcnt vmcnt(32)
	ds_write_b32 v4, v16
	ds_write_b32 v4, v17 offset:264
	ds_write_b32 v4, v18 offset:528
	ds_write_b32 v4, v19 offset:792
	ds_write_b32 v4, v20 offset:1056
	ds_write_b32 v4, v21 offset:1320
	ds_write_b32 v4, v22 offset:1584
	ds_write_b32 v4, v23 offset:1848
	ds_write_b32 v4, v24 offset:2112
	ds_write_b32 v4, v25 offset:2376
	ds_write_b32 v4, v26 offset:2640
	ds_write_b32 v4, v27 offset:2904
	ds_write_b32 v4, v28 offset:3168
	ds_write_b32 v4, v29 offset:3432
	ds_write_b32 v4, v30 offset:3696
	ds_write_b32 v4, v31 offset:3960
	ds_write_b32 v4, v32 offset:4224
	ds_write_b32 v4, v33 offset:4488
	ds_write_b32 v4, v34 offset:4752
	ds_write_b32 v4, v35 offset:5016
	ds_write_b32 v4, v36 offset:5280
	ds_write_b32 v4, v37 offset:5544
	ds_write_b32 v4, v38 offset:5808
	ds_write_b32 v4, v39 offset:6072
	ds_write_b32 v4, v40 offset:6336
	ds_write_b32 v4, v41 offset:6600
	ds_write_b32 v4, v42 offset:6864
	ds_write_b32 v4, v43 offset:7128
	ds_write_b32 v4, v44 offset:7392
	ds_write_b32 v4, v45 offset:7656
	ds_write_b32 v4, v46 offset:7920
	ds_write_b32 v4, v47 offset:8184
	s_waitcnt lgkmcnt(0)
	ds_read_b32 v48, v7
	ds_read_b32 v49, v7 offset:132
	ds_read_b32 v50, v7 offset:264
	ds_read_b32 v51, v7 offset:396
	ds_read_b32 v52, v7 offset:528
	ds_read_b32 v53, v7 offset:660
	ds_read_b32 v54, v7 offset:792
	ds_read_b32 v55, v7 offset:924
	ds_read_b32 v56, v7 offset:32
	ds_read_b32 v57, v7 offset:164
	ds_read_b32 v58, v7 offset:296
	ds_read_b32 v59, v7 offset:428
	ds_read_b32 v60, v7 offset:560
	ds_read_b32 v61, v7 offset:692
	ds_read_b32 v62, v7 offset:824
	ds_read_b32 v63, v7 offset:956
	ds_read_b32 v64, v7 offset:64
	ds_read_b32 v65, v7 offset:196
	ds_read_b32 v66, v7 offset:328
	ds_read_b32 v67, v7 offset:460
	ds_read_b32 v68, v7 offset:592
	ds_read_b32 v69, v7 offset:724
	ds_read_b32 v70, v7 offset:856
	ds_read_b32 v71, v7 offset:988
	ds_read_b32 v72, v7 offset:96
	ds_read_b32 v73, v7 offset:228
	ds_read_b32 v74, v7 offset:360
	ds_read_b32 v75, v7 offset:492
	ds_read_b32 v76, v7 offset:624
	ds_read_b32 v77, v7 offset:756
	ds_read_b32 v78, v7 offset:888
	ds_read_b32 v79, v7 offset:1020
	s_waitcnt lgkmcnt(0)
	v_cvt_pk_bf16_f32 v48, v48, v49
	v_cvt_pk_bf16_f32 v49, v50, v51
	v_cvt_pk_bf16_f32 v50, v52, v53
	v_cvt_pk_bf16_f32 v51, v54, v55
	global_store_dwordx4 v10, v[48:51], s[16:17] sc1
	v_cvt_pk_bf16_f32 v56, v56, v57
	v_cvt_pk_bf16_f32 v57, v58, v59
	v_cvt_pk_bf16_f32 v58, v60, v61
	v_cvt_pk_bf16_f32 v59, v62, v63
	global_store_dwordx4 v10, v[56:59], s[16:17] offset:256 sc1
	v_cvt_pk_bf16_f32 v64, v64, v65
	v_cvt_pk_bf16_f32 v65, v66, v67
	v_cvt_pk_bf16_f32 v66, v68, v69
	v_cvt_pk_bf16_f32 v67, v70, v71
	global_store_dwordx4 v11, v[64:67], s[16:17] offset:512 sc1
	v_cvt_pk_bf16_f32 v72, v72, v73
	v_cvt_pk_bf16_f32 v73, v74, v75
	v_cvt_pk_bf16_f32 v74, v76, v77
	v_cvt_pk_bf16_f32 v75, v78, v79
	global_store_dwordx4 v11, v[72:75], s[16:17] offset:768 sc1
	s_add_u32 s9, s9, s19
	s_cmpk_ge_u32 s9, 0x800
	s_cbranch_scc1 .Ltc3b_lastB
; __device__ __forceinline__ void tr_load(const float* W, int N, int item, int lane, float (&wv)[32]) {
;     const int nblk = N / 32, kb = item / nblk, nb = item % nblk, k0 = 64 * kb, n0 = 32 * nb;
; #pragma unroll
;     for (int i = 0; i < 32; ++i) { const int kk = 2 * i + (lane >> 5); wv[i] = __builtin_nontemporal_load(W + (size_t)(k0 + kk) * N + n0 + (lane & 31)); }
; }
; template <int MAP, bool HASG, bool PERMW>
; __device__ __forceinline__ void tr_store(int K, int N, bf16_t* WT, LAS float* scr, int item, int lane, const float* gk) {
;     const int nblk = N / 32, kb = item / nblk, nb = item % nblk, k0 = 64 * kb, n0 = 32 * nb;
;     asm volatile("s_waitcnt lgkmcnt(0)" ::: "memory");
;     const int c = lane & 7;
;     f32x4 g0 = {1.f, 1.f, 1.f, 1.f}, g1 = {1.f, 1.f, 1.f, 1.f};
;     if (HASG) { g0 = *(const f32x4*)(gk + k0 + 8 * c); g1 = *(const f32x4*)(gk + k0 + 8 * c + 4); }
; #pragma unroll
;     for (int j = 0; j < 4; ++j) { const int n = (lane >> 3) + 8 * j; const LAS float* s = scr + (8 * c) * 33 + n;
;         u32x4 o; o.x = pk2(s[0 * 33] * g0[0], s[1 * 33] * g0[1]); o.y = pk2(s[2 * 33] * g0[2], s[3 * 33] * g0[3]); o.z = pk2(s[4 * 33] * g1[0], s[5 * 33] * g1[1]); o.w = pk2(s[6 * 33] * g1[2], s[7 * 33] * g1[3]);
;         const int wr_ = rowmap<MAP>(n0 + n), slot_ = PERMW ? ((wr_ & ~31) + invperm32(wr_ & 31)) : wr_;
;         *(u32x4*)((char*)WT + tiled_off(slot_, k0 + 8 * c, K / 64)) = o; }
;     asm volatile("s_waitcnt lgkmcnt(0)" ::: "memory");
; }
; template <int MAP, bool HASG = false, bool PERMW = false>
; __device__ __forceinline__ void transpose_mat(const float* W, int K, int N, bf16_t* WT, LAS float* scr, int gw, int ngw, int lane, const float* gk = nullptr) {
;     const int nitems = (K / 64) * (N / 32);
;     int it = gw;
;     if (it >= nitems) return;
;     float wv[32];
;     tr_load(W, N, it, lane, wv);
;     for (;;) {
;         __builtin_amdgcn_sched_barrier(0);
; #pragma unroll
;         for (int i = 0; i < 32; ++i) { const int kk = 2 * i + (lane >> 5); scr[kk * 33 + (lane & 31)] = wv[i]; }
;         __builtin_amdgcn_sched_barrier(0);
;         const int nx = it + ngw;
;         if (nx < nitems) tr_load(W, N, nx, lane, wv);
;         __builtin_amdgcn_sched_barrier(0);
;         tr_store<MAP, HASG, PERMW>(K, N, WT, scr, it, lane, gk);
;         if (nx >= nitems) break;
;         it = nx;
;     }
; }
	s_lshr_b32 s11, s9, 6
	s_and_b32 s12, s9, 63
	s_lshl_b32 s13, s11, 19
	s_lshl_b32 s14, s12, 7
	s_add_u32 s13, s13, s14
	s_add_u32 s14, s4, s13
	s_addc_u32 s15, s5, 0
	global_load_dword v16, v3, s[14:15] nt
	s_add_u32 s14, s14, 0x4000
	s_addc_u32 s15, s15, 0
	global_load_dword v17, v3, s[14:15] nt
	s_add_u32 s14, s14, 0x4000
	s_addc_u32 s15, s15, 0
	global_load_dword v18, v3, s[14:15] nt
	s_add_u32 s14, s14, 0x4000
	s_addc_u32 s15, s15, 0
	global_load_dword v19, v3, s[14:15] nt
	s_add_u32 s14, s14, 0x4000
	s_addc_u32 s15, s15, 0
	global_load_dword v20, v3, s[14:15] nt
	s_add_u32 s14, s14, 0x4000
	s_addc_u32 s15, s15, 0
	global_load_dword v21, v3, s[14:15] nt
	s_add_u32 s14, s14, 0x4000
	s_addc_u32 s15, s15, 0
	global_load_dword v22, v3, s[14:15] nt
	s_add_u32 s14, s14, 0x4000
	s_addc_u32 s15, s15, 0
	global_load_dword v23, v3, s[14:15] nt
	s_add_u32 s14, s14, 0x4000
	s_addc_u32 s15, s15, 0
	global_load_dword v24, v3, s[14:15] nt
	s_add_u32 s14, s14, 0x4000
	s_addc_u32 s15, s15, 0
	global_load_dword v25, v3, s[14:15] nt
	s_add_u32 s14, s14, 0x4000
	s_addc_u32 s15, s15, 0
	global_load_dword v26, v3, s[14:15] nt
	s_add_u32 s14, s14, 0x4000
	s_addc_u32 s15, s15, 0
	global_load_dword v27, v3, s[14:15] nt
	s_add_u32 s14, s14, 0x4000
	s_addc_u32 s15, s15, 0
	global_load_dword v28, v3, s[14:15] nt
	s_add_u32 s14, s14, 0x4000
	s_addc_u32 s15, s15, 0
	global_load_dword v29, v3, s[14:15] nt
	s_add_u32 s14, s14, 0x4000
	s_addc_u32 s15, s15, 0
	global_load_dword v30, v3, s[14:15] nt
	s_add_u32 s14, s14, 0x4000
	s_addc_u32 s15, s15, 0
	global_load_dword v31, v3, s[14:15] nt
	s_add_u32 s14, s14, 0x4000
	s_addc_u32 s15, s15, 0
	global_load_dword v32, v3, s[14:15] nt
	s_add_u32 s14, s14, 0x4000
	s_addc_u32 s15, s15, 0
	global_load_dword v33, v3, s[14:15] nt
	s_add_u32 s14, s14, 0x4000
	s_addc_u32 s15, s15, 0
	global_load_dword v34, v3, s[14:15] nt
	s_add_u32 s14, s14, 0x4000
	s_addc_u32 s15, s15, 0
	global_load_dword v35, v3, s[14:15] nt
	s_add_u32 s14, s14, 0x4000
	s_addc_u32 s15, s15, 0
	global_load_dword v36, v3, s[14:15] nt
	s_add_u32 s14, s14, 0x4000
	s_addc_u32 s15, s15, 0
	global_load_dword v37, v3, s[14:15] nt
	s_add_u32 s14, s14, 0x4000
	s_addc_u32 s15, s15, 0
	global_load_dword v38, v3, s[14:15] nt
	s_add_u32 s14, s14, 0x4000
	s_addc_u32 s15, s15, 0
	global_load_dword v39, v3, s[14:15] nt
	s_add_u32 s14, s14, 0x4000
	s_addc_u32 s15, s15, 0
	global_load_dword v40, v3, s[14:15] nt
	s_add_u32 s14, s14, 0x4000
	s_addc_u32 s15, s15, 0
	global_load_dword v41, v3, s[14:15] nt
	s_add_u32 s14, s14, 0x4000
	s_addc_u32 s15, s15, 0
	global_load_dword v42, v3, s[14:15] nt
	s_add_u32 s14, s14, 0x4000
	s_addc_u32 s15, s15, 0
	global_load_dword v43, v3, s[14:15] nt
	s_add_u32 s14, s14, 0x4000
	s_addc_u32 s15, s15, 0
	global_load_dword v44, v3, s[14:15] nt
	s_add_u32 s14, s14, 0x4000
	s_addc_u32 s15, s15, 0
	global_load_dword v45, v3, s[14:15] nt
	s_add_u32 s14, s14, 0x4000
	s_addc_u32 s15, s15, 0
	global_load_dword v46, v3, s[14:15] nt
	s_add_u32 s14, s14, 0x4000
	s_addc_u32 s15, s15, 0
	global_load_dword v47, v3, s[14:15] nt
	s_lshr_b32 s16, s12, 2
	s_mul_i32 s16, s16, 0x20
	s_add_u32 s16, s16, s11
	s_lshl_b32 s16, s16, 14
	s_and_b32 s17, s12, 3
	s_lshl_b32 s17, s17, 12
	s_add_u32 s16, s16, s17
	s_add_u32 s16, s6, s16
	s_addc_u32 s17, s7, 0
	s_waitcnt vmcnt(32)
	ds_write_b32 v4, v88
	ds_write_b32 v4, v89 offset:264
	ds_write_b32 v4, v90 offset:528
	ds_write_b32 v4, v91 offset:792
	ds_write_b32 v4, v92 offset:1056
	ds_write_b32 v4, v93 offset:1320
	ds_write_b32 v4, v94 offset:1584
	ds_write_b32 v4, v95 offset:1848
	ds_write_b32 v4, v96 offset:2112
	ds_write_b32 v4, v97 offset:2376
	ds_write_b32 v4, v98 offset:2640
	ds_write_b32 v4, v99 offset:2904
	ds_write_b32 v4, v100 offset:3168
	ds_write_b32 v4, v101 offset:3432
	ds_write_b32 v4, v102 offset:3696
	ds_write_b32 v4, v103 offset:3960
	ds_write_b32 v4, v104 offset:4224
	ds_write_b32 v4, v105 offset:4488
	ds_write_b32 v4, v106 offset:4752
	ds_write_b32 v4, v107 offset:5016
	ds_write_b32 v4, v108 offset:5280
	ds_write_b32 v4, v109 offset:5544
	ds_write_b32 v4, v110 offset:5808
	ds_write_b32 v4, v111 offset:6072
	ds_write_b32 v4, v112 offset:6336
	ds_write_b32 v4, v113 offset:6600
	ds_write_b32 v4, v114 offset:6864
	ds_write_b32 v4, v115 offset:7128
	ds_write_b32 v4, v116 offset:7392
	ds_write_b32 v4, v117 offset:7656
	ds_write_b32 v4, v118 offset:7920
	ds_write_b32 v4, v119 offset:8184
	s_waitcnt lgkmcnt(0)
	ds_read_b32 v48, v7
	ds_read_b32 v49, v7 offset:132
	ds_read_b32 v50, v7 offset:264
	ds_read_b32 v51, v7 offset:396
	ds_read_b32 v52, v7 offset:528
	ds_read_b32 v53, v7 offset:660
	ds_read_b32 v54, v7 offset:792
	ds_read_b32 v55, v7 offset:924
	ds_read_b32 v56, v7 offset:32
	ds_read_b32 v57, v7 offset:164
	ds_read_b32 v58, v7 offset:296
	ds_read_b32 v59, v7 offset:428
	ds_read_b32 v60, v7 offset:560
	ds_read_b32 v61, v7 offset:692
	ds_read_b32 v62, v7 offset:824
	ds_read_b32 v63, v7 offset:956
	ds_read_b32 v64, v7 offset:64
	ds_read_b32 v65, v7 offset:196
	ds_read_b32 v66, v7 offset:328
	ds_read_b32 v67, v7 offset:460
	ds_read_b32 v68, v7 offset:592
	ds_read_b32 v69, v7 offset:724
	ds_read_b32 v70, v7 offset:856
	ds_read_b32 v71, v7 offset:988
	ds_read_b32 v72, v7 offset:96
	ds_read_b32 v73, v7 offset:228
	ds_read_b32 v74, v7 offset:360
	ds_read_b32 v75, v7 offset:492
	ds_read_b32 v76, v7 offset:624
	ds_read_b32 v77, v7 offset:756
	ds_read_b32 v78, v7 offset:888
	ds_read_b32 v79, v7 offset:1020
	s_waitcnt lgkmcnt(0)
	v_cvt_pk_bf16_f32 v48, v48, v49
	v_cvt_pk_bf16_f32 v49, v50, v51
	v_cvt_pk_bf16_f32 v50, v52, v53
	v_cvt_pk_bf16_f32 v51, v54, v55
	global_store_dwordx4 v10, v[48:51], s[24:25] sc1
	v_cvt_pk_bf16_f32 v56, v56, v57
	v_cvt_pk_bf16_f32 v57, v58, v59
	v_cvt_pk_bf16_f32 v58, v60, v61
	v_cvt_pk_bf16_f32 v59, v62, v63
	global_store_dwordx4 v10, v[56:59], s[24:25] offset:256 sc1
	v_cvt_pk_bf16_f32 v64, v64, v65
	v_cvt_pk_bf16_f32 v65, v66, v67
	v_cvt_pk_bf16_f32 v66, v68, v69
	v_cvt_pk_bf16_f32 v67, v70, v71
	global_store_dwordx4 v11, v[64:67], s[24:25] offset:512 sc1
	v_cvt_pk_bf16_f32 v72, v72, v73
	v_cvt_pk_bf16_f32 v73, v74, v75
	v_cvt_pk_bf16_f32 v74, v76, v77
	v_cvt_pk_bf16_f32 v75, v78, v79
	global_store_dwordx4 v11, v[72:75], s[24:25] offset:768 sc1
	s_branch .Ltc3b_loop

; __device__ __forceinline__ void tr_load(const float* W, int N, int item, int lane, float (&wv)[32]) {
;     const int nblk = N / 32, kb = item / nblk, nb = item % nblk, k0 = 64 * kb, n0 = 32 * nb;
; #pragma unroll
;     for (int i = 0; i < 32; ++i) { const int kk = 2 * i + (lane >> 5); wv[i] = __builtin_nontemporal_load(W + (size_t)(k0 + kk) * N + n0 + (lane & 31)); }
; }
; template <int MAP, bool HASG, bool PERMW>
; __device__ __forceinline__ void tr_store(int K, int N, bf16_t* WT, LAS float* scr, int item, int lane, const float* gk) {
;     const int nblk = N / 32, kb = item / nblk, nb = item % nblk, k0 = 64 * kb, n0 = 32 * nb;
;     asm volatile("s_waitcnt lgkmcnt(0)" ::: "memory");
;     const int c = lane & 7;
;     f32x4 g0 = {1.f, 1.f, 1.f, 1.f}, g1 = {1.f, 1.f, 1.f, 1.f};
;     if (HASG) { g0 = *(const f32x4*)(gk + k0 + 8 * c); g1 = *(const f32x4*)(gk + k0 + 8 * c + 4); }
; #pragma unroll
;     for (int j = 0; j < 4; ++j) { const int n = (lane >> 3) + 8 * j; const LAS float* s = scr + (8 * c) * 33 + n;
;         u32x4 o; o.x = pk2(s[0 * 33] * g0[0], s[1 * 33] * g0[1]); o.y = pk2(s[2 * 33] * g0[2], s[3 * 33] * g0[3]); o.z = pk2(s[4 * 33] * g1[0], s[5 * 33] * g1[1]); o.w = pk2(s[6 * 33] * g1[2], s[7 * 33] * g1[3]);
;         const int wr_ = rowmap<MAP>(n0 + n), slot_ = PERMW ? ((wr_ & ~31) + invperm32(wr_ & 31)) : wr_;
;         *(u32x4*)((char*)WT + tiled_off(slot_, k0 + 8 * c, K / 64)) = o; }
;     asm volatile("s_waitcnt lgkmcnt(0)" ::: "memory");
; }
; template <int MAP, bool HASG = false, bool PERMW = false>
; __device__ __forceinline__ void transpose_mat(const float* W, int K, int N, bf16_t* WT, LAS float* scr, int gw, int ngw, int lane, const float* gk = nullptr) {
;     const int nitems = (K / 64) * (N / 32);
;     int it = gw;
;     if (it >= nitems) return;
;     float wv[32];
;     tr_load(W, N, it, lane, wv);
;     for (;;) {
;         __builtin_amdgcn_sched_barrier(0);
; #pragma unroll
;         for (int i = 0; i < 32; ++i) { const int kk = 2 * i + (lane >> 5); scr[kk * 33 + (lane & 31)] = wv[i]; }
;         __builtin_amdgcn_sched_barrier(0);
;         const int nx = it + ngw;
;         if (nx < nitems) tr_load(W, N, nx, lane, wv);
;         __builtin_amdgcn_sched_barrier(0);
;         tr_store<MAP, HASG, PERMW>(K, N, WT, scr, it, lane, gk);
;         if (nx >= nitems) break;
;         it = nx;
;     }
; }
.Ltc3c_loop:
	s_add_u32 s9, s9, s19
	s_cmpk_ge_u32 s9, 0x800
	s_cbranch_scc1 .Ltc3c_lastA
	s_lshr_b32 s11, s9, 6
	s_and_b32 s12, s9, 63
	s_lshl_b32 s13, s11, 19
	s_lshl_b32 s14, s12, 7
	s_add_u32 s13, s13, s14
	s_add_u32 s14, s4, s13
	s_addc_u32 s15, s5, 0
	global_load_dword v88, v3, s[14:15] nt
	s_add_u32 s14, s14, 0x4000
	s_addc_u32 s15, s15, 0
	global_load_dword v89, v3, s[14:15] nt
	s_add_u32 s14, s14, 0x4000
	s_addc_u32 s15, s15, 0
	global_load_dword v90, v3, s[14:15] nt
	s_add_u32 s14, s14, 0x4000
	s_addc_u32 s15, s15, 0
	global_load_dword v91, v3, s[14:15] nt
	s_add_u32 s14, s14, 0x4000
	s_addc_u32 s15, s15, 0
	global_load_dword v92, v3, s[14:15] nt
	s_add_u32 s14, s14, 0x4000
	s_addc_u32 s15, s15, 0
	global_load_dword v93, v3, s[14:15] nt
	s_add_u32 s14, s14, 0x4000
	s_addc_u32 s15, s15, 0
	global_load_dword v94, v3, s[14:15] nt
	s_add_u32 s14, s14, 0x4000
	s_addc_u32 s15, s15, 0
	global_load_dword v95, v3, s[14:15] nt
	s_add_u32 s14, s14, 0x4000
	s_addc_u32 s15, s15, 0
	global_load_dword v96, v3, s[14:15] nt
	s_add_u32 s14, s14, 0x4000
	s_addc_u32 s15, s15, 0
	global_load_dword v97, v3, s[14:15] nt
	s_add_u32 s14, s14, 0x4000
	s_addc_u32 s15, s15, 0
	global_load_dword v98, v3, s[14:15] nt
	s_add_u32 s14, s14, 0x4000
	s_addc_u32 s15, s15, 0
	global_load_dword v99, v3, s[14:15] nt
	s_add_u32 s14, s14, 0x4000
	s_addc_u32 s15, s15, 0
	global_load_dword v100, v3, s[14:15] nt
	s_add_u32 s14, s14, 0x4000
	s_addc_u32 s15, s15, 0
	global_load_dword v101, v3, s[14:15] nt
	s_add_u32 s14, s14, 0x4000
	s_addc_u32 s15, s15, 0
	global_load_dword v102, v3, s[14:15] nt
	s_add_u32 s14, s14, 0x4000
	s_addc_u32 s15, s15, 0
	global_load_dword v103, v3, s[14:15] nt
	s_add_u32 s14, s14, 0x4000
	s_addc_u32 s15, s15, 0
	global_load_dword v104, v3, s[14:15] nt
	s_add_u32 s14, s14, 0x4000
	s_addc_u32 s15, s15, 0
	global_load_dword v105, v3, s[14:15] nt
	s_add_u32 s14, s14, 0x4000
	s_addc_u32 s15, s15, 0
	global_load_dword v106, v3, s[14:15] nt
	s_add_u32 s14, s14, 0x4000
	s_addc_u32 s15, s15, 0
	global_load_dword v107, v3, s[14:15] nt
	s_add_u32 s14, s14, 0x4000
	s_addc_u32 s15, s15, 0
	global_load_dword v108, v3, s[14:15] nt
	s_add_u32 s14, s14, 0x4000
	s_addc_u32 s15, s15, 0
	global_load_dword v109, v3, s[14:15] nt
	s_add_u32 s14, s14, 0x4000
	s_addc_u32 s15, s15, 0
	global_load_dword v110, v3, s[14:15] nt
	s_add_u32 s14, s14, 0x4000
	s_addc_u32 s15, s15, 0
	global_load_dword v111, v3, s[14:15] nt
	s_add_u32 s14, s14, 0x4000
	s_addc_u32 s15, s15, 0
	global_load_dword v112, v3, s[14:15] nt
	s_add_u32 s14, s14, 0x4000
	s_addc_u32 s15, s15, 0
	global_load_dword v113, v3, s[14:15] nt
	s_add_u32 s14, s14, 0x4000
	s_addc_u32 s15, s15, 0
	global_load_dword v114, v3, s[14:15] nt
	s_add_u32 s14, s14, 0x4000
	s_addc_u32 s15, s15, 0
	global_load_dword v115, v3, s[14:15] nt
	s_add_u32 s14, s14, 0x4000
	s_addc_u32 s15, s15, 0
	global_load_dword v116, v3, s[14:15] nt
	s_add_u32 s14, s14, 0x4000
	s_addc_u32 s15, s15, 0
	global_load_dword v117, v3, s[14:15] nt
	s_add_u32 s14, s14, 0x4000
	s_addc_u32 s15, s15, 0
	global_load_dword v118, v3, s[14:15] nt
	s_add_u32 s14, s14, 0x4000
	s_addc_u32 s15, s15, 0
	global_load_dword v119, v3, s[14:15] nt
	s_lshr_b32 s24, s12, 2
	s_mul_i32 s24, s24, 0x20
	s_add_u32 s24, s24, s11
	s_lshl_b32 s24, s24, 14
	s_and_b32 s25, s12, 3
	s_lshl_b32 s25, s25, 12
	s_add_u32 s24, s24, s25
	s_add_u32 s24, s6, s24
	s_addc_u32 s25, s7, 0
	s_waitcnt vmcnt(32)
	ds_write_b32 v4, v16
	ds_write_b32 v4, v17 offset:264
	ds_write_b32 v4, v18 offset:528
	ds_write_b32 v4, v19 offset:792
	ds_write_b32 v4, v20 offset:1056
	ds_write_b32 v4, v21 offset:1320
	ds_write_b32 v4, v22 offset:1584
	ds_write_b32 v4, v23 offset:1848
	ds_write_b32 v4, v24 offset:2112
	ds_write_b32 v4, v25 offset:2376
	ds_write_b32 v4, v26 offset:2640
	ds_write_b32 v4, v27 offset:2904
	ds_write_b32 v4, v28 offset:3168
	ds_write_b32 v4, v29 offset:3432
	ds_write_b32 v4, v30 offset:3696
	ds_write_b32 v4, v31 offset:3960
	ds_write_b32 v4, v32 offset:4224
	ds_write_b32 v4, v33 offset:4488
	ds_write_b32 v4, v34 offset:4752
	ds_write_b32 v4, v35 offset:5016
	ds_write_b32 v4, v36 offset:5280
	ds_write_b32 v4, v37 offset:5544
	ds_write_b32 v4, v38 offset:5808
	ds_write_b32 v4, v39 offset:6072
	ds_write_b32 v4, v40 offset:6336
	ds_write_b32 v4, v41 offset:6600
	ds_write_b32 v4, v42 offset:6864
	ds_write_b32 v4, v43 offset:7128
	ds_write_b32 v4, v44 offset:7392
	ds_write_b32 v4, v45 offset:7656
	ds_write_b32 v4, v46 offset:7920
	ds_write_b32 v4, v47 offset:8184
	s_waitcnt lgkmcnt(0)
	ds_read_b32 v48, v7
	ds_read_b32 v49, v7 offset:132
	ds_read_b32 v50, v7 offset:264
	ds_read_b32 v51, v7 offset:396
	ds_read_b32 v52, v7 offset:528
	ds_read_b32 v53, v7 offset:660
	ds_read_b32 v54, v7 offset:792
	ds_read_b32 v55, v7 offset:924
	ds_read_b32 v56, v7 offset:32
	ds_read_b32 v57, v7 offset:164
	ds_read_b32 v58, v7 offset:296
	ds_read_b32 v59, v7 offset:428
	ds_read_b32 v60, v7 offset:560
	ds_read_b32 v61, v7 offset:692
	ds_read_b32 v62, v7 offset:824
	ds_read_b32 v63, v7 offset:956
	ds_read_b32 v64, v7 offset:64
	ds_read_b32 v65, v7 offset:196
	ds_read_b32 v66, v7 offset:328
	ds_read_b32 v67, v7 offset:460
	ds_read_b32 v68, v7 offset:592
	ds_read_b32 v69, v7 offset:724
	ds_read_b32 v70, v7 offset:856
	ds_read_b32 v71, v7 offset:988
	ds_read_b32 v72, v7 offset:96
	ds_read_b32 v73, v7 offset:228
	ds_read_b32 v74, v7 offset:360
	ds_read_b32 v75, v7 offset:492
	ds_read_b32 v76, v7 offset:624
	ds_read_b32 v77, v7 offset:756
	ds_read_b32 v78, v7 offset:888
	ds_read_b32 v79, v7 offset:1020
	s_waitcnt lgkmcnt(0)
	v_cvt_pk_bf16_f32 v48, v48, v49
	v_cvt_pk_bf16_f32 v49, v50, v51
	v_cvt_pk_bf16_f32 v50, v52, v53
	v_cvt_pk_bf16_f32 v51, v54, v55
	global_store_dwordx4 v8, v[48:51], s[16:17] sc1
	v_cvt_pk_bf16_f32 v56, v56, v57
	v_cvt_pk_bf16_f32 v57, v58, v59
	v_cvt_pk_bf16_f32 v58, v60, v61
	v_cvt_pk_bf16_f32 v59, v62, v63
	global_store_dwordx4 v9, v[56:59], s[16:17] sc1
	v_cvt_pk_bf16_f32 v64, v64, v65
	v_cvt_pk_bf16_f32 v65, v66, v67
	v_cvt_pk_bf16_f32 v66, v68, v69
	v_cvt_pk_bf16_f32 v67, v70, v71
	global_store_dwordx4 v8, v[64:67], s[16:17] offset:2048 sc1
	v_cvt_pk_bf16_f32 v72, v72, v73
	v_cvt_pk_bf16_f32 v73, v74, v75
	v_cvt_pk_bf16_f32 v74, v76, v77
	v_cvt_pk_bf16_f32 v75, v78, v79
	global_store_dwordx4 v9, v[72:75], s[16:17] offset:2048 sc1
	s_add_u32 s9, s9, s19
	s_cmpk_ge_u32 s9, 0x800
	s_cbranch_scc1 .Ltc3c_lastB
; __device__ __forceinline__ void tr_load(const float* W, int N, int item, int lane, float (&wv)[32]) {
;     const int nblk = N / 32, kb = item / nblk, nb = item % nblk, k0 = 64 * kb, n0 = 32 * nb;
; #pragma unroll
;     for (int i = 0; i < 32; ++i) { const int kk = 2 * i + (lane >> 5); wv[i] = __builtin_nontemporal_load(W + (size_t)(k0 + kk) * N + n0 + (lane & 31)); }
; }
; template <int MAP, bool HASG, bool PERMW>
; __device__ __forceinline__ void tr_store(int K, int N, bf16_t* WT, LAS float* scr, int item, int lane, const float* gk) {
;     const int nblk = N / 32, kb = item / nblk, nb = item % nblk, k0 = 64 * kb, n0 = 32 * nb;
;     asm volatile("s_waitcnt lgkmcnt(0)" ::: "memory");
;     const int c = lane & 7;
;     f32x4 g0 = {1.f, 1.f, 1.f, 1.f}, g1 = {1.f, 1.f, 1.f, 1.f};
;     if (HASG) { g0 = *(const f32x4*)(gk + k0 + 8 * c); g1 = *(const f32x4*)(gk + k0 + 8 * c + 4); }
; #pragma unroll
;     for (int j = 0; j < 4; ++j) { const int n = (lane >> 3) + 8 * j; const LAS float* s = scr + (8 * c) * 33 + n;
;         u32x4 o; o.x = pk2(s[0 * 33] * g0[0], s[1 * 33] * g0[1]); o.y = pk2(s[2 * 33] * g0[2], s[3 * 33] * g0[3]); o.z = pk2(s[4 * 33] * g1[0], s[5 * 33] * g1[1]); o.w = pk2(s[6 * 33] * g1[2], s[7 * 33] * g1[3]);
;         const int wr_ = rowmap<MAP>(n0 + n), slot_ = PERMW ? ((wr_ & ~31) + invperm32(wr_ & 31)) : wr_;
;         *(u32x4*)((char*)WT + tiled_off(slot_, k0 + 8 * c, K / 64)) = o; }
;     asm volatile("s_waitcnt lgkmcnt(0)" ::: "memory");
; }
; template <int MAP, bool HASG = false, bool PERMW = false>
; __device__ __forceinline__ void transpose_mat(const float* W, int K, int N, bf16_t* WT, LAS float* scr, int gw, int ngw, int lane, const float* gk = nullptr) {
;     const int nitems = (K / 64) * (N / 32);
;     int it = gw;
;     if (it >= nitems) return;
;     float wv[32];
;     tr_load(W, N, it, lane, wv);
;     for (;;) {
;         __builtin_amdgcn_sched_barrier(0);
; #pragma unroll
;         for (int i = 0; i < 32; ++i) { const int kk = 2 * i + (lane >> 5); scr[kk * 33 + (lane & 31)] = wv[i]; }
;         __builtin_amdgcn_sched_barrier(0);
;         const int nx = it + ngw;
;         if (nx < nitems) tr_load(W, N, nx, lane, wv);
;         __builtin_amdgcn_sched_barrier(0);
;         tr_store<MAP, HASG, PERMW>(K, N, WT, scr, it, lane, gk);
;         if (nx >= nitems) break;
;         it = nx;
;     }
; }
	s_lshr_b32 s11, s9, 6
	s_and_b32 s12, s9, 63
	s_lshl_b32 s13, s11, 19
	s_lshl_b32 s14, s12, 7
	s_add_u32 s13, s13, s14
	s_add_u32 s14, s4, s13
	s_addc_u32 s15, s5, 0
	global_load_dword v16, v3, s[14:15] nt
	s_add_u32 s14, s14, 0x4000
	s_addc_u32 s15, s15, 0
	global_load_dword v17, v3, s[14:15] nt
	s_add_u32 s14, s14, 0x4000
	s_addc_u32 s15, s15, 0
	global_load_dword v18, v3, s[14:15] nt
	s_add_u32 s14, s14, 0x4000
	s_addc_u32 s15, s15, 0
	global_load_dword v19, v3, s[14:15] nt
	s_add_u32 s14, s14, 0x4000
	s_addc_u32 s15, s15, 0
	global_load_dword v20, v3, s[14:15] nt
	s_add_u32 s14, s14, 0x4000
	s_addc_u32 s15, s15, 0
	global_load_dword v21, v3, s[14:15] nt
	s_add_u32 s14, s14, 0x4000
	s_addc_u32 s15, s15, 0
	global_load_dword v22, v3, s[14:15] nt
	s_add_u32 s14, s14, 0x4000
	s_addc_u32 s15, s15, 0
	global_load_dword v23, v3, s[14:15] nt
	s_add_u32 s14, s14, 0x4000
	s_addc_u32 s15, s15, 0
	global_load_dword v24, v3, s[14:15] nt
	s_add_u32 s14, s14, 0x4000
	s_addc_u32 s15, s15, 0
	global_load_dword v25, v3, s[14:15] nt
	s_add_u32 s14, s14, 0x4000
	s_addc_u32 s15, s15, 0
	global_load_dword v26, v3, s[14:15] nt
	s_add_u32 s14, s14, 0x4000
	s_addc_u32 s15, s15, 0
	global_load_dword v27, v3, s[14:15] nt
	s_add_u32 s14, s14, 0x4000
	s_addc_u32 s15, s15, 0
	global_load_dword v28, v3, s[14:15] nt
	s_add_u32 s14, s14, 0x4000
	s_addc_u32 s15, s15, 0
	global_load_dword v29, v3, s[14:15] nt
	s_add_u32 s14, s14, 0x4000
	s_addc_u32 s15, s15, 0
	global_load_dword v30, v3, s[14:15] nt
	s_add_u32 s14, s14, 0x4000
	s_addc_u32 s15, s15, 0
	global_load_dword v31, v3, s[14:15] nt
	s_add_u32 s14, s14, 0x4000
	s_addc_u32 s15, s15, 0
	global_load_dword v32, v3, s[14:15] nt
	s_add_u32 s14, s14, 0x4000
	s_addc_u32 s15, s15, 0
	global_load_dword v33, v3, s[14:15] nt
	s_add_u32 s14, s14, 0x4000
	s_addc_u32 s15, s15, 0
	global_load_dword v34, v3, s[14:15] nt
	s_add_u32 s14, s14, 0x4000
	s_addc_u32 s15, s15, 0
	global_load_dword v35, v3, s[14:15] nt
	s_add_u32 s14, s14, 0x4000
	s_addc_u32 s15, s15, 0
	global_load_dword v36, v3, s[14:15] nt
	s_add_u32 s14, s14, 0x4000
	s_addc_u32 s15, s15, 0
	global_load_dword v37, v3, s[14:15] nt
	s_add_u32 s14, s14, 0x4000
	s_addc_u32 s15, s15, 0
	global_load_dword v38, v3, s[14:15] nt
	s_add_u32 s14, s14, 0x4000
	s_addc_u32 s15, s15, 0
	global_load_dword v39, v3, s[14:15] nt
	s_add_u32 s14, s14, 0x4000
	s_addc_u32 s15, s15, 0
	global_load_dword v40, v3, s[14:15] nt
	s_add_u32 s14, s14, 0x4000
	s_addc_u32 s15, s15, 0
	global_load_dword v41, v3, s[14:15] nt
	s_add_u32 s14, s14, 0x4000
	s_addc_u32 s15, s15, 0
	global_load_dword v42, v3, s[14:15] nt
	s_add_u32 s14, s14, 0x4000
	s_addc_u32 s15, s15, 0
	global_load_dword v43, v3, s[14:15] nt
	s_add_u32 s14, s14, 0x4000
	s_addc_u32 s15, s15, 0
	global_load_dword v44, v3, s[14:15] nt
	s_add_u32 s14, s14, 0x4000
	s_addc_u32 s15, s15, 0
	global_load_dword v45, v3, s[14:15] nt
	s_add_u32 s14, s14, 0x4000
	s_addc_u32 s15, s15, 0
	global_load_dword v46, v3, s[14:15] nt
	s_add_u32 s14, s14, 0x4000
	s_addc_u32 s15, s15, 0
	global_load_dword v47, v3, s[14:15] nt
	s_lshr_b32 s16, s12, 2
	s_mul_i32 s16, s16, 0x20
	s_add_u32 s16, s16, s11
	s_lshl_b32 s16, s16, 14
	s_and_b32 s17, s12, 3
	s_lshl_b32 s17, s17, 12
	s_add_u32 s16, s16, s17
	s_add_u32 s16, s6, s16
	s_addc_u32 s17, s7, 0
	s_waitcnt vmcnt(32)
	ds_write_b32 v4, v88
	ds_write_b32 v4, v89 offset:264
	ds_write_b32 v4, v90 offset:528
	ds_write_b32 v4, v91 offset:792
	ds_write_b32 v4, v92 offset:1056
	ds_write_b32 v4, v93 offset:1320
	ds_write_b32 v4, v94 offset:1584
	ds_write_b32 v4, v95 offset:1848
	ds_write_b32 v4, v96 offset:2112
	ds_write_b32 v4, v97 offset:2376
	ds_write_b32 v4, v98 offset:2640
	ds_write_b32 v4, v99 offset:2904
	ds_write_b32 v4, v100 offset:3168
	ds_write_b32 v4, v101 offset:3432
	ds_write_b32 v4, v102 offset:3696
	ds_write_b32 v4, v103 offset:3960
	ds_write_b32 v4, v104 offset:4224
	ds_write_b32 v4, v105 offset:4488
	ds_write_b32 v4, v106 offset:4752
	ds_write_b32 v4, v107 offset:5016
	ds_write_b32 v4, v108 offset:5280
	ds_write_b32 v4, v109 offset:5544
	ds_write_b32 v4, v110 offset:5808
	ds_write_b32 v4, v111 offset:6072
	ds_write_b32 v4, v112 offset:6336
	ds_write_b32 v4, v113 offset:6600
	ds_write_b32 v4, v114 offset:6864
	ds_write_b32 v4, v115 offset:7128
	ds_write_b32 v4, v116 offset:7392
	ds_write_b32 v4, v117 offset:7656
	ds_write_b32 v4, v118 offset:7920
	ds_write_b32 v4, v119 offset:8184
	s_waitcnt lgkmcnt(0)
	ds_read_b32 v48, v7
	ds_read_b32 v49, v7 offset:132
	ds_read_b32 v50, v7 offset:264
	ds_read_b32 v51, v7 offset:396
	ds_read_b32 v52, v7 offset:528
	ds_read_b32 v53, v7 offset:660
	ds_read_b32 v54, v7 offset:792
	ds_read_b32 v55, v7 offset:924
	ds_read_b32 v56, v7 offset:32
	ds_read_b32 v57, v7 offset:164
	ds_read_b32 v58, v7 offset:296
	ds_read_b32 v59, v7 offset:428
	ds_read_b32 v60, v7 offset:560
	ds_read_b32 v61, v7 offset:692
	ds_read_b32 v62, v7 offset:824
	ds_read_b32 v63, v7 offset:956
	ds_read_b32 v64, v7 offset:64
	ds_read_b32 v65, v7 offset:196
	ds_read_b32 v66, v7 offset:328
	ds_read_b32 v67, v7 offset:460
	ds_read_b32 v68, v7 offset:592
	ds_read_b32 v69, v7 offset:724
	ds_read_b32 v70, v7 offset:856
	ds_read_b32 v71, v7 offset:988
	ds_read_b32 v72, v7 offset:96
	ds_read_b32 v73, v7 offset:228
	ds_read_b32 v74, v7 offset:360
	ds_read_b32 v75, v7 offset:492
	ds_read_b32 v76, v7 offset:624
	ds_read_b32 v77, v7 offset:756
	ds_read_b32 v78, v7 offset:888
	ds_read_b32 v79, v7 offset:1020
	s_waitcnt lgkmcnt(0)
	v_cvt_pk_bf16_f32 v48, v48, v49
	v_cvt_pk_bf16_f32 v49, v50, v51
	v_cvt_pk_bf16_f32 v50, v52, v53
	v_cvt_pk_bf16_f32 v51, v54, v55
	global_store_dwordx4 v8, v[48:51], s[24:25] sc1
	v_cvt_pk_bf16_f32 v56, v56, v57
	v_cvt_pk_bf16_f32 v57, v58, v59
	v_cvt_pk_bf16_f32 v58, v60, v61
	v_cvt_pk_bf16_f32 v59, v62, v63
	global_store_dwordx4 v9, v[56:59], s[24:25] sc1
	v_cvt_pk_bf16_f32 v64, v64, v65
	v_cvt_pk_bf16_f32 v65, v66, v67
	v_cvt_pk_bf16_f32 v66, v68, v69
	v_cvt_pk_bf16_f32 v67, v70, v71
	global_store_dwordx4 v8, v[64:67], s[24:25] offset:2048 sc1
	v_cvt_pk_bf16_f32 v72, v72, v73
	v_cvt_pk_bf16_f32 v73, v74, v75
	v_cvt_pk_bf16_f32 v74, v76, v77
	v_cvt_pk_bf16_f32 v75, v78, v79
	global_store_dwordx4 v9, v[72:75], s[24:25] offset:2048 sc1
	s_branch .Ltc3c_loop

; __device__ __forceinline__ void tr_load(const float* W, int N, int item, int lane, float (&wv)[32]) {
;     const int nblk = N / 32, kb = item / nblk, nb = item % nblk, k0 = 64 * kb, n0 = 32 * nb;
; #pragma unroll
;     for (int i = 0; i < 32; ++i) { const int kk = 2 * i + (lane >> 5); wv[i] = __builtin_nontemporal_load(W + (size_t)(k0 + kk) * N + n0 + (lane & 31)); }
; }
; template <int MAP, bool HASG, bool PERMW>
; __device__ __forceinline__ void tr_store(int K, int N, bf16_t* WT, LAS float* scr, int item, int lane, const float* gk) {
;     const int nblk = N / 32, kb = item / nblk, nb = item % nblk, k0 = 64 * kb, n0 = 32 * nb;
;     asm volatile("s_waitcnt lgkmcnt(0)" ::: "memory");
;     const int c = lane & 7;
;     f32x4 g0 = {1.f, 1.f, 1.f, 1.f}, g1 = {1.f, 1.f, 1.f, 1.f};
;     if (HASG) { g0 = *(const f32x4*)(gk + k0 + 8 * c); g1 = *(const f32x4*)(gk + k0 + 8 * c + 4); }
; #pragma unroll
;     for (int j = 0; j < 4; ++j) { const int n = (lane >> 3) + 8 * j; const LAS float* s = scr + (8 * c) * 33 + n;
;         u32x4 o; o.x = pk2(s[0 * 33] * g0[0], s[1 * 33] * g0[1]); o.y = pk2(s[2 * 33] * g0[2], s[3 * 33] * g0[3]); o.z = pk2(s[4 * 33] * g1[0], s[5 * 33] * g1[1]); o.w = pk2(s[6 * 33] * g1[2], s[7 * 33] * g1[3]);
;         const int wr_ = rowmap<MAP>(n0 + n), slot_ = PERMW ? ((wr_ & ~31) + invperm32(wr_ & 31)) : wr_;
;         *(u32x4*)((char*)WT + tiled_off(slot_, k0 + 8 * c, K / 64)) = o; }
;     asm volatile("s_waitcnt lgkmcnt(0)" ::: "memory");
; }
; template <int MAP, bool HASG = false, bool PERMW = false>
; __device__ __forceinline__ void transpose_mat(const float* W, int K, int N, bf16_t* WT, LAS float* scr, int gw, int ngw, int lane, const float* gk = nullptr) {
;     const int nitems = (K / 64) * (N / 32);
;     int it = gw;
;     if (it >= nitems) return;
;     float wv[32];
;     tr_load(W, N, it, lane, wv);
;     for (;;) {
;         __builtin_amdgcn_sched_barrier(0);
; #pragma unroll
;         for (int i = 0; i < 32; ++i) { const int kk = 2 * i + (lane >> 5); scr[kk * 33 + (lane & 31)] = wv[i]; }
;         __builtin_amdgcn_sched_barrier(0);
;         const int nx = it + ngw;
;         if (nx < nitems) tr_load(W, N, nx, lane, wv);
;         __builtin_amdgcn_sched_barrier(0);
;         tr_store<MAP, HASG, PERMW>(K, N, WT, scr, it, lane, gk);
;         if (nx >= nitems) break;
;         it = nx;
;     }
; }
.Ltc3e_loop:
	s_add_u32 s9, s9, s19
	s_cmpk_ge_u32 s9, 0x1600
	s_cbranch_scc1 .Ltc3e_lastA
	s_mul_hi_u32 s11, s9, 0x2e8ba2e9
	s_lshr_b32 s11, s11, 5
	s_mul_i32 s12, s11, 0xb0
	s_sub_u32 s12, s9, s12
	s_mul_i32 s13, s11, 0x160000
	s_lshl_b32 s14, s12, 7
	s_add_u32 s13, s13, s14
	s_add_u32 s14, s4, s13
	s_addc_u32 s15, s5, 0
	global_load_dword v88, v15, s[14:15] nt
	s_add_u32 s14, s14, 0xb000
	s_addc_u32 s15, s15, 0
	global_load_dword v89, v15, s[14:15] nt
	s_add_u32 s14, s14, 0xb000
	s_addc_u32 s15, s15, 0
	global_load_dword v90, v15, s[14:15] nt
	s_add_u32 s14, s14, 0xb000
	s_addc_u32 s15, s15, 0
	global_load_dword v91, v15, s[14:15] nt
	s_add_u32 s14, s14, 0xb000
	s_addc_u32 s15, s15, 0
	global_load_dword v92, v15, s[14:15] nt
	s_add_u32 s14, s14, 0xb000
	s_addc_u32 s15, s15, 0
	global_load_dword v93, v15, s[14:15] nt
	s_add_u32 s14, s14, 0xb000
	s_addc_u32 s15, s15, 0
	global_load_dword v94, v15, s[14:15] nt
	s_add_u32 s14, s14, 0xb000
	s_addc_u32 s15, s15, 0
	global_load_dword v95, v15, s[14:15] nt
	s_add_u32 s14, s14, 0xb000
	s_addc_u32 s15, s15, 0
	global_load_dword v96, v15, s[14:15] nt
	s_add_u32 s14, s14, 0xb000
	s_addc_u32 s15, s15, 0
	global_load_dword v97, v15, s[14:15] nt
	s_add_u32 s14, s14, 0xb000
	s_addc_u32 s15, s15, 0
	global_load_dword v98, v15, s[14:15] nt
	s_add_u32 s14, s14, 0xb000
	s_addc_u32 s15, s15, 0
	global_load_dword v99, v15, s[14:15] nt
	s_add_u32 s14, s14, 0xb000
	s_addc_u32 s15, s15, 0
	global_load_dword v100, v15, s[14:15] nt
	s_add_u32 s14, s14, 0xb000
	s_addc_u32 s15, s15, 0
	global_load_dword v101, v15, s[14:15] nt
	s_add_u32 s14, s14, 0xb000
	s_addc_u32 s15, s15, 0
	global_load_dword v102, v15, s[14:15] nt
	s_add_u32 s14, s14, 0xb000
	s_addc_u32 s15, s15, 0
	global_load_dword v103, v15, s[14:15] nt
	s_add_u32 s14, s14, 0xb000
	s_addc_u32 s15, s15, 0
	global_load_dword v104, v15, s[14:15] nt
	s_add_u32 s14, s14, 0xb000
	s_addc_u32 s15, s15, 0
	global_load_dword v105, v15, s[14:15] nt
	s_add_u32 s14, s14, 0xb000
	s_addc_u32 s15, s15, 0
	global_load_dword v106, v15, s[14:15] nt
	s_add_u32 s14, s14, 0xb000
	s_addc_u32 s15, s15, 0
	global_load_dword v107, v15, s[14:15] nt
	s_add_u32 s14, s14, 0xb000
	s_addc_u32 s15, s15, 0
	global_load_dword v108, v15, s[14:15] nt
	s_add_u32 s14, s14, 0xb000
	s_addc_u32 s15, s15, 0
	global_load_dword v109, v15, s[14:15] nt
	s_add_u32 s14, s14, 0xb000
	s_addc_u32 s15, s15, 0
	global_load_dword v110, v15, s[14:15] nt
	s_add_u32 s14, s14, 0xb000
	s_addc_u32 s15, s15, 0
	global_load_dword v111, v15, s[14:15] nt
	s_add_u32 s14, s14, 0xb000
	s_addc_u32 s15, s15, 0
	global_load_dword v112, v15, s[14:15] nt
	s_add_u32 s14, s14, 0xb000
	s_addc_u32 s15, s15, 0
	global_load_dword v113, v15, s[14:15] nt
	s_add_u32 s14, s14, 0xb000
	s_addc_u32 s15, s15, 0
	global_load_dword v114, v15, s[14:15] nt
	s_add_u32 s14, s14, 0xb000
	s_addc_u32 s15, s15, 0
	global_load_dword v115, v15, s[14:15] nt
	s_add_u32 s14, s14, 0xb000
	s_addc_u32 s15, s15, 0
	global_load_dword v116, v15, s[14:15] nt
	s_add_u32 s14, s14, 0xb000
	s_addc_u32 s15, s15, 0
	global_load_dword v117, v15, s[14:15] nt
	s_add_u32 s14, s14, 0xb000
	s_addc_u32 s15, s15, 0
	global_load_dword v118, v15, s[14:15] nt
	s_add_u32 s14, s14, 0xb000
	s_addc_u32 s15, s15, 0
	global_load_dword v119, v15, s[14:15] nt
	s_lshl_b32 s14, s11, 8
	s_add_u32 s14, s20, s14
	s_addc_u32 s15, s21, 0
	global_load_dwordx4 v[120:123], v14, s[14:15]
	global_load_dwordx4 v[124:127], v14, s[14:15] offset:16
	s_lshr_b32 s24, s12, 2
	s_lshl_b32 s24, s24, 1
	s_lshl_b32 s24, s24, 5
	s_add_u32 s24, s24, s11
	s_lshl_b32 s24, s24, 14
	s_and_b32 s25, s12, 3
	s_lshl_b32 s25, s25, 12
	s_add_u32 s24, s24, s25
	s_add_u32 s24, s6, s24
	s_addc_u32 s25, s7, 0
	s_waitcnt vmcnt(34)
	ds_write_b32 v4, v16
	ds_write_b32 v4, v17 offset:264
	ds_write_b32 v4, v18 offset:528
	ds_write_b32 v4, v19 offset:792
	ds_write_b32 v4, v20 offset:1056
	ds_write_b32 v4, v21 offset:1320
	ds_write_b32 v4, v22 offset:1584
	ds_write_b32 v4, v23 offset:1848
	ds_write_b32 v4, v24 offset:2112
	ds_write_b32 v4, v25 offset:2376
	ds_write_b32 v4, v26 offset:2640
	ds_write_b32 v4, v27 offset:2904
	ds_write_b32 v4, v28 offset:3168
	ds_write_b32 v4, v29 offset:3432
	ds_write_b32 v4, v30 offset:3696
	ds_write_b32 v4, v31 offset:3960
	ds_write_b32 v4, v32 offset:4224
	ds_write_b32 v4, v33 offset:4488
	ds_write_b32 v4, v34 offset:4752
	ds_write_b32 v4, v35 offset:5016
	ds_write_b32 v4, v36 offset:5280
	ds_write_b32 v4, v37 offset:5544
	ds_write_b32 v4, v38 offset:5808
	ds_write_b32 v4, v39 offset:6072
	ds_write_b32 v4, v40 offset:6336
	ds_write_b32 v4, v41 offset:6600
	ds_write_b32 v4, v42 offset:6864
	ds_write_b32 v4, v43 offset:7128
	ds_write_b32 v4, v44 offset:7392
	ds_write_b32 v4, v45 offset:7656
	ds_write_b32 v4, v46 offset:7920
	ds_write_b32 v4, v47 offset:8184
	s_waitcnt lgkmcnt(0)
	ds_read_b32 v48, v7
	ds_read_b32 v49, v7 offset:132
	ds_read_b32 v50, v7 offset:264
	ds_read_b32 v51, v7 offset:396
	ds_read_b32 v52, v7 offset:528
	ds_read_b32 v53, v7 offset:660
	ds_read_b32 v54, v7 offset:792
	ds_read_b32 v55, v7 offset:924
	ds_read_b32 v56, v7 offset:32
	ds_read_b32 v57, v7 offset:164
	ds_read_b32 v58, v7 offset:296
	ds_read_b32 v59, v7 offset:428
	ds_read_b32 v60, v7 offset:560
	ds_read_b32 v61, v7 offset:692
	ds_read_b32 v62, v7 offset:824
	ds_read_b32 v63, v7 offset:956
	ds_read_b32 v64, v7 offset:64
	ds_read_b32 v65, v7 offset:196
	ds_read_b32 v66, v7 offset:328
	ds_read_b32 v67, v7 offset:460
	ds_read_b32 v68, v7 offset:592
	ds_read_b32 v69, v7 offset:724
	ds_read_b32 v70, v7 offset:856
	ds_read_b32 v71, v7 offset:988
	ds_read_b32 v72, v7 offset:96
	ds_read_b32 v73, v7 offset:228
	ds_read_b32 v74, v7 offset:360
	ds_read_b32 v75, v7 offset:492
	ds_read_b32 v76, v7 offset:624
	ds_read_b32 v77, v7 offset:756
	ds_read_b32 v78, v7 offset:888
	ds_read_b32 v79, v7 offset:1020
	s_waitcnt lgkmcnt(0)
; __device__ __forceinline__ void tr_load(const float* W, int N, int item, int lane, float (&wv)[32]) {
;     const int nblk = N / 32, kb = item / nblk, nb = item % nblk, k0 = 64 * kb, n0 = 32 * nb;
; #pragma unroll
;     for (int i = 0; i < 32; ++i) { const int kk = 2 * i + (lane >> 5); wv[i] = __builtin_nontemporal_load(W + (size_t)(k0 + kk) * N + n0 + (lane & 31)); }
; }
; template <int MAP, bool HASG, bool PERMW>
; __device__ __forceinline__ void tr_store(int K, int N, bf16_t* WT, LAS float* scr, int item, int lane, const float* gk) {
;     const int nblk = N / 32, kb = item / nblk, nb = item % nblk, k0 = 64 * kb, n0 = 32 * nb;
;     asm volatile("s_waitcnt lgkmcnt(0)" ::: "memory");
;     const int c = lane & 7;
;     f32x4 g0 = {1.f, 1.f, 1.f, 1.f}, g1 = {1.f, 1.f, 1.f, 1.f};
;     if (HASG) { g0 = *(const f32x4*)(gk + k0 + 8 * c); g1 = *(const f32x4*)(gk + k0 + 8 * c + 4); }
; #pragma unroll
;     for (int j = 0; j < 4; ++j) { const int n = (lane >> 3) + 8 * j; const LAS float* s = scr + (8 * c) * 33 + n;
;         u32x4 o; o.x = pk2(s[0 * 33] * g0[0], s[1 * 33] * g0[1]); o.y = pk2(s[2 * 33] * g0[2], s[3 * 33] * g0[3]); o.z = pk2(s[4 * 33] * g1[0], s[5 * 33] * g1[1]); o.w = pk2(s[6 * 33] * g1[2], s[7 * 33] * g1[3]);
;         const int wr_ = rowmap<MAP>(n0 + n), slot_ = PERMW ? ((wr_ & ~31) + invperm32(wr_ & 31)) : wr_;
;         *(u32x4*)((char*)WT + tiled_off(slot_, k0 + 8 * c, K / 64)) = o; }
;     asm volatile("s_waitcnt lgkmcnt(0)" ::: "memory");
; }
; template <int MAP, bool HASG = false, bool PERMW = false>
; __device__ __forceinline__ void transpose_mat(const float* W, int K, int N, bf16_t* WT, LAS float* scr, int gw, int ngw, int lane, const float* gk = nullptr) {
;     const int nitems = (K / 64) * (N / 32);
;     int it = gw;
;     if (it >= nitems) return;
;     float wv[32];
;     tr_load(W, N, it, lane, wv);
;     for (;;) {
;         __builtin_amdgcn_sched_barrier(0);
; #pragma unroll
;         for (int i = 0; i < 32; ++i) { const int kk = 2 * i + (lane >> 5); scr[kk * 33 + (lane & 31)] = wv[i]; }
;         __builtin_amdgcn_sched_barrier(0);
;         const int nx = it + ngw;
;         if (nx < nitems) tr_load(W, N, nx, lane, wv);
;         __builtin_amdgcn_sched_barrier(0);
;         tr_store<MAP, HASG, PERMW>(K, N, WT, scr, it, lane, gk);
;         if (nx >= nitems) break;
;         it = nx;
;     }
; }
	v_mul_f32_e32 v48, v48, v80
	v_mul_f32_e32 v49, v49, v81
	v_mul_f32_e32 v50, v50, v82
	v_mul_f32_e32 v51, v51, v83
	v_mul_f32_e32 v52, v52, v84
	v_mul_f32_e32 v53, v53, v85
	v_mul_f32_e32 v54, v54, v86
	v_mul_f32_e32 v55, v55, v87
	v_cvt_pk_bf16_f32 v48, v48, v49
	v_cvt_pk_bf16_f32 v49, v50, v51
	v_cvt_pk_bf16_f32 v50, v52, v53
	v_cvt_pk_bf16_f32 v51, v54, v55
	global_store_dwordx4 v10, v[48:51], s[16:17] sc1
	v_mul_f32_e32 v56, v56, v80
	v_mul_f32_e32 v57, v57, v81
	v_mul_f32_e32 v58, v58, v82
	v_mul_f32_e32 v59, v59, v83
	v_mul_f32_e32 v60, v60, v84
	v_mul_f32_e32 v61, v61, v85
	v_mul_f32_e32 v62, v62, v86
	v_mul_f32_e32 v63, v63, v87
	v_cvt_pk_bf16_f32 v56, v56, v57
	v_cvt_pk_bf16_f32 v57, v58, v59
	v_cvt_pk_bf16_f32 v58, v60, v61
	v_cvt_pk_bf16_f32 v59, v62, v63
	global_store_dwordx4 v10, v[56:59], s[16:17] offset:256 sc1
	v_mul_f32_e32 v64, v64, v80
	v_mul_f32_e32 v65, v65, v81
	v_mul_f32_e32 v66, v66, v82
	v_mul_f32_e32 v67, v67, v83
	v_mul_f32_e32 v68, v68, v84
	v_mul_f32_e32 v69, v69, v85
	v_mul_f32_e32 v70, v70, v86
	v_mul_f32_e32 v71, v71, v87
	v_cvt_pk_bf16_f32 v64, v64, v65
	v_cvt_pk_bf16_f32 v65, v66, v67
	v_cvt_pk_bf16_f32 v66, v68, v69
	v_cvt_pk_bf16_f32 v67, v70, v71
	global_store_dwordx4 v11, v[64:67], s[16:17] offset:512 sc1
	v_mul_f32_e32 v72, v72, v80
	v_mul_f32_e32 v73, v73, v81
	v_mul_f32_e32 v74, v74, v82
	v_mul_f32_e32 v75, v75, v83
	v_mul_f32_e32 v76, v76, v84
	v_mul_f32_e32 v77, v77, v85
	v_mul_f32_e32 v78, v78, v86
	v_mul_f32_e32 v79, v79, v87
	v_cvt_pk_bf16_f32 v72, v72, v73
	v_cvt_pk_bf16_f32 v73, v74, v75
	v_cvt_pk_bf16_f32 v74, v76, v77
	v_cvt_pk_bf16_f32 v75, v78, v79
	global_store_dwordx4 v11, v[72:75], s[16:17] offset:768 sc1
	s_add_u32 s9, s9, s19
	s_cmpk_ge_u32 s9, 0x1600
	s_cbranch_scc1 .Ltc3e_lastB
	s_mul_hi_u32 s11, s9, 0x2e8ba2e9
	s_lshr_b32 s11, s11, 5
	s_mul_i32 s12, s11, 0xb0
	s_sub_u32 s12, s9, s12
	s_mul_i32 s13, s11, 0x160000
	s_lshl_b32 s14, s12, 7
	s_add_u32 s13, s13, s14
	s_add_u32 s14, s4, s13
	s_addc_u32 s15, s5, 0
	global_load_dword v16, v15, s[14:15] nt
	s_add_u32 s14, s14, 0xb000
	s_addc_u32 s15, s15, 0
	global_load_dword v17, v15, s[14:15] nt
	s_add_u32 s14, s14, 0xb000
	s_addc_u32 s15, s15, 0
	global_load_dword v18, v15, s[14:15] nt
	s_add_u32 s14, s14, 0xb000
	s_addc_u32 s15, s15, 0
	global_load_dword v19, v15, s[14:15] nt
	s_add_u32 s14, s14, 0xb000
	s_addc_u32 s15, s15, 0
	global_load_dword v20, v15, s[14:15] nt
	s_add_u32 s14, s14, 0xb000
	s_addc_u32 s15, s15, 0
	global_load_dword v21, v15, s[14:15] nt
	s_add_u32 s14, s14, 0xb000
	s_addc_u32 s15, s15, 0
	global_load_dword v22, v15, s[14:15] nt
	s_add_u32 s14, s14, 0xb000
	s_addc_u32 s15, s15, 0
	global_load_dword v23, v15, s[14:15] nt
	s_add_u32 s14, s14, 0xb000
	s_addc_u32 s15, s15, 0
	global_load_dword v24, v15, s[14:15] nt
	s_add_u32 s14, s14, 0xb000
	s_addc_u32 s15, s15, 0
	global_load_dword v25, v15, s[14:15] nt
	s_add_u32 s14, s14, 0xb000
	s_addc_u32 s15, s15, 0
	global_load_dword v26, v15, s[14:15] nt
	s_add_u32 s14, s14, 0xb000
	s_addc_u32 s15, s15, 0
	global_load_dword v27, v15, s[14:15] nt
	s_add_u32 s14, s14, 0xb000
	s_addc_u32 s15, s15, 0
	global_load_dword v28, v15, s[14:15] nt
	s_add_u32 s14, s14, 0xb000
	s_addc_u32 s15, s15, 0
	global_load_dword v29, v15, s[14:15] nt
	s_add_u32 s14, s14, 0xb000
	s_addc_u32 s15, s15, 0
	global_load_dword v30, v15, s[14:15] nt
	s_add_u32 s14, s14, 0xb000
	s_addc_u32 s15, s15, 0
	global_load_dword v31, v15, s[14:15] nt
	s_add_u32 s14, s14, 0xb000
	s_addc_u32 s15, s15, 0
	global_load_dword v32, v15, s[14:15] nt
	s_add_u32 s14, s14, 0xb000
	s_addc_u32 s15, s15, 0
	global_load_dword v33, v15, s[14:15] nt
	s_add_u32 s14, s14, 0xb000
	s_addc_u32 s15, s15, 0
	global_load_dword v34, v15, s[14:15] nt
	s_add_u32 s14, s14, 0xb000
	s_addc_u32 s15, s15, 0
	global_load_dword v35, v15, s[14:15] nt
	s_add_u32 s14, s14, 0xb000
	s_addc_u32 s15, s15, 0
	global_load_dword v36, v15, s[14:15] nt
	s_add_u32 s14, s14, 0xb000
	s_addc_u32 s15, s15, 0
	global_load_dword v37, v15, s[14:15] nt
	s_add_u32 s14, s14, 0xb000
	s_addc_u32 s15, s15, 0
	global_load_dword v38, v15, s[14:15] nt
	s_add_u32 s14, s14, 0xb000
	s_addc_u32 s15, s15, 0
	global_load_dword v39, v15, s[14:15] nt
	s_add_u32 s14, s14, 0xb000
	s_addc_u32 s15, s15, 0
	global_load_dword v40, v15, s[14:15] nt
	s_add_u32 s14, s14, 0xb000
	s_addc_u32 s15, s15, 0
	global_load_dword v41, v15, s[14:15] nt
	s_add_u32 s14, s14, 0xb000
	s_addc_u32 s15, s15, 0
	global_load_dword v42, v15, s[14:15] nt
	s_add_u32 s14, s14, 0xb000
	s_addc_u32 s15, s15, 0
	global_load_dword v43, v15, s[14:15] nt
	s_add_u32 s14, s14, 0xb000
	s_addc_u32 s15, s15, 0
	global_load_dword v44, v15, s[14:15] nt
	s_add_u32 s14, s14, 0xb000
	s_addc_u32 s15, s15, 0
	global_load_dword v45, v15, s[14:15] nt
	s_add_u32 s14, s14, 0xb000
	s_addc_u32 s15, s15, 0
	global_load_dword v46, v15, s[14:15] nt
	s_add_u32 s14, s14, 0xb000
	s_addc_u32 s15, s15, 0
	global_load_dword v47, v15, s[14:15] nt
	s_lshl_b32 s14, s11, 8
	s_add_u32 s14, s20, s14
	s_addc_u32 s15, s21, 0
	global_load_dwordx4 v[80:83], v14, s[14:15]
	global_load_dwordx4 v[84:87], v14, s[14:15] offset:16
	s_lshr_b32 s16, s12, 2
	s_lshl_b32 s16, s16, 1
	s_lshl_b32 s16, s16, 5
	s_add_u32 s16, s16, s11
	s_lshl_b32 s16, s16, 14
	s_and_b32 s17, s12, 3
	s_lshl_b32 s17, s17, 12
	s_add_u32 s16, s16, s17
	s_add_u32 s16, s6, s16
	s_addc_u32 s17, s7, 0
	s_waitcnt vmcnt(34)
; __device__ __forceinline__ void tr_load(const float* W, int N, int item, int lane, float (&wv)[32]) {
;     const int nblk = N / 32, kb = item / nblk, nb = item % nblk, k0 = 64 * kb, n0 = 32 * nb;
; #pragma unroll
;     for (int i = 0; i < 32; ++i) { const int kk = 2 * i + (lane >> 5); wv[i] = __builtin_nontemporal_load(W + (size_t)(k0 + kk) * N + n0 + (lane & 31)); }
; }
; template <int MAP, bool HASG, bool PERMW>
; __device__ __forceinline__ void tr_store(int K, int N, bf16_t* WT, LAS float* scr, int item, int lane, const float* gk) {
;     const int nblk = N / 32, kb = item / nblk, nb = item % nblk, k0 = 64 * kb, n0 = 32 * nb;
;     asm volatile("s_waitcnt lgkmcnt(0)" ::: "memory");
;     const int c = lane & 7;
;     f32x4 g0 = {1.f, 1.f, 1.f, 1.f}, g1 = {1.f, 1.f, 1.f, 1.f};
;     if (HASG) { g0 = *(const f32x4*)(gk + k0 + 8 * c); g1 = *(const f32x4*)(gk + k0 + 8 * c + 4); }
; #pragma unroll
;     for (int j = 0; j < 4; ++j) { const int n = (lane >> 3) + 8 * j; const LAS float* s = scr + (8 * c) * 33 + n;
;         u32x4 o; o.x = pk2(s[0 * 33] * g0[0], s[1 * 33] * g0[1]); o.y = pk2(s[2 * 33] * g0[2], s[3 * 33] * g0[3]); o.z = pk2(s[4 * 33] * g1[0], s[5 * 33] * g1[1]); o.w = pk2(s[6 * 33] * g1[2], s[7 * 33] * g1[3]);
;         const int wr_ = rowmap<MAP>(n0 + n), slot_ = PERMW ? ((wr_ & ~31) + invperm32(wr_ & 31)) : wr_;
;         *(u32x4*)((char*)WT + tiled_off(slot_, k0 + 8 * c, K / 64)) = o; }
;     asm volatile("s_waitcnt lgkmcnt(0)" ::: "memory");
; }
; template <int MAP, bool HASG = false, bool PERMW = false>
; __device__ __forceinline__ void transpose_mat(const float* W, int K, int N, bf16_t* WT, LAS float* scr, int gw, int ngw, int lane, const float* gk = nullptr) {
;     const int nitems = (K / 64) * (N / 32);
;     int it = gw;
;     if (it >= nitems) return;
;     float wv[32];
;     tr_load(W, N, it, lane, wv);
;     for (;;) {
;         __builtin_amdgcn_sched_barrier(0);
; #pragma unroll
;         for (int i = 0; i < 32; ++i) { const int kk = 2 * i + (lane >> 5); scr[kk * 33 + (lane & 31)] = wv[i]; }
;         __builtin_amdgcn_sched_barrier(0);
;         const int nx = it + ngw;
;         if (nx < nitems) tr_load(W, N, nx, lane, wv);
;         __builtin_amdgcn_sched_barrier(0);
;         tr_store<MAP, HASG, PERMW>(K, N, WT, scr, it, lane, gk);
;         if (nx >= nitems) break;
;         it = nx;
;     }
; }
	ds_write_b32 v4, v88
	ds_write_b32 v4, v89 offset:264
	ds_write_b32 v4, v90 offset:528
	ds_write_b32 v4, v91 offset:792
	ds_write_b32 v4, v92 offset:1056
	ds_write_b32 v4, v93 offset:1320
	ds_write_b32 v4, v94 offset:1584
	ds_write_b32 v4, v95 offset:1848
	ds_write_b32 v4, v96 offset:2112
	ds_write_b32 v4, v97 offset:2376
	ds_write_b32 v4, v98 offset:2640
	ds_write_b32 v4, v99 offset:2904
	ds_write_b32 v4, v100 offset:3168
	ds_write_b32 v4, v101 offset:3432
	ds_write_b32 v4, v102 offset:3696
	ds_write_b32 v4, v103 offset:3960
	ds_write_b32 v4, v104 offset:4224
	ds_write_b32 v4, v105 offset:4488
	ds_write_b32 v4, v106 offset:4752
	ds_write_b32 v4, v107 offset:5016
	ds_write_b32 v4, v108 offset:5280
	ds_write_b32 v4, v109 offset:5544
	ds_write_b32 v4, v110 offset:5808
	ds_write_b32 v4, v111 offset:6072
	ds_write_b32 v4, v112 offset:6336
	ds_write_b32 v4, v113 offset:6600
	ds_write_b32 v4, v114 offset:6864
	ds_write_b32 v4, v115 offset:7128
	ds_write_b32 v4, v116 offset:7392
	ds_write_b32 v4, v117 offset:7656
	ds_write_b32 v4, v118 offset:7920
	ds_write_b32 v4, v119 offset:8184
	s_waitcnt lgkmcnt(0)
	ds_read_b32 v48, v7
	ds_read_b32 v49, v7 offset:132
	ds_read_b32 v50, v7 offset:264
	ds_read_b32 v51, v7 offset:396
	ds_read_b32 v52, v7 offset:528
	ds_read_b32 v53, v7 offset:660
	ds_read_b32 v54, v7 offset:792
	ds_read_b32 v55, v7 offset:924
	ds_read_b32 v56, v7 offset:32
	ds_read_b32 v57, v7 offset:164
	ds_read_b32 v58, v7 offset:296
	ds_read_b32 v59, v7 offset:428
	ds_read_b32 v60, v7 offset:560
	ds_read_b32 v61, v7 offset:692
	ds_read_b32 v62, v7 offset:824
	ds_read_b32 v63, v7 offset:956
	ds_read_b32 v64, v7 offset:64
	ds_read_b32 v65, v7 offset:196
	ds_read_b32 v66, v7 offset:328
	ds_read_b32 v67, v7 offset:460
	ds_read_b32 v68, v7 offset:592
	ds_read_b32 v69, v7 offset:724
	ds_read_b32 v70, v7 offset:856
	ds_read_b32 v71, v7 offset:988
	ds_read_b32 v72, v7 offset:96
	ds_read_b32 v73, v7 offset:228
	ds_read_b32 v74, v7 offset:360
	ds_read_b32 v75, v7 offset:492
	ds_read_b32 v76, v7 offset:624
	ds_read_b32 v77, v7 offset:756
	ds_read_b32 v78, v7 offset:888
	ds_read_b32 v79, v7 offset:1020
	s_waitcnt lgkmcnt(0)
	v_mul_f32_e32 v48, v48, v120
	v_mul_f32_e32 v49, v49, v121
	v_mul_f32_e32 v50, v50, v122
	v_mul_f32_e32 v51, v51, v123
	v_mul_f32_e32 v52, v52, v124
	v_mul_f32_e32 v53, v53, v125
	v_mul_f32_e32 v54, v54, v126
	v_mul_f32_e32 v55, v55, v127
	v_cvt_pk_bf16_f32 v48, v48, v49
	v_cvt_pk_bf16_f32 v49, v50, v51
	v_cvt_pk_bf16_f32 v50, v52, v53
	v_cvt_pk_bf16_f32 v51, v54, v55
	global_store_dwordx4 v10, v[48:51], s[24:25] sc1
	v_mul_f32_e32 v56, v56, v120
	v_mul_f32_e32 v57, v57, v121
	v_mul_f32_e32 v58, v58, v122
	v_mul_f32_e32 v59, v59, v123
	v_mul_f32_e32 v60, v60, v124
	v_mul_f32_e32 v61, v61, v125
	v_mul_f32_e32 v62, v62, v126
	v_mul_f32_e32 v63, v63, v127
	v_cvt_pk_bf16_f32 v56, v56, v57
	v_cvt_pk_bf16_f32 v57, v58, v59
	v_cvt_pk_bf16_f32 v58, v60, v61
	v_cvt_pk_bf16_f32 v59, v62, v63
	global_store_dwordx4 v10, v[56:59], s[24:25] offset:256 sc1
	v_mul_f32_e32 v64, v64, v120
	v_mul_f32_e32 v65, v65, v121
	v_mul_f32_e32 v66, v66, v122
	v_mul_f32_e32 v67, v67, v123
	v_mul_f32_e32 v68, v68, v124
	v_mul_f32_e32 v69, v69, v125
	v_mul_f32_e32 v70, v70, v126
	v_mul_f32_e32 v71, v71, v127
	v_cvt_pk_bf16_f32 v64, v64, v65
	v_cvt_pk_bf16_f32 v65, v66, v67
	v_cvt_pk_bf16_f32 v66, v68, v69
	v_cvt_pk_bf16_f32 v67, v70, v71
	global_store_dwordx4 v11, v[64:67], s[24:25] offset:512 sc1
	v_mul_f32_e32 v72, v72, v120
	v_mul_f32_e32 v73, v73, v121
	v_mul_f32_e32 v74, v74, v122
	v_mul_f32_e32 v75, v75, v123
	v_mul_f32_e32 v76, v76, v124
	v_mul_f32_e32 v77, v77, v125
	v_mul_f32_e32 v78, v78, v126
	v_mul_f32_e32 v79, v79, v127
	v_cvt_pk_bf16_f32 v72, v72, v73
	v_cvt_pk_bf16_f32 v73, v74, v75
	v_cvt_pk_bf16_f32 v74, v76, v77
	v_cvt_pk_bf16_f32 v75, v78, v79
	global_store_dwordx4 v11, v[72:75], s[24:25] offset:768 sc1
	s_branch .Ltc3e_loop
.Ltc3e_lastA:
	s_waitcnt vmcnt(0)
	ds_write_b32 v4, v16
	ds_write_b32 v4, v17 offset:264
	ds_write_b32 v4, v18 offset:528
	ds_write_b32 v4, v19 offset:792
	ds_write_b32 v4, v20 offset:1056
	ds_write_b32 v4, v21 offset:1320
	ds_write_b32 v4, v22 offset:1584
	ds_write_b32 v4, v23 offset:1848
	ds_write_b32 v4, v24 offset:2112
	ds_write_b32 v4, v25 offset:2376
	ds_write_b32 v4, v26 offset:2640
	ds_write_b32 v4, v27 offset:2904
	ds_write_b32 v4, v28 offset:3168
	ds_write_b32 v4, v29 offset:3432
	ds_write_b32 v4, v30 offset:3696
	ds_write_b32 v4, v31 offset:3960
	ds_write_b32 v4, v32 offset:4224
	ds_write_b32 v4, v33 offset:4488
	ds_write_b32 v4, v34 offset:4752
	ds_write_b32 v4, v35 offset:5016
	ds_write_b32 v4, v36 offset:5280
	ds_write_b32 v4, v37 offset:5544
	ds_write_b32 v4, v38 offset:5808
	ds_write_b32 v4, v39 offset:6072
	ds_write_b32 v4, v40 offset:6336
	ds_write_b32 v4, v41 offset:6600
	ds_write_b32 v4, v42 offset:6864
	ds_write_b32 v4, v43 offset:7128
	ds_write_b32 v4, v44 offset:7392
	ds_write_b32 v4, v45 offset:7656
	ds_write_b32 v4, v46 offset:7920
	ds_write_b32 v4, v47 offset:8184
	s_waitcnt lgkmcnt(0)
	ds_read_b32 v48, v7
	ds_read_b32 v49, v7 offset:132
	ds_read_b32 v50, v7 offset:264
	ds_read_b32 v51, v7 offset:396
	ds_read_b32 v52, v7 offset:528
	ds_read_b32 v53, v7 offset:660
	ds_read_b32 v54, v7 offset:792
	ds_read_b32 v55, v7 offset:924
	ds_read_b32 v56, v7 offset:32
	ds_read_b32 v57, v7 offset:164
	ds_read_b32 v58, v7 offset:296
	ds_read_b32 v59, v7 offset:428
	ds_read_b32 v60, v7 offset:560
	ds_read_b32 v61, v7 offset:692
	ds_read_b32 v62, v7 offset:824
	ds_read_b32 v63, v7 offset:956
	ds_read_b32 v64, v7 offset:64
	ds_read_b32 v65, v7 offset:196
	ds_read_b32 v66, v7 offset:328
	ds_read_b32 v67, v7 offset:460
	ds_read_b32 v68, v7 offset:592
	ds_read_b32 v69, v7 offset:724
	ds_read_b32 v70, v7 offset:856
	ds_read_b32 v71, v7 offset:988
	ds_read_b32 v72, v7 offset:96
	ds_read_b32 v73, v7 offset:228
	ds_read_b32 v74, v7 offset:360
	ds_read_b32 v75, v7 offset:492
	ds_read_b32 v76, v7 offset:624
	ds_read_b32 v77, v7 offset:756
	ds_read_b32 v78, v7 offset:888
	ds_read_b32 v79, v7 offset:1020
	s_waitcnt lgkmcnt(0)
; #define LAS __attribute__((address_space(3)))
; __device__ __forceinline__ unsigned pk2(float lo, float hi) { f32x2 f = {lo, hi}; bf16x2_t b = __builtin_convertvector(f, bf16x2_t); return __builtin_bit_cast(unsigned, b); }
; template <int MAP, bool HASG, bool PERMW>
; __device__ __forceinline__ void tr_store(int K, int N, bf16_t* WT, LAS float* scr, int item, int lane, const float* gk) {
;     const int nblk = N / 32, kb = item / nblk, nb = item % nblk, k0 = 64 * kb, n0 = 32 * nb;
;     asm volatile("s_waitcnt lgkmcnt(0)" ::: "memory");
;     const int c = lane & 7;
;     f32x4 g0 = {1.f, 1.f, 1.f, 1.f}, g1 = {1.f, 1.f, 1.f, 1.f};
;     if (HASG) { g0 = *(const f32x4*)(gk + k0 + 8 * c); g1 = *(const f32x4*)(gk + k0 + 8 * c + 4); }
; #pragma unroll
;     for (int j = 0; j < 4; ++j) { const int n = (lane >> 3) + 8 * j; const LAS float* s = scr + (8 * c) * 33 + n;
;         u32x4 o; o.x = pk2(s[0 * 33] * g0[0], s[1 * 33] * g0[1]); o.y = pk2(s[2 * 33] * g0[2], s[3 * 33] * g0[3]); o.z = pk2(s[4 * 33] * g1[0], s[5 * 33] * g1[1]); o.w = pk2(s[6 * 33] * g1[2], s[7 * 33] * g1[3]);
;         const int wr_ = rowmap<MAP>(n0 + n), slot_ = PERMW ? ((wr_ & ~31) + invperm32(wr_ & 31)) : wr_;
;         *(u32x4*)((char*)WT + tiled_off(slot_, k0 + 8 * c, K / 64)) = o; }
;     asm volatile("s_waitcnt lgkmcnt(0)" ::: "memory");
; }
; template <int MAP, bool HASG = false, bool PERMW = false>
; __device__ __forceinline__ void transpose_mat(const float* W, int K, int N, bf16_t* WT, LAS float* scr, int gw, int ngw, int lane, const float* gk = nullptr) {
;     const int nitems = (K / 64) * (N / 32);
;     int it = gw;
;     if (it >= nitems) return;
;     float wv[32];
;     tr_load(W, N, it, lane, wv);
;     for (;;) {
;         __builtin_amdgcn_sched_barrier(0);
; #pragma unroll
;         for (int i = 0; i < 32; ++i) { const int kk = 2 * i + (lane >> 5); scr[kk * 33 + (lane & 31)] = wv[i]; }
	v_mul_f32_e32 v48, v48, v80
	v_mul_f32_e32 v49, v49, v81
	v_mul_f32_e32 v50, v50, v82
	v_mul_f32_e32 v51, v51, v83
	v_mul_f32_e32 v52, v52, v84
	v_mul_f32_e32 v53, v53, v85
	v_mul_f32_e32 v54, v54, v86
	v_mul_f32_e32 v55, v55, v87
	v_cvt_pk_bf16_f32 v48, v48, v49
	v_cvt_pk_bf16_f32 v49, v50, v51
	v_cvt_pk_bf16_f32 v50, v52, v53
	v_cvt_pk_bf16_f32 v51, v54, v55
	global_store_dwordx4 v10, v[48:51], s[16:17] sc1
	v_mul_f32_e32 v56, v56, v80
	v_mul_f32_e32 v57, v57, v81
	v_mul_f32_e32 v58, v58, v82
	v_mul_f32_e32 v59, v59, v83
	v_mul_f32_e32 v60, v60, v84
	v_mul_f32_e32 v61, v61, v85
	v_mul_f32_e32 v62, v62, v86
	v_mul_f32_e32 v63, v63, v87
	v_cvt_pk_bf16_f32 v56, v56, v57
	v_cvt_pk_bf16_f32 v57, v58, v59
	v_cvt_pk_bf16_f32 v58, v60, v61
	v_cvt_pk_bf16_f32 v59, v62, v63
	global_store_dwordx4 v10, v[56:59], s[16:17] offset:256 sc1
	v_mul_f32_e32 v64, v64, v80
	v_mul_f32_e32 v65, v65, v81
	v_mul_f32_e32 v66, v66, v82
	v_mul_f32_e32 v67, v67, v83
	v_mul_f32_e32 v68, v68, v84
	v_mul_f32_e32 v69, v69, v85
	v_mul_f32_e32 v70, v70, v86
	v_mul_f32_e32 v71, v71, v87
	v_cvt_pk_bf16_f32 v64, v64, v65
	v_cvt_pk_bf16_f32 v65, v66, v67
	v_cvt_pk_bf16_f32 v66, v68, v69
	v_cvt_pk_bf16_f32 v67, v70, v71
	global_store_dwordx4 v11, v[64:67], s[16:17] offset:512 sc1
	v_mul_f32_e32 v72, v72, v80
	v_mul_f32_e32 v73, v73, v81
	v_mul_f32_e32 v74, v74, v82
	v_mul_f32_e32 v75, v75, v83
	v_mul_f32_e32 v76, v76, v84
	v_mul_f32_e32 v77, v77, v85
	v_mul_f32_e32 v78, v78, v86
	v_mul_f32_e32 v79, v79, v87
	v_cvt_pk_bf16_f32 v72, v72, v73
	v_cvt_pk_bf16_f32 v73, v74, v75
	v_cvt_pk_bf16_f32 v74, v76, v77
	v_cvt_pk_bf16_f32 v75, v78, v79
	global_store_dwordx4 v11, v[72:75], s[16:17] offset:768 sc1
	s_branch .Ltc3e_exit
.Ltc3e_lastB:
	s_waitcnt vmcnt(0)
	ds_write_b32 v4, v88
	ds_write_b32 v4, v89 offset:264
	ds_write_b32 v4, v90 offset:528
	ds_write_b32 v4, v91 offset:792
	ds_write_b32 v4, v92 offset:1056
	ds_write_b32 v4, v93 offset:1320
	ds_write_b32 v4, v94 offset:1584
	ds_write_b32 v4, v95 offset:1848
	ds_write_b32 v4, v96 offset:2112
	ds_write_b32 v4, v97 offset:2376
	ds_write_b32 v4, v98 offset:2640
	ds_write_b32 v4, v99 offset:2904
	ds_write_b32 v4, v100 offset:3168
	ds_write_b32 v4, v101 offset:3432
	ds_write_b32 v4, v102 offset:3696
	ds_write_b32 v4, v103 offset:3960
	ds_write_b32 v4, v104 offset:4224
	ds_write_b32 v4, v105 offset:4488
	ds_write_b32 v4, v106 offset:4752
	ds_write_b32 v4, v107 offset:5016
	ds_write_b32 v4, v108 offset:5280
	ds_write_b32 v4, v109 offset:5544
	ds_write_b32 v4, v110 offset:5808
	ds_write_b32 v4, v111 offset:6072
	ds_write_b32 v4, v112 offset:6336
	ds_write_b32 v4, v113 offset:6600
	ds_write_b32 v4, v114 offset:6864
	ds_write_b32 v4, v115 offset:7128
	ds_write_b32 v4, v116 offset:7392
	ds_write_b32 v4, v117 offset:7656
	ds_write_b32 v4, v118 offset:7920
	ds_write_b32 v4, v119 offset:8184
	s_waitcnt lgkmcnt(0)
	ds_read_b32 v48, v7
	ds_read_b32 v49, v7 offset:132
	ds_read_b32 v50, v7 offset:264
	ds_read_b32 v51, v7 offset:396
	ds_read_b32 v52, v7 offset:528
	ds_read_b32 v53, v7 offset:660
	ds_read_b32 v54, v7 offset:792
	ds_read_b32 v55, v7 offset:924
	ds_read_b32 v56, v7 offset:32
	ds_read_b32 v57, v7 offset:164
	ds_read_b32 v58, v7 offset:296
	ds_read_b32 v59, v7 offset:428
	ds_read_b32 v60, v7 offset:560
	ds_read_b32 v61, v7 offset:692
	ds_read_b32 v62, v7 offset:824
	ds_read_b32 v63, v7 offset:956
	ds_read_b32 v64, v7 offset:64
	ds_read_b32 v65, v7 offset:196
	ds_read_b32 v66, v7 offset:328
	ds_read_b32 v67, v7 offset:460
	ds_read_b32 v68, v7 offset:592
	ds_read_b32 v69, v7 offset:724
	ds_read_b32 v70, v7 offset:856
	ds_read_b32 v71, v7 offset:988
	ds_read_b32 v72, v7 offset:96
	ds_read_b32 v73, v7 offset:228
	ds_read_b32 v74, v7 offset:360
	ds_read_b32 v75, v7 offset:492
	ds_read_b32 v76, v7 offset:624
	ds_read_b32 v77, v7 offset:756
	ds_read_b32 v78, v7 offset:888
	ds_read_b32 v79, v7 offset:1020
	s_waitcnt lgkmcnt(0)
	v_mul_f32_e32 v48, v48, v120
	v_mul_f32_e32 v49, v49, v121
	v_mul_f32_e32 v50, v50, v122
	v_mul_f32_e32 v51, v51, v123
	v_mul_f32_e32 v52, v52, v124
	v_mul_f32_e32 v53, v53, v125
	v_mul_f32_e32 v54, v54, v126
	v_mul_f32_e32 v55, v55, v127
	v_cvt_pk_bf16_f32 v48, v48, v49
	v_cvt_pk_bf16_f32 v49, v50, v51
	v_cvt_pk_bf16_f32 v50, v52, v53
	v_cvt_pk_bf16_f32 v51, v54, v55
	global_store_dwordx4 v10, v[48:51], s[24:25] sc1
	v_mul_f32_e32 v56, v56, v120
	v_mul_f32_e32 v57, v57, v121
	v_mul_f32_e32 v58, v58, v122
	v_mul_f32_e32 v59, v59, v123
	v_mul_f32_e32 v60, v60, v124
	v_mul_f32_e32 v61, v61, v125
	v_mul_f32_e32 v62, v62, v126
	v_mul_f32_e32 v63, v63, v127
	v_cvt_pk_bf16_f32 v56, v56, v57
	v_cvt_pk_bf16_f32 v57, v58, v59
	v_cvt_pk_bf16_f32 v58, v60, v61
	v_cvt_pk_bf16_f32 v59, v62, v63
	global_store_dwordx4 v10, v[56:59], s[24:25] offset:256 sc1
	v_mul_f32_e32 v64, v64, v120
	v_mul_f32_e32 v65, v65, v121
	v_mul_f32_e32 v66, v66, v122
	v_mul_f32_e32 v67, v67, v123
	v_mul_f32_e32 v68, v68, v124
	v_mul_f32_e32 v69, v69, v125
	v_mul_f32_e32 v70, v70, v126
	v_mul_f32_e32 v71, v71, v127
	v_cvt_pk_bf16_f32 v64, v64, v65
	v_cvt_pk_bf16_f32 v65, v66, v67
	v_cvt_pk_bf16_f32 v66, v68, v69
	v_cvt_pk_bf16_f32 v67, v70, v71
	global_store_dwordx4 v11, v[64:67], s[24:25] offset:512 sc1
	v_mul_f32_e32 v72, v72, v120
	v_mul_f32_e32 v73, v73, v121
	v_mul_f32_e32 v74, v74, v122
	v_mul_f32_e32 v75, v75, v123
	v_mul_f32_e32 v76, v76, v124
	v_mul_f32_e32 v77, v77, v125
	v_mul_f32_e32 v78, v78, v126
	v_mul_f32_e32 v79, v79, v127
	v_cvt_pk_bf16_f32 v72, v72, v73
	v_cvt_pk_bf16_f32 v73, v74, v75
	v_cvt_pk_bf16_f32 v74, v76, v77
	v_cvt_pk_bf16_f32 v75, v78, v79
	global_store_dwordx4 v11, v[72:75], s[24:25] offset:768 sc1

; __device__ __forceinline__ void tr_load(const float* W, int N, int item, int lane, float (&wv)[32]) {
;     const int nblk = N / 32, kb = item / nblk, nb = item % nblk, k0 = 64 * kb, n0 = 32 * nb;
; #pragma unroll
;     for (int i = 0; i < 32; ++i) { const int kk = 2 * i + (lane >> 5); wv[i] = __builtin_nontemporal_load(W + (size_t)(k0 + kk) * N + n0 + (lane & 31)); }
; }
; template <int MAP, bool HASG, bool PERMW>
; __device__ __forceinline__ void tr_store(int K, int N, bf16_t* WT, LAS float* scr, int item, int lane, const float* gk) {
;     const int nblk = N / 32, kb = item / nblk, nb = item % nblk, k0 = 64 * kb, n0 = 32 * nb;
;     asm volatile("s_waitcnt lgkmcnt(0)" ::: "memory");
;     const int c = lane & 7;
;     f32x4 g0 = {1.f, 1.f, 1.f, 1.f}, g1 = {1.f, 1.f, 1.f, 1.f};
;     if (HASG) { g0 = *(const f32x4*)(gk + k0 + 8 * c); g1 = *(const f32x4*)(gk + k0 + 8 * c + 4); }
; #pragma unroll
;     for (int j = 0; j < 4; ++j) { const int n = (lane >> 3) + 8 * j; const LAS float* s = scr + (8 * c) * 33 + n;
;         u32x4 o; o.x = pk2(s[0 * 33] * g0[0], s[1 * 33] * g0[1]); o.y = pk2(s[2 * 33] * g0[2], s[3 * 33] * g0[3]); o.z = pk2(s[4 * 33] * g1[0], s[5 * 33] * g1[1]); o.w = pk2(s[6 * 33] * g1[2], s[7 * 33] * g1[3]);
;         const int wr_ = rowmap<MAP>(n0 + n), slot_ = PERMW ? ((wr_ & ~31) + invperm32(wr_ & 31)) : wr_;
;         *(u32x4*)((char*)WT + tiled_off(slot_, k0 + 8 * c, K / 64)) = o; }
;     asm volatile("s_waitcnt lgkmcnt(0)" ::: "memory");
; }
; template <int MAP, bool HASG = false, bool PERMW = false>
; __device__ __forceinline__ void transpose_mat(const float* W, int K, int N, bf16_t* WT, LAS float* scr, int gw, int ngw, int lane, const float* gk = nullptr) {
;     const int nitems = (K / 64) * (N / 32);
;     int it = gw;
;     if (it >= nitems) return;
;     float wv[32];
;     tr_load(W, N, it, lane, wv);
;     for (;;) {
;         __builtin_amdgcn_sched_barrier(0);
; #pragma unroll
;         for (int i = 0; i < 32; ++i) { const int kk = 2 * i + (lane >> 5); scr[kk * 33 + (lane & 31)] = wv[i]; }
;         __builtin_amdgcn_sched_barrier(0);
;         const int nx = it + ngw;
;         if (nx < nitems) tr_load(W, N, nx, lane, wv);
;         __builtin_amdgcn_sched_barrier(0);
;         tr_store<MAP, HASG, PERMW>(K, N, WT, scr, it, lane, gk);
;         if (nx >= nitems) break;
;         it = nx;
;     }
; }
.Ltc3d_loop:
	s_add_u32 s9, s9, s19
	s_cmpk_ge_u32 s9, 0x1600
	s_cbranch_scc1 .Ltc3d_lastA
	s_mul_hi_u32 s11, s9, 0x2e8ba2e9
	s_lshr_b32 s11, s11, 5
	s_mul_i32 s12, s11, 0xb0
	s_sub_u32 s12, s9, s12
	s_mul_i32 s13, s11, 0x160000
	s_lshl_b32 s14, s12, 7
	s_add_u32 s13, s13, s14
	s_add_u32 s14, s4, s13
	s_addc_u32 s15, s5, 0
	global_load_dword v88, v15, s[14:15] nt
	s_add_u32 s14, s14, 0xb000
	s_addc_u32 s15, s15, 0
	global_load_dword v89, v15, s[14:15] nt
	s_add_u32 s14, s14, 0xb000
	s_addc_u32 s15, s15, 0
	global_load_dword v90, v15, s[14:15] nt
	s_add_u32 s14, s14, 0xb000
	s_addc_u32 s15, s15, 0
	global_load_dword v91, v15, s[14:15] nt
	s_add_u32 s14, s14, 0xb000
	s_addc_u32 s15, s15, 0
	global_load_dword v92, v15, s[14:15] nt
	s_add_u32 s14, s14, 0xb000
	s_addc_u32 s15, s15, 0
	global_load_dword v93, v15, s[14:15] nt
	s_add_u32 s14, s14, 0xb000
	s_addc_u32 s15, s15, 0
	global_load_dword v94, v15, s[14:15] nt
	s_add_u32 s14, s14, 0xb000
	s_addc_u32 s15, s15, 0
	global_load_dword v95, v15, s[14:15] nt
	s_add_u32 s14, s14, 0xb000
	s_addc_u32 s15, s15, 0
	global_load_dword v96, v15, s[14:15] nt
	s_add_u32 s14, s14, 0xb000
	s_addc_u32 s15, s15, 0
	global_load_dword v97, v15, s[14:15] nt
	s_add_u32 s14, s14, 0xb000
	s_addc_u32 s15, s15, 0
	global_load_dword v98, v15, s[14:15] nt
	s_add_u32 s14, s14, 0xb000
	s_addc_u32 s15, s15, 0
	global_load_dword v99, v15, s[14:15] nt
	s_add_u32 s14, s14, 0xb000
	s_addc_u32 s15, s15, 0
	global_load_dword v100, v15, s[14:15] nt
	s_add_u32 s14, s14, 0xb000
	s_addc_u32 s15, s15, 0
	global_load_dword v101, v15, s[14:15] nt
	s_add_u32 s14, s14, 0xb000
	s_addc_u32 s15, s15, 0
	global_load_dword v102, v15, s[14:15] nt
	s_add_u32 s14, s14, 0xb000
	s_addc_u32 s15, s15, 0
	global_load_dword v103, v15, s[14:15] nt
	s_add_u32 s14, s14, 0xb000
	s_addc_u32 s15, s15, 0
	global_load_dword v104, v15, s[14:15] nt
	s_add_u32 s14, s14, 0xb000
	s_addc_u32 s15, s15, 0
	global_load_dword v105, v15, s[14:15] nt
	s_add_u32 s14, s14, 0xb000
	s_addc_u32 s15, s15, 0
	global_load_dword v106, v15, s[14:15] nt
	s_add_u32 s14, s14, 0xb000
	s_addc_u32 s15, s15, 0
	global_load_dword v107, v15, s[14:15] nt
	s_add_u32 s14, s14, 0xb000
	s_addc_u32 s15, s15, 0
	global_load_dword v108, v15, s[14:15] nt
	s_add_u32 s14, s14, 0xb000
	s_addc_u32 s15, s15, 0
	global_load_dword v109, v15, s[14:15] nt
	s_add_u32 s14, s14, 0xb000
	s_addc_u32 s15, s15, 0
	global_load_dword v110, v15, s[14:15] nt
	s_add_u32 s14, s14, 0xb000
	s_addc_u32 s15, s15, 0
	global_load_dword v111, v15, s[14:15] nt
	s_add_u32 s14, s14, 0xb000
	s_addc_u32 s15, s15, 0
	global_load_dword v112, v15, s[14:15] nt
	s_add_u32 s14, s14, 0xb000
	s_addc_u32 s15, s15, 0
	global_load_dword v113, v15, s[14:15] nt
	s_add_u32 s14, s14, 0xb000
	s_addc_u32 s15, s15, 0
	global_load_dword v114, v15, s[14:15] nt
	s_add_u32 s14, s14, 0xb000
	s_addc_u32 s15, s15, 0
	global_load_dword v115, v15, s[14:15] nt
	s_add_u32 s14, s14, 0xb000
	s_addc_u32 s15, s15, 0
	global_load_dword v116, v15, s[14:15] nt
	s_add_u32 s14, s14, 0xb000
	s_addc_u32 s15, s15, 0
	global_load_dword v117, v15, s[14:15] nt
	s_add_u32 s14, s14, 0xb000
	s_addc_u32 s15, s15, 0
	global_load_dword v118, v15, s[14:15] nt
	s_add_u32 s14, s14, 0xb000
	s_addc_u32 s15, s15, 0
	global_load_dword v119, v15, s[14:15] nt
	s_lshl_b32 s14, s11, 8
	s_add_u32 s14, s20, s14
	s_addc_u32 s15, s21, 0
	global_load_dwordx4 v[120:123], v14, s[14:15]
	global_load_dwordx4 v[124:127], v14, s[14:15] offset:16
	s_lshr_b32 s24, s12, 2
	s_lshl_b32 s24, s24, 1
	s_add_u32 s24, s24, 1
	s_lshl_b32 s24, s24, 5
	s_add_u32 s24, s24, s11
	s_lshl_b32 s24, s24, 14
	s_and_b32 s25, s12, 3
	s_lshl_b32 s25, s25, 12
	s_add_u32 s24, s24, s25
	s_add_u32 s24, s6, s24
	s_addc_u32 s25, s7, 0
	s_waitcnt vmcnt(34)
	ds_write_b32 v4, v16
	ds_write_b32 v4, v17 offset:264
	ds_write_b32 v4, v18 offset:528
	ds_write_b32 v4, v19 offset:792
	ds_write_b32 v4, v20 offset:1056
	ds_write_b32 v4, v21 offset:1320
	ds_write_b32 v4, v22 offset:1584
	ds_write_b32 v4, v23 offset:1848
	ds_write_b32 v4, v24 offset:2112
	ds_write_b32 v4, v25 offset:2376
	ds_write_b32 v4, v26 offset:2640
	ds_write_b32 v4, v27 offset:2904
	ds_write_b32 v4, v28 offset:3168
	ds_write_b32 v4, v29 offset:3432
	ds_write_b32 v4, v30 offset:3696
	ds_write_b32 v4, v31 offset:3960
	ds_write_b32 v4, v32 offset:4224
	ds_write_b32 v4, v33 offset:4488
	ds_write_b32 v4, v34 offset:4752
	ds_write_b32 v4, v35 offset:5016
	ds_write_b32 v4, v36 offset:5280
	ds_write_b32 v4, v37 offset:5544
	ds_write_b32 v4, v38 offset:5808
	ds_write_b32 v4, v39 offset:6072
	ds_write_b32 v4, v40 offset:6336
	ds_write_b32 v4, v41 offset:6600
	ds_write_b32 v4, v42 offset:6864
	ds_write_b32 v4, v43 offset:7128
	ds_write_b32 v4, v44 offset:7392
	ds_write_b32 v4, v45 offset:7656
	ds_write_b32 v4, v46 offset:7920
	ds_write_b32 v4, v47 offset:8184
	s_waitcnt lgkmcnt(0)
	ds_read_b32 v48, v7
	ds_read_b32 v49, v7 offset:132
	ds_read_b32 v50, v7 offset:264
	ds_read_b32 v51, v7 offset:396
	ds_read_b32 v52, v7 offset:528
	ds_read_b32 v53, v7 offset:660
	ds_read_b32 v54, v7 offset:792
	ds_read_b32 v55, v7 offset:924
	ds_read_b32 v56, v7 offset:32
	ds_read_b32 v57, v7 offset:164
	ds_read_b32 v58, v7 offset:296
	ds_read_b32 v59, v7 offset:428
	ds_read_b32 v60, v7 offset:560
	ds_read_b32 v61, v7 offset:692
	ds_read_b32 v62, v7 offset:824
	ds_read_b32 v63, v7 offset:956
	ds_read_b32 v64, v7 offset:64
	ds_read_b32 v65, v7 offset:196
	ds_read_b32 v66, v7 offset:328
	ds_read_b32 v67, v7 offset:460
	ds_read_b32 v68, v7 offset:592
	ds_read_b32 v69, v7 offset:724
	ds_read_b32 v70, v7 offset:856
	ds_read_b32 v71, v7 offset:988
	ds_read_b32 v72, v7 offset:96
	ds_read_b32 v73, v7 offset:228
	ds_read_b32 v74, v7 offset:360
	ds_read_b32 v75, v7 offset:492
	ds_read_b32 v76, v7 offset:624
	ds_read_b32 v77, v7 offset:756
	ds_read_b32 v78, v7 offset:888
	ds_read_b32 v79, v7 offset:1020
	s_waitcnt lgkmcnt(0)
; __device__ __forceinline__ void tr_load(const float* W, int N, int item, int lane, float (&wv)[32]) {
;     const int nblk = N / 32, kb = item / nblk, nb = item % nblk, k0 = 64 * kb, n0 = 32 * nb;
; #pragma unroll
;     for (int i = 0; i < 32; ++i) { const int kk = 2 * i + (lane >> 5); wv[i] = __builtin_nontemporal_load(W + (size_t)(k0 + kk) * N + n0 + (lane & 31)); }
; }
; template <int MAP, bool HASG, bool PERMW>
; __device__ __forceinline__ void tr_store(int K, int N, bf16_t* WT, LAS float* scr, int item, int lane, const float* gk) {
;     const int nblk = N / 32, kb = item / nblk, nb = item % nblk, k0 = 64 * kb, n0 = 32 * nb;
;     asm volatile("s_waitcnt lgkmcnt(0)" ::: "memory");
;     const int c = lane & 7;
;     f32x4 g0 = {1.f, 1.f, 1.f, 1.f}, g1 = {1.f, 1.f, 1.f, 1.f};
;     if (HASG) { g0 = *(const f32x4*)(gk + k0 + 8 * c); g1 = *(const f32x4*)(gk + k0 + 8 * c + 4); }
; #pragma unroll
;     for (int j = 0; j < 4; ++j) { const int n = (lane >> 3) + 8 * j; const LAS float* s = scr + (8 * c) * 33 + n;
;         u32x4 o; o.x = pk2(s[0 * 33] * g0[0], s[1 * 33] * g0[1]); o.y = pk2(s[2 * 33] * g0[2], s[3 * 33] * g0[3]); o.z = pk2(s[4 * 33] * g1[0], s[5 * 33] * g1[1]); o.w = pk2(s[6 * 33] * g1[2], s[7 * 33] * g1[3]);
;         const int wr_ = rowmap<MAP>(n0 + n), slot_ = PERMW ? ((wr_ & ~31) + invperm32(wr_ & 31)) : wr_;
;         *(u32x4*)((char*)WT + tiled_off(slot_, k0 + 8 * c, K / 64)) = o; }
;     asm volatile("s_waitcnt lgkmcnt(0)" ::: "memory");
; }
; template <int MAP, bool HASG = false, bool PERMW = false>
; __device__ __forceinline__ void transpose_mat(const float* W, int K, int N, bf16_t* WT, LAS float* scr, int gw, int ngw, int lane, const float* gk = nullptr) {
;     const int nitems = (K / 64) * (N / 32);
;     int it = gw;
;     if (it >= nitems) return;
;     float wv[32];
;     tr_load(W, N, it, lane, wv);
;     for (;;) {
;         __builtin_amdgcn_sched_barrier(0);
; #pragma unroll
;         for (int i = 0; i < 32; ++i) { const int kk = 2 * i + (lane >> 5); scr[kk * 33 + (lane & 31)] = wv[i]; }
;         __builtin_amdgcn_sched_barrier(0);
;         const int nx = it + ngw;
;         if (nx < nitems) tr_load(W, N, nx, lane, wv);
;         __builtin_amdgcn_sched_barrier(0);
;         tr_store<MAP, HASG, PERMW>(K, N, WT, scr, it, lane, gk);
;         if (nx >= nitems) break;
;         it = nx;
;     }
; }
	v_mul_f32_e32 v48, v48, v80
	v_mul_f32_e32 v49, v49, v81
	v_mul_f32_e32 v50, v50, v82
	v_mul_f32_e32 v51, v51, v83
	v_mul_f32_e32 v52, v52, v84
	v_mul_f32_e32 v53, v53, v85
	v_mul_f32_e32 v54, v54, v86
	v_mul_f32_e32 v55, v55, v87
	v_cvt_pk_bf16_f32 v48, v48, v49
	v_cvt_pk_bf16_f32 v49, v50, v51
	v_cvt_pk_bf16_f32 v50, v52, v53
	v_cvt_pk_bf16_f32 v51, v54, v55
	global_store_dwordx4 v10, v[48:51], s[16:17] sc1
	v_mul_f32_e32 v56, v56, v80
	v_mul_f32_e32 v57, v57, v81
	v_mul_f32_e32 v58, v58, v82
	v_mul_f32_e32 v59, v59, v83
	v_mul_f32_e32 v60, v60, v84
	v_mul_f32_e32 v61, v61, v85
	v_mul_f32_e32 v62, v62, v86
	v_mul_f32_e32 v63, v63, v87
	v_cvt_pk_bf16_f32 v56, v56, v57
	v_cvt_pk_bf16_f32 v57, v58, v59
	v_cvt_pk_bf16_f32 v58, v60, v61
	v_cvt_pk_bf16_f32 v59, v62, v63
	global_store_dwordx4 v10, v[56:59], s[16:17] offset:256 sc1
	v_mul_f32_e32 v64, v64, v80
	v_mul_f32_e32 v65, v65, v81
	v_mul_f32_e32 v66, v66, v82
	v_mul_f32_e32 v67, v67, v83
	v_mul_f32_e32 v68, v68, v84
	v_mul_f32_e32 v69, v69, v85
	v_mul_f32_e32 v70, v70, v86
	v_mul_f32_e32 v71, v71, v87
	v_cvt_pk_bf16_f32 v64, v64, v65
	v_cvt_pk_bf16_f32 v65, v66, v67
	v_cvt_pk_bf16_f32 v66, v68, v69
	v_cvt_pk_bf16_f32 v67, v70, v71
	global_store_dwordx4 v11, v[64:67], s[16:17] offset:512 sc1
	v_mul_f32_e32 v72, v72, v80
	v_mul_f32_e32 v73, v73, v81
	v_mul_f32_e32 v74, v74, v82
	v_mul_f32_e32 v75, v75, v83
	v_mul_f32_e32 v76, v76, v84
	v_mul_f32_e32 v77, v77, v85
	v_mul_f32_e32 v78, v78, v86
	v_mul_f32_e32 v79, v79, v87
	v_cvt_pk_bf16_f32 v72, v72, v73
	v_cvt_pk_bf16_f32 v73, v74, v75
	v_cvt_pk_bf16_f32 v74, v76, v77
	v_cvt_pk_bf16_f32 v75, v78, v79
	global_store_dwordx4 v11, v[72:75], s[16:17] offset:768 sc1
	s_add_u32 s9, s9, s19
	s_cmpk_ge_u32 s9, 0x1600
	s_cbranch_scc1 .Ltc3d_lastB
	s_mul_hi_u32 s11, s9, 0x2e8ba2e9
	s_lshr_b32 s11, s11, 5
	s_mul_i32 s12, s11, 0xb0
	s_sub_u32 s12, s9, s12
	s_mul_i32 s13, s11, 0x160000
	s_lshl_b32 s14, s12, 7
	s_add_u32 s13, s13, s14
	s_add_u32 s14, s4, s13
	s_addc_u32 s15, s5, 0
	global_load_dword v16, v15, s[14:15] nt
	s_add_u32 s14, s14, 0xb000
	s_addc_u32 s15, s15, 0
	global_load_dword v17, v15, s[14:15] nt
	s_add_u32 s14, s14, 0xb000
	s_addc_u32 s15, s15, 0
	global_load_dword v18, v15, s[14:15] nt
	s_add_u32 s14, s14, 0xb000
	s_addc_u32 s15, s15, 0
	global_load_dword v19, v15, s[14:15] nt
	s_add_u32 s14, s14, 0xb000
	s_addc_u32 s15, s15, 0
	global_load_dword v20, v15, s[14:15] nt
	s_add_u32 s14, s14, 0xb000
	s_addc_u32 s15, s15, 0
	global_load_dword v21, v15, s[14:15] nt
	s_add_u32 s14, s14, 0xb000
	s_addc_u32 s15, s15, 0
	global_load_dword v22, v15, s[14:15] nt
	s_add_u32 s14, s14, 0xb000
	s_addc_u32 s15, s15, 0
	global_load_dword v23, v15, s[14:15] nt
	s_add_u32 s14, s14, 0xb000
	s_addc_u32 s15, s15, 0
	global_load_dword v24, v15, s[14:15] nt
	s_add_u32 s14, s14, 0xb000
	s_addc_u32 s15, s15, 0
	global_load_dword v25, v15, s[14:15] nt
	s_add_u32 s14, s14, 0xb000
	s_addc_u32 s15, s15, 0
	global_load_dword v26, v15, s[14:15] nt
	s_add_u32 s14, s14, 0xb000
	s_addc_u32 s15, s15, 0
	global_load_dword v27, v15, s[14:15] nt
	s_add_u32 s14, s14, 0xb000
	s_addc_u32 s15, s15, 0
	global_load_dword v28, v15, s[14:15] nt
	s_add_u32 s14, s14, 0xb000
	s_addc_u32 s15, s15, 0
	global_load_dword v29, v15, s[14:15] nt
	s_add_u32 s14, s14, 0xb000
	s_addc_u32 s15, s15, 0
	global_load_dword v30, v15, s[14:15] nt
	s_add_u32 s14, s14, 0xb000
	s_addc_u32 s15, s15, 0
	global_load_dword v31, v15, s[14:15] nt
	s_add_u32 s14, s14, 0xb000
	s_addc_u32 s15, s15, 0
	global_load_dword v32, v15, s[14:15] nt
	s_add_u32 s14, s14, 0xb000
	s_addc_u32 s15, s15, 0
	global_load_dword v33, v15, s[14:15] nt
	s_add_u32 s14, s14, 0xb000
	s_addc_u32 s15, s15, 0
	global_load_dword v34, v15, s[14:15] nt
	s_add_u32 s14, s14, 0xb000
	s_addc_u32 s15, s15, 0
	global_load_dword v35, v15, s[14:15] nt
	s_add_u32 s14, s14, 0xb000
	s_addc_u32 s15, s15, 0
	global_load_dword v36, v15, s[14:15] nt
	s_add_u32 s14, s14, 0xb000
	s_addc_u32 s15, s15, 0
	global_load_dword v37, v15, s[14:15] nt
	s_add_u32 s14, s14, 0xb000
	s_addc_u32 s15, s15, 0
	global_load_dword v38, v15, s[14:15] nt
	s_add_u32 s14, s14, 0xb000
	s_addc_u32 s15, s15, 0
	global_load_dword v39, v15, s[14:15] nt
	s_add_u32 s14, s14, 0xb000
	s_addc_u32 s15, s15, 0
	global_load_dword v40, v15, s[14:15] nt
	s_add_u32 s14, s14, 0xb000
	s_addc_u32 s15, s15, 0
	global_load_dword v41, v15, s[14:15] nt
	s_add_u32 s14, s14, 0xb000
	s_addc_u32 s15, s15, 0
	global_load_dword v42, v15, s[14:15] nt
	s_add_u32 s14, s14, 0xb000
	s_addc_u32 s15, s15, 0
	global_load_dword v43, v15, s[14:15] nt
	s_add_u32 s14, s14, 0xb000
	s_addc_u32 s15, s15, 0
	global_load_dword v44, v15, s[14:15] nt
	s_add_u32 s14, s14, 0xb000
	s_addc_u32 s15, s15, 0
	global_load_dword v45, v15, s[14:15] nt
	s_add_u32 s14, s14, 0xb000
	s_addc_u32 s15, s15, 0
	global_load_dword v46, v15, s[14:15] nt
	s_add_u32 s14, s14, 0xb000
	s_addc_u32 s15, s15, 0
	global_load_dword v47, v15, s[14:15] nt
	s_lshl_b32 s14, s11, 8
	s_add_u32 s14, s20, s14
	s_addc_u32 s15, s21, 0
	global_load_dwordx4 v[80:83], v14, s[14:15]
	global_load_dwordx4 v[84:87], v14, s[14:15] offset:16
	s_lshr_b32 s16, s12, 2
	s_lshl_b32 s16, s16, 1
	s_add_u32 s16, s16, 1
	s_lshl_b32 s16, s16, 5
	s_add_u32 s16, s16, s11
	s_lshl_b32 s16, s16, 14
	s_and_b32 s17, s12, 3
	s_lshl_b32 s17, s17, 12
	s_add_u32 s16, s16, s17
	s_add_u32 s16, s6, s16
	s_addc_u32 s17, s7, 0
	s_waitcnt vmcnt(34)
; __device__ __forceinline__ void tr_load(const float* W, int N, int item, int lane, float (&wv)[32]) {
;     const int nblk = N / 32, kb = item / nblk, nb = item % nblk, k0 = 64 * kb, n0 = 32 * nb;
; #pragma unroll
;     for (int i = 0; i < 32; ++i) { const int kk = 2 * i + (lane >> 5); wv[i] = __builtin_nontemporal_load(W + (size_t)(k0 + kk) * N + n0 + (lane & 31)); }
; }
; template <int MAP, bool HASG, bool PERMW>
; __device__ __forceinline__ void tr_store(int K, int N, bf16_t* WT, LAS float* scr, int item, int lane, const float* gk) {
;     const int nblk = N / 32, kb = item / nblk, nb = item % nblk, k0 = 64 * kb, n0 = 32 * nb;
;     asm volatile("s_waitcnt lgkmcnt(0)" ::: "memory");
;     const int c = lane & 7;
;     f32x4 g0 = {1.f, 1.f, 1.f, 1.f}, g1 = {1.f, 1.f, 1.f, 1.f};
;     if (HASG) { g0 = *(const f32x4*)(gk + k0 + 8 * c); g1 = *(const f32x4*)(gk + k0 + 8 * c + 4); }
; #pragma unroll
;     for (int j = 0; j < 4; ++j) { const int n = (lane >> 3) + 8 * j; const LAS float* s = scr + (8 * c) * 33 + n;
;         u32x4 o; o.x = pk2(s[0 * 33] * g0[0], s[1 * 33] * g0[1]); o.y = pk2(s[2 * 33] * g0[2], s[3 * 33] * g0[3]); o.z = pk2(s[4 * 33] * g1[0], s[5 * 33] * g1[1]); o.w = pk2(s[6 * 33] * g1[2], s[7 * 33] * g1[3]);
;         const int wr_ = rowmap<MAP>(n0 + n), slot_ = PERMW ? ((wr_ & ~31) + invperm32(wr_ & 31)) : wr_;
;         *(u32x4*)((char*)WT + tiled_off(slot_, k0 + 8 * c, K / 64)) = o; }
;     asm volatile("s_waitcnt lgkmcnt(0)" ::: "memory");
; }
; template <int MAP, bool HASG = false, bool PERMW = false>
; __device__ __forceinline__ void transpose_mat(const float* W, int K, int N, bf16_t* WT, LAS float* scr, int gw, int ngw, int lane, const float* gk = nullptr) {
;     const int nitems = (K / 64) * (N / 32);
;     int it = gw;
;     if (it >= nitems) return;
;     float wv[32];
;     tr_load(W, N, it, lane, wv);
;     for (;;) {
;         __builtin_amdgcn_sched_barrier(0);
; #pragma unroll
;         for (int i = 0; i < 32; ++i) { const int kk = 2 * i + (lane >> 5); scr[kk * 33 + (lane & 31)] = wv[i]; }
;         __builtin_amdgcn_sched_barrier(0);
;         const int nx = it + ngw;
;         if (nx < nitems) tr_load(W, N, nx, lane, wv);
;         __builtin_amdgcn_sched_barrier(0);
;         tr_store<MAP, HASG, PERMW>(K, N, WT, scr, it, lane, gk);
;         if (nx >= nitems) break;
;         it = nx;
;     }
; }
	ds_write_b32 v4, v88
	ds_write_b32 v4, v89 offset:264
	ds_write_b32 v4, v90 offset:528
	ds_write_b32 v4, v91 offset:792
	ds_write_b32 v4, v92 offset:1056
	ds_write_b32 v4, v93 offset:1320
	ds_write_b32 v4, v94 offset:1584
	ds_write_b32 v4, v95 offset:1848
	ds_write_b32 v4, v96 offset:2112
	ds_write_b32 v4, v97 offset:2376
	ds_write_b32 v4, v98 offset:2640
	ds_write_b32 v4, v99 offset:2904
	ds_write_b32 v4, v100 offset:3168
	ds_write_b32 v4, v101 offset:3432
	ds_write_b32 v4, v102 offset:3696
	ds_write_b32 v4, v103 offset:3960
	ds_write_b32 v4, v104 offset:4224
	ds_write_b32 v4, v105 offset:4488
	ds_write_b32 v4, v106 offset:4752
	ds_write_b32 v4, v107 offset:5016
	ds_write_b32 v4, v108 offset:5280
	ds_write_b32 v4, v109 offset:5544
	ds_write_b32 v4, v110 offset:5808
	ds_write_b32 v4, v111 offset:6072
	ds_write_b32 v4, v112 offset:6336
	ds_write_b32 v4, v113 offset:6600
	ds_write_b32 v4, v114 offset:6864
	ds_write_b32 v4, v115 offset:7128
	ds_write_b32 v4, v116 offset:7392
	ds_write_b32 v4, v117 offset:7656
	ds_write_b32 v4, v118 offset:7920
	ds_write_b32 v4, v119 offset:8184
	s_waitcnt lgkmcnt(0)
	ds_read_b32 v48, v7
	ds_read_b32 v49, v7 offset:132
	ds_read_b32 v50, v7 offset:264
	ds_read_b32 v51, v7 offset:396
	ds_read_b32 v52, v7 offset:528
	ds_read_b32 v53, v7 offset:660
	ds_read_b32 v54, v7 offset:792
	ds_read_b32 v55, v7 offset:924
	ds_read_b32 v56, v7 offset:32
	ds_read_b32 v57, v7 offset:164
	ds_read_b32 v58, v7 offset:296
	ds_read_b32 v59, v7 offset:428
	ds_read_b32 v60, v7 offset:560
	ds_read_b32 v61, v7 offset:692
	ds_read_b32 v62, v7 offset:824
	ds_read_b32 v63, v7 offset:956
	ds_read_b32 v64, v7 offset:64
	ds_read_b32 v65, v7 offset:196
	ds_read_b32 v66, v7 offset:328
	ds_read_b32 v67, v7 offset:460
	ds_read_b32 v68, v7 offset:592
	ds_read_b32 v69, v7 offset:724
	ds_read_b32 v70, v7 offset:856
	ds_read_b32 v71, v7 offset:988
	ds_read_b32 v72, v7 offset:96
	ds_read_b32 v73, v7 offset:228
	ds_read_b32 v74, v7 offset:360
	ds_read_b32 v75, v7 offset:492
	ds_read_b32 v76, v7 offset:624
	ds_read_b32 v77, v7 offset:756
	ds_read_b32 v78, v7 offset:888
	ds_read_b32 v79, v7 offset:1020
	s_waitcnt lgkmcnt(0)
	v_mul_f32_e32 v48, v48, v120
	v_mul_f32_e32 v49, v49, v121
	v_mul_f32_e32 v50, v50, v122
	v_mul_f32_e32 v51, v51, v123
	v_mul_f32_e32 v52, v52, v124
	v_mul_f32_e32 v53, v53, v125
	v_mul_f32_e32 v54, v54, v126
	v_mul_f32_e32 v55, v55, v127
	v_cvt_pk_bf16_f32 v48, v48, v49
	v_cvt_pk_bf16_f32 v49, v50, v51
	v_cvt_pk_bf16_f32 v50, v52, v53
	v_cvt_pk_bf16_f32 v51, v54, v55
	global_store_dwordx4 v10, v[48:51], s[24:25] sc1
	v_mul_f32_e32 v56, v56, v120
	v_mul_f32_e32 v57, v57, v121
	v_mul_f32_e32 v58, v58, v122
	v_mul_f32_e32 v59, v59, v123
	v_mul_f32_e32 v60, v60, v124
	v_mul_f32_e32 v61, v61, v125
	v_mul_f32_e32 v62, v62, v126
	v_mul_f32_e32 v63, v63, v127
	v_cvt_pk_bf16_f32 v56, v56, v57
	v_cvt_pk_bf16_f32 v57, v58, v59
	v_cvt_pk_bf16_f32 v58, v60, v61
	v_cvt_pk_bf16_f32 v59, v62, v63
	global_store_dwordx4 v10, v[56:59], s[24:25] offset:256 sc1
	v_mul_f32_e32 v64, v64, v120
	v_mul_f32_e32 v65, v65, v121
	v_mul_f32_e32 v66, v66, v122
	v_mul_f32_e32 v67, v67, v123
	v_mul_f32_e32 v68, v68, v124
	v_mul_f32_e32 v69, v69, v125
	v_mul_f32_e32 v70, v70, v126
	v_mul_f32_e32 v71, v71, v127
	v_cvt_pk_bf16_f32 v64, v64, v65
	v_cvt_pk_bf16_f32 v65, v66, v67
	v_cvt_pk_bf16_f32 v66, v68, v69
	v_cvt_pk_bf16_f32 v67, v70, v71
	global_store_dwordx4 v11, v[64:67], s[24:25] offset:512 sc1
	v_mul_f32_e32 v72, v72, v120
	v_mul_f32_e32 v73, v73, v121
	v_mul_f32_e32 v74, v74, v122
	v_mul_f32_e32 v75, v75, v123
	v_mul_f32_e32 v76, v76, v124
	v_mul_f32_e32 v77, v77, v125
	v_mul_f32_e32 v78, v78, v126
	v_mul_f32_e32 v79, v79, v127
	v_cvt_pk_bf16_f32 v72, v72, v73
	v_cvt_pk_bf16_f32 v73, v74, v75
	v_cvt_pk_bf16_f32 v74, v76, v77
	v_cvt_pk_bf16_f32 v75, v78, v79
	global_store_dwordx4 v11, v[72:75], s[24:25] offset:768 sc1
	s_branch .Ltc3d_loop
